# v082 + lane reductions (xor 16 / xor 32) in the residual, SwiGLU and conv-in epilogues by v_permlane16/32_swap instead of ds_bpermute (96 sites)
# baseline (speedup 1.0000x reference)
; __device__ __forceinline__ unsigned cvt_pk_bf16(float lo, float hi) { unsigned r; asm volatile("v_cvt_pk_bf16_f32 %0, %1, %2" : "=v"(r) : "v"(lo), "v"(hi)); return r; }
; __device__ __forceinline__ float bf_lo(unsigned w) { return __uint_as_float(w << 16); }
; __device__ __forceinline__ float bf_hi(unsigned w) { return __uint_as_float(w & 0xffff0000u); }
;     __device__ __forceinline__ void operator()(const f32x4 (&acc)[2][2][4][2], const Unit& u, int wr, int wc, int fr, int fq) const {
;     ...
;                 for (int bj = 0; bj < 2; ++bj) xin[ai][m][bj] = *(const u32x4*)(X + (size_t)(u.pm * BM + ai * HALF + wr * 64 + m * 16 + fr) * 1024 + col0 + bj * HALF);
; #pragma unroll
;         for (int ai = 0; ai < 2; ++ai)
; #pragma unroll
;             for (int m = 0; m < 4; ++m) {
;                 const int row = u.pm * BM + ai * HALF + wr * 64 + m * 16 + fr;
;                 float ss = 0.f;
; #pragma unroll
;                 for (int bj = 0; bj < 2; ++bj) {
;                     bf16_t* xp = X + (size_t)row * 1024 + col0 + bj * HALF;
;                     const u32x4 xv = xin[ai][m][bj];
;                     f32x4 y0 = acc[ai][bj][m][0], y1 = acc[ai][bj][m][1];
;                     y0[0] += bf_lo(xv.x); y0[1] += bf_hi(xv.x); y0[2] += bf_lo(xv.y); y0[3] += bf_hi(xv.y);
;                     y1[0] += bf_lo(xv.z); y1[1] += bf_hi(xv.z); y1[2] += bf_lo(xv.w); y1[3] += bf_hi(xv.w);
;                     if (FINAL) {
;                         float* op = out + (size_t)row * 1024 + col0 + bj * HALF;
;                         __builtin_nontemporal_store(y0, (f32x4*)op); __builtin_nontemporal_store(y1, (f32x4*)(op + 4));
;                     } else {
;                         u32x4 w; w.x = cvt_pk_bf16(y0[0], y0[1]); w.y = cvt_pk_bf16(y0[2], y0[3]); w.z = cvt_pk_bf16(y1[0], y1[1]); w.w = cvt_pk_bf16(y1[2], y1[3]);
;                         *(u32x4*)xp = w;
;                         ss += (y0[0] * y0[0] + y0[1] * y0[1]) + (y0[2] * y0[2] + y0[3] * y0[3]) + (y1[0] * y1[0] + y1[1] * y1[1]) + (y1[2] * y1[2] + y1[3] * y1[3]);
;                     }
;                 }
;                 if (!FINAL) {
;                     ss += __shfl_xor(ss, 16); ss += __shfl_xor(ss, 32);
;                     if (fq == 0) ssq[(size_t)row * 16 + u.pn * 4 + wc] = ss;
.LBB0_396:
	v_lshl_or_b32 v200, s12, 8, v233
	v_lshl_add_u32 v226, s46, 8, v231
	v_ashrrev_i32_e32 v201, 31, v200
	v_lshlrev_b64 v[246:247], 1, v[200:201]
	v_ashrrev_i32_e32 v227, 31, v226
	v_lshl_add_u64 v[124:125], s[70:71], 0, v[246:247]
	v_lshlrev_b64 v[126:127], 11, v[226:227]
	v_lshl_add_u64 v[132:133], v[124:125], 0, v[126:127]
	global_load_dwordx4 v[238:241], v[132:133], off
	global_load_dwordx4 v[242:245], v[132:133], off offset:256
	v_or_b32_e32 v222, 16, v226
	v_or_b32_e32 v218, 32, v226
	v_or_b32_e32 v214, 48, v226
	v_add_u32_e32 v210, 0x80, v226
	v_add_u32_e32 v206, 0x90, v226
	v_add_u32_e32 v202, 0xa0, v226
	v_add_u32_e32 v198, 0xb0, v226
	v_ashrrev_i32_e32 v223, 31, v222
	v_ashrrev_i32_e32 v219, 31, v218
	v_ashrrev_i32_e32 v215, 31, v214
	v_ashrrev_i32_e32 v211, 31, v210
	v_ashrrev_i32_e32 v207, 31, v206
	v_ashrrev_i32_e32 v203, 31, v202
	v_ashrrev_i32_e32 v199, 31, v198
	v_lshlrev_b64 v[228:229], 11, v[222:223]
	v_lshlrev_b64 v[224:225], 11, v[218:219]
	v_lshlrev_b64 v[220:221], 11, v[214:215]
	v_lshlrev_b64 v[216:217], 11, v[210:211]
	v_lshlrev_b64 v[212:213], 11, v[206:207]
	v_lshlrev_b64 v[208:209], 11, v[202:203]
	v_lshlrev_b64 v[204:205], 11, v[198:199]
	v_lshl_add_u64 v[248:249], s[70:71], 0, v[126:127]
	v_lshl_add_u64 v[126:127], v[124:125], 0, v[228:229]
	v_lshl_add_u64 v[132:133], v[124:125], 0, v[224:225]
	v_lshl_add_u64 v[134:135], v[124:125], 0, v[220:221]
	v_lshl_add_u64 v[136:137], v[124:125], 0, v[216:217]
	v_lshl_add_u64 v[138:139], v[124:125], 0, v[212:213]
	v_lshl_add_u64 v[250:251], v[124:125], 0, v[208:209]
	v_lshl_add_u64 v[124:125], v[124:125], 0, v[204:205]
	global_load_dwordx4 v[180:183], v[126:127], off
	global_load_dwordx4 v[176:179], v[126:127], off offset:256
	global_load_dwordx4 v[172:175], v[132:133], off
	global_load_dwordx4 v[168:171], v[132:133], off offset:256
	global_load_dwordx4 v[164:167], v[134:135], off
	global_load_dwordx4 v[160:163], v[134:135], off offset:256
	global_load_dwordx4 v[156:159], v[136:137], off
	global_load_dwordx4 v[152:155], v[136:137], off offset:256
	global_load_dwordx4 v[148:151], v[138:139], off
	global_load_dwordx4 v[144:147], v[138:139], off offset:256
	global_load_dwordx4 v[140:143], v[250:251], off
	s_nop 0
	global_load_dwordx4 v[136:139], v[250:251], off offset:256
	global_load_dwordx4 v[132:135], v[124:125], off
	s_nop 0
	global_load_dwordx4 v[124:127], v[124:125], off offset:256
	v_lshl_add_u64 v[246:247], v[248:249], 0, v[246:247]
	s_lshl_b32 s46, s12, 2
	s_ashr_i32 s47, s46, 31
	s_waitcnt vmcnt(14)
	v_lshlrev_b32_e32 v248, 16, v238
	v_and_b32_e32 v238, 0xffff0000, v238
	v_lshlrev_b32_e32 v249, 16, v239
	v_and_b32_e32 v239, 0xffff0000, v239
	v_lshlrev_b32_e32 v250, 16, v240
	v_and_b32_e32 v240, 0xffff0000, v240
	v_lshlrev_b32_e32 v252, 16, v242
	v_lshlrev_b32_e32 v253, 16, v243
	v_add_f32_e32 v129, v129, v238
	v_add_f32_e32 v131, v131, v239
	v_and_b32_e32 v243, 0xffff0000, v243
	v_add_f32_e32 v128, v128, v248
	v_add_f32_e32 v130, v130, v249
	v_add_f32_e32 v121, v121, v240
	v_add_f32_e32 v238, v116, v252
	v_add_f32_e32 v240, v118, v253
	v_cvt_pk_bf16_f32 v116, v128, v129
	v_mul_f32_e32 v118, v129, v129
	v_mul_f32_e32 v129, v131, v131
	v_lshlrev_b32_e32 v251, 16, v241
	v_and_b32_e32 v241, 0xffff0000, v241
	v_and_b32_e32 v242, 0xffff0000, v242
	v_fmac_f32_e32 v118, v128, v128
	v_fmac_f32_e32 v129, v130, v130
	v_add_f32_e32 v128, v119, v243
	v_lshlrev_b32_e32 v119, 16, v244
	v_add_f32_e32 v120, v120, v250
	v_add_f32_e32 v123, v123, v241
	v_add_f32_e32 v239, v117, v242
	v_cvt_pk_bf16_f32 v117, v130, v131
	v_mul_f32_e32 v131, v121, v121
	v_add_f32_e32 v118, v118, v129
	v_add_f32_e32 v129, v112, v119
	v_and_b32_e32 v112, 0xffff0000, v244
	v_add_f32_e32 v122, v122, v251
	v_mul_f32_e32 v241, v123, v123
	v_fmac_f32_e32 v131, v120, v120
	v_add_f32_e32 v130, v113, v112
	v_lshlrev_b32_e32 v112, 16, v245
	v_fmac_f32_e32 v241, v122, v122
	v_add_f32_e32 v118, v131, v118
	v_add_f32_e32 v131, v114, v112
	v_and_b32_e32 v112, 0xffff0000, v245
	v_add_f32_e32 v118, v241, v118
	v_add_f32_e32 v241, v115, v112
	v_mul_f32_e32 v112, v239, v239
	v_mul_f32_e32 v113, v128, v128
	v_fmac_f32_e32 v112, v238, v238
	v_fmac_f32_e32 v113, v240, v240
	v_add_f32_e32 v112, v112, v113
	v_mul_f32_e32 v113, v130, v130
	v_fmac_f32_e32 v113, v129, v129
	v_add_f32_e32 v112, v113, v112
	v_mul_f32_e32 v113, v241, v241
	v_fmac_f32_e32 v113, v131, v131
	v_add_f32_e32 v112, v113, v112
	v_and_b32_e32 v114, 64, v237
	v_add_f32_e32 v113, v118, v112
	v_xor_b32_e32 v112, 16, v237
	v_add_u32_e32 v115, 64, v114
	v_cmp_lt_i32_e32 vcc, v112, v115
	v_cvt_pk_bf16_f32 v118, v120, v121
	v_cvt_pk_bf16_f32 v119, v122, v123
	global_store_dwordx4 v[246:247], v[116:119], off
	s_nop 0
	v_cndmask_b32_e32 v112, v237, v112, vcc
	v_lshlrev_b32_e32 v112, 2, v112
	v_mov_b32_e32 v114, v113
	s_nop 1
	v_permlane16_swap_b32_e32 v113, v114
	v_cvt_pk_bf16_f32 v116, v238, v239
	v_cvt_pk_bf16_f32 v117, v240, v128
	v_cvt_pk_bf16_f32 v118, v129, v130
	v_cvt_pk_bf16_f32 v119, v131, v241
	s_waitcnt lgkmcnt(0)
	v_add_f32_e32 v114, v113, v114
	v_xor_b32_e32 v113, 32, v237
	v_cmp_lt_i32_e32 vcc, v113, v115
	global_store_dwordx4 v[246:247], v[116:119], off offset:256
	s_nop 0
	v_cndmask_b32_e32 v113, v237, v113, vcc
	v_lshlrev_b32_e32 v113, 2, v113
	v_mov_b32_e32 v115, v114
	s_nop 1
	v_permlane32_swap_b32_e32 v114, v115
	s_and_saveexec_b64 s[48:49], s[0:1]
	s_cbranch_execz .LBB0_398
	s_waitcnt lgkmcnt(0)
	v_add_f32_e32 v116, v114, v115
	v_lshlrev_b64 v[114:115], 6, v[226:227]
	v_lshl_add_u64 v[114:115], s[34:35], 0, v[114:115]
	v_lshl_add_u64 v[114:115], s[46:47], 2, v[114:115]
	s_lshl_b32 s12, s30, 2
	v_lshl_add_u64 v[114:115], v[114:115], 0, s[12:13]
	global_store_dword v[114:115], v116, off
; __device__ __forceinline__ unsigned cvt_pk_bf16(float lo, float hi) { unsigned r; asm volatile("v_cvt_pk_bf16_f32 %0, %1, %2" : "=v"(r) : "v"(lo), "v"(hi)); return r; }
; __device__ __forceinline__ float bf_lo(unsigned w) { return __uint_as_float(w << 16); }
; __device__ __forceinline__ float bf_hi(unsigned w) { return __uint_as_float(w & 0xffff0000u); }
;     __device__ __forceinline__ void operator()(const f32x4 (&acc)[2][2][4][2], const Unit& u, int wr, int wc, int fr, int fq) const {
;     ...
;         for (int ai = 0; ai < 2; ++ai)
; #pragma unroll
;             for (int m = 0; m < 4; ++m) {
;                 const int row = u.pm * BM + ai * HALF + wr * 64 + m * 16 + fr;
;                 float ss = 0.f;
; #pragma unroll
;                 for (int bj = 0; bj < 2; ++bj) {
;                     bf16_t* xp = X + (size_t)row * 1024 + col0 + bj * HALF;
;                     const u32x4 xv = xin[ai][m][bj];
;                     f32x4 y0 = acc[ai][bj][m][0], y1 = acc[ai][bj][m][1];
;                     y0[0] += bf_lo(xv.x); y0[1] += bf_hi(xv.x); y0[2] += bf_lo(xv.y); y0[3] += bf_hi(xv.y);
;                     y1[0] += bf_lo(xv.z); y1[1] += bf_hi(xv.z); y1[2] += bf_lo(xv.w); y1[3] += bf_hi(xv.w);
;                     if (FINAL) {
;                         float* op = out + (size_t)row * 1024 + col0 + bj * HALF;
;                         __builtin_nontemporal_store(y0, (f32x4*)op); __builtin_nontemporal_store(y1, (f32x4*)(op + 4));
;                     } else {
;                         u32x4 w; w.x = cvt_pk_bf16(y0[0], y0[1]); w.y = cvt_pk_bf16(y0[2], y0[3]); w.z = cvt_pk_bf16(y1[0], y1[1]); w.w = cvt_pk_bf16(y1[2], y1[3]);
;                         *(u32x4*)xp = w;
;                         ss += (y0[0] * y0[0] + y0[1] * y0[1]) + (y0[2] * y0[2] + y0[3] * y0[3]) + (y1[0] * y1[0] + y1[1] * y1[1]) + (y1[2] * y1[2] + y1[3] * y1[3]);
;                     }
;                 }
;                 if (!FINAL) {
;                     ss += __shfl_xor(ss, 16); ss += __shfl_xor(ss, 32);
;                     if (fq == 0) ssq[(size_t)row * 16 + u.pn * 4 + wc] = ss;
;                 }
.LBB0_398:
	s_or_b64 exec, exec, s[48:49]
	s_waitcnt vmcnt(14)
	v_lshlrev_b32_e32 v116, 16, v180
	v_add_f32_e32 v108, v108, v116
	v_and_b32_e32 v116, 0xffff0000, v180
	v_add_f32_e32 v109, v109, v116
	v_lshlrev_b32_e32 v116, 16, v181
	v_add_f32_e32 v110, v110, v116
	v_and_b32_e32 v116, 0xffff0000, v181
	v_add_f32_e32 v111, v111, v116
	v_lshlrev_b32_e32 v116, 16, v182
	v_add_f32_e32 v116, v104, v116
	v_and_b32_e32 v104, 0xffff0000, v182
	v_add_f32_e32 v117, v105, v104
	v_lshlrev_b32_e32 v104, 16, v183
	v_add_f32_e32 v118, v106, v104
	v_and_b32_e32 v104, 0xffff0000, v183
	v_mul_f32_e32 v106, v109, v109
	v_add_f32_e32 v107, v107, v104
	v_cvt_pk_bf16_f32 v104, v108, v109
	v_fmac_f32_e32 v106, v108, v108
	v_mul_f32_e32 v108, v111, v111
	v_fmac_f32_e32 v108, v110, v110
	v_add_f32_e32 v106, v106, v108
	v_mul_f32_e32 v108, v117, v117
	v_fmac_f32_e32 v108, v116, v116
	v_add_f32_e32 v106, v108, v106
	v_mul_f32_e32 v108, v107, v107
	v_fmac_f32_e32 v108, v118, v118
	v_add_f32_e32 v106, v108, v106
	v_lshlrev_b32_e32 v108, 16, v176
	v_add_f32_e32 v100, v100, v108
	v_and_b32_e32 v108, 0xffff0000, v176
	v_add_f32_e32 v101, v101, v108
	v_lshlrev_b32_e32 v108, 16, v177
	v_add_f32_e32 v102, v102, v108
	v_and_b32_e32 v108, 0xffff0000, v177
	v_add_f32_e32 v103, v103, v108
	v_lshlrev_b32_e32 v108, 16, v178
	v_add_f32_e32 v108, v96, v108
	v_and_b32_e32 v96, 0xffff0000, v178
	v_add_f32_e32 v109, v97, v96
	v_lshlrev_b32_e32 v96, 16, v179
	v_cvt_pk_bf16_f32 v105, v110, v111
	v_add_f32_e32 v110, v98, v96
	v_and_b32_e32 v96, 0xffff0000, v179
	v_add_f32_e32 v111, v99, v96
	v_mul_f32_e32 v96, v101, v101
	v_mul_f32_e32 v97, v103, v103
	v_fmac_f32_e32 v96, v100, v100
	v_fmac_f32_e32 v97, v102, v102
	v_add_f32_e32 v96, v96, v97
	v_mul_f32_e32 v97, v109, v109
	v_fmac_f32_e32 v97, v108, v108
	v_add_f32_e32 v96, v97, v96
	v_mul_f32_e32 v97, v111, v111
	v_fmac_f32_e32 v97, v110, v110
	v_add_f32_e32 v96, v97, v96
	v_add_f32_e32 v96, v106, v96
	v_mov_b32_e32 v97, v96
	s_nop 1
	v_permlane16_swap_b32_e32 v96, v97
	s_waitcnt lgkmcnt(1)
	v_lshl_add_u64 v[114:115], s[70:71], 0, v[228:229]
	v_lshl_add_u64 v[114:115], v[200:201], 1, v[114:115]
	v_cvt_pk_bf16_f32 v106, v116, v117
	v_cvt_pk_bf16_f32 v107, v118, v107
	s_waitcnt lgkmcnt(0)
	v_add_f32_e32 v96, v96, v97
	v_mov_b32_e32 v97, v96
	s_nop 1
	v_permlane32_swap_b32_e32 v96, v97
	global_store_dwordx4 v[114:115], v[104:107], off
	v_cvt_pk_bf16_f32 v98, v100, v101
	v_cvt_pk_bf16_f32 v99, v102, v103
	v_cvt_pk_bf16_f32 v100, v108, v109
	v_cvt_pk_bf16_f32 v101, v110, v111
	global_store_dwordx4 v[114:115], v[98:101], off offset:256
	s_and_saveexec_b64 s[48:49], s[0:1]
	s_cbranch_execz .LBB0_400
	s_waitcnt lgkmcnt(0)
	v_add_f32_e32 v98, v96, v97
	v_lshlrev_b64 v[96:97], 6, v[222:223]
	v_lshl_add_u64 v[96:97], s[34:35], 0, v[96:97]
	v_lshl_add_u64 v[96:97], s[46:47], 2, v[96:97]
	s_lshl_b32 s12, s30, 2
	v_lshl_add_u64 v[96:97], v[96:97], 0, s[12:13]
	global_store_dword v[96:97], v98, off
.LBB0_400:
	s_or_b64 exec, exec, s[48:49]
	s_waitcnt vmcnt(14)
	v_lshlrev_b32_e32 v98, 16, v172
	v_add_f32_e32 v92, v92, v98
	v_and_b32_e32 v98, 0xffff0000, v172
	v_add_f32_e32 v93, v93, v98
	v_lshlrev_b32_e32 v98, 16, v173
	v_add_f32_e32 v94, v94, v98
	v_and_b32_e32 v98, 0xffff0000, v173
	v_add_f32_e32 v95, v95, v98
	v_lshlrev_b32_e32 v98, 16, v174
	v_add_f32_e32 v98, v88, v98
	v_and_b32_e32 v88, 0xffff0000, v174
	v_add_f32_e32 v99, v89, v88
	v_lshlrev_b32_e32 v88, 16, v175
	v_add_f32_e32 v100, v90, v88
	v_and_b32_e32 v88, 0xffff0000, v175
	v_mul_f32_e32 v90, v93, v93
	v_add_f32_e32 v91, v91, v88
	v_cvt_pk_bf16_f32 v88, v92, v93
	v_fmac_f32_e32 v90, v92, v92
	v_mul_f32_e32 v92, v95, v95
	v_fmac_f32_e32 v92, v94, v94
	v_add_f32_e32 v90, v90, v92
	v_mul_f32_e32 v92, v99, v99
	v_fmac_f32_e32 v92, v98, v98
	v_add_f32_e32 v90, v92, v90
	v_mul_f32_e32 v92, v91, v91
	v_fmac_f32_e32 v92, v100, v100
	v_add_f32_e32 v90, v92, v90
	v_lshlrev_b32_e32 v92, 16, v168
	v_add_f32_e32 v84, v84, v92
	v_and_b32_e32 v92, 0xffff0000, v168
	v_add_f32_e32 v85, v85, v92
	v_lshlrev_b32_e32 v92, 16, v169
	v_add_f32_e32 v86, v86, v92
	v_and_b32_e32 v92, 0xffff0000, v169
	v_add_f32_e32 v87, v87, v92
	v_lshlrev_b32_e32 v92, 16, v170
	v_add_f32_e32 v92, v80, v92
	v_and_b32_e32 v80, 0xffff0000, v170
	v_add_f32_e32 v93, v81, v80
	v_lshlrev_b32_e32 v80, 16, v171
	v_cvt_pk_bf16_f32 v89, v94, v95
	v_add_f32_e32 v94, v82, v80
	v_and_b32_e32 v80, 0xffff0000, v171
	v_add_f32_e32 v95, v83, v80
	v_mul_f32_e32 v80, v85, v85
	v_mul_f32_e32 v81, v87, v87
	v_fmac_f32_e32 v80, v84, v84
	v_fmac_f32_e32 v81, v86, v86
	v_add_f32_e32 v80, v80, v81
	v_mul_f32_e32 v81, v93, v93
	v_fmac_f32_e32 v81, v92, v92
	v_add_f32_e32 v80, v81, v80
	v_mul_f32_e32 v81, v95, v95
	v_fmac_f32_e32 v81, v94, v94
	v_add_f32_e32 v80, v81, v80
	v_add_f32_e32 v80, v90, v80
	v_mov_b32_e32 v81, v80
	s_nop 1
	v_permlane16_swap_b32_e32 v80, v81
	s_waitcnt lgkmcnt(1)
	v_lshl_add_u64 v[96:97], s[70:71], 0, v[224:225]
	v_lshl_add_u64 v[96:97], v[200:201], 1, v[96:97]
	v_cvt_pk_bf16_f32 v90, v98, v99
	v_cvt_pk_bf16_f32 v91, v100, v91
	s_waitcnt lgkmcnt(0)
	v_add_f32_e32 v80, v80, v81
	v_mov_b32_e32 v81, v80
	s_nop 1
	v_permlane32_swap_b32_e32 v80, v81
	global_store_dwordx4 v[96:97], v[88:91], off
	v_cvt_pk_bf16_f32 v82, v84, v85
	v_cvt_pk_bf16_f32 v83, v86, v87
	v_cvt_pk_bf16_f32 v84, v92, v93
	v_cvt_pk_bf16_f32 v85, v94, v95
	global_store_dwordx4 v[96:97], v[82:85], off offset:256
	s_and_saveexec_b64 s[48:49], s[0:1]
	s_cbranch_execz .LBB0_402
	s_waitcnt lgkmcnt(0)
	v_add_f32_e32 v82, v80, v81
	v_lshlrev_b64 v[80:81], 6, v[218:219]
	v_lshl_add_u64 v[80:81], s[34:35], 0, v[80:81]
	v_lshl_add_u64 v[80:81], s[46:47], 2, v[80:81]
	s_lshl_b32 s12, s30, 2
	v_lshl_add_u64 v[80:81], v[80:81], 0, s[12:13]
	global_store_dword v[80:81], v82, off
; __device__ __forceinline__ unsigned cvt_pk_bf16(float lo, float hi) { unsigned r; asm volatile("v_cvt_pk_bf16_f32 %0, %1, %2" : "=v"(r) : "v"(lo), "v"(hi)); return r; }
; __device__ __forceinline__ float bf_lo(unsigned w) { return __uint_as_float(w << 16); }
; __device__ __forceinline__ float bf_hi(unsigned w) { return __uint_as_float(w & 0xffff0000u); }
;     __device__ __forceinline__ void operator()(const f32x4 (&acc)[2][2][4][2], const Unit& u, int wr, int wc, int fr, int fq) const {
;     ...
;         for (int ai = 0; ai < 2; ++ai)
; #pragma unroll
;             for (int m = 0; m < 4; ++m) {
;                 const int row = u.pm * BM + ai * HALF + wr * 64 + m * 16 + fr;
;                 float ss = 0.f;
; #pragma unroll
;                 for (int bj = 0; bj < 2; ++bj) {
;                     bf16_t* xp = X + (size_t)row * 1024 + col0 + bj * HALF;
;                     const u32x4 xv = xin[ai][m][bj];
;                     f32x4 y0 = acc[ai][bj][m][0], y1 = acc[ai][bj][m][1];
;                     y0[0] += bf_lo(xv.x); y0[1] += bf_hi(xv.x); y0[2] += bf_lo(xv.y); y0[3] += bf_hi(xv.y);
;                     y1[0] += bf_lo(xv.z); y1[1] += bf_hi(xv.z); y1[2] += bf_lo(xv.w); y1[3] += bf_hi(xv.w);
;                     if (FINAL) {
;                         float* op = out + (size_t)row * 1024 + col0 + bj * HALF;
;                         __builtin_nontemporal_store(y0, (f32x4*)op); __builtin_nontemporal_store(y1, (f32x4*)(op + 4));
;                     } else {
;                         u32x4 w; w.x = cvt_pk_bf16(y0[0], y0[1]); w.y = cvt_pk_bf16(y0[2], y0[3]); w.z = cvt_pk_bf16(y1[0], y1[1]); w.w = cvt_pk_bf16(y1[2], y1[3]);
;                         *(u32x4*)xp = w;
;                         ss += (y0[0] * y0[0] + y0[1] * y0[1]) + (y0[2] * y0[2] + y0[3] * y0[3]) + (y1[0] * y1[0] + y1[1] * y1[1]) + (y1[2] * y1[2] + y1[3] * y1[3]);
;                     }
;                 }
;                 if (!FINAL) {
;                     ss += __shfl_xor(ss, 16); ss += __shfl_xor(ss, 32);
;                     if (fq == 0) ssq[(size_t)row * 16 + u.pn * 4 + wc] = ss;
;                 }
.LBB0_402:
	s_or_b64 exec, exec, s[48:49]
	s_waitcnt vmcnt(14)
	v_lshlrev_b32_e32 v82, 16, v164
	v_add_f32_e32 v76, v76, v82
	v_and_b32_e32 v82, 0xffff0000, v164
	v_add_f32_e32 v77, v77, v82
	v_lshlrev_b32_e32 v82, 16, v165
	v_add_f32_e32 v78, v78, v82
	v_and_b32_e32 v82, 0xffff0000, v165
	v_add_f32_e32 v79, v79, v82
	v_lshlrev_b32_e32 v82, 16, v166
	v_add_f32_e32 v82, v72, v82
	v_and_b32_e32 v72, 0xffff0000, v166
	v_add_f32_e32 v83, v73, v72
	v_lshlrev_b32_e32 v72, 16, v167
	v_add_f32_e32 v84, v74, v72
	v_and_b32_e32 v72, 0xffff0000, v167
	v_mul_f32_e32 v74, v77, v77
	v_add_f32_e32 v75, v75, v72
	v_cvt_pk_bf16_f32 v72, v76, v77
	v_fmac_f32_e32 v74, v76, v76
	v_mul_f32_e32 v76, v79, v79
	v_fmac_f32_e32 v76, v78, v78
	v_add_f32_e32 v74, v74, v76
	v_mul_f32_e32 v76, v83, v83
	v_fmac_f32_e32 v76, v82, v82
	v_add_f32_e32 v74, v76, v74
	v_mul_f32_e32 v76, v75, v75
	v_fmac_f32_e32 v76, v84, v84
	v_add_f32_e32 v74, v76, v74
	v_lshlrev_b32_e32 v76, 16, v160
	v_add_f32_e32 v68, v68, v76
	v_and_b32_e32 v76, 0xffff0000, v160
	v_add_f32_e32 v69, v69, v76
	v_lshlrev_b32_e32 v76, 16, v161
	v_add_f32_e32 v70, v70, v76
	v_and_b32_e32 v76, 0xffff0000, v161
	v_add_f32_e32 v71, v71, v76
	v_lshlrev_b32_e32 v76, 16, v162
	v_add_f32_e32 v76, v64, v76
	v_and_b32_e32 v64, 0xffff0000, v162
	v_add_f32_e32 v77, v65, v64
	v_lshlrev_b32_e32 v64, 16, v163
	v_cvt_pk_bf16_f32 v73, v78, v79
	v_add_f32_e32 v78, v66, v64
	v_and_b32_e32 v64, 0xffff0000, v163
	v_add_f32_e32 v79, v67, v64
	v_mul_f32_e32 v64, v69, v69
	v_mul_f32_e32 v65, v71, v71
	v_fmac_f32_e32 v64, v68, v68
	v_fmac_f32_e32 v65, v70, v70
	v_add_f32_e32 v64, v64, v65
	v_mul_f32_e32 v65, v77, v77
	v_fmac_f32_e32 v65, v76, v76
	v_add_f32_e32 v64, v65, v64
	v_mul_f32_e32 v65, v79, v79
	v_fmac_f32_e32 v65, v78, v78
	v_add_f32_e32 v64, v65, v64
	v_add_f32_e32 v64, v74, v64
	v_mov_b32_e32 v65, v64
	s_nop 1
	v_permlane16_swap_b32_e32 v64, v65
	s_waitcnt lgkmcnt(1)
	v_lshl_add_u64 v[80:81], s[70:71], 0, v[220:221]
	v_lshl_add_u64 v[80:81], v[200:201], 1, v[80:81]
	v_cvt_pk_bf16_f32 v74, v82, v83
	v_cvt_pk_bf16_f32 v75, v84, v75
	s_waitcnt lgkmcnt(0)
	v_add_f32_e32 v64, v64, v65
	v_mov_b32_e32 v65, v64
	s_nop 1
	v_permlane32_swap_b32_e32 v64, v65
	global_store_dwordx4 v[80:81], v[72:75], off
	v_cvt_pk_bf16_f32 v66, v68, v69
	v_cvt_pk_bf16_f32 v67, v70, v71
	v_cvt_pk_bf16_f32 v68, v76, v77
	v_cvt_pk_bf16_f32 v69, v78, v79
	global_store_dwordx4 v[80:81], v[66:69], off offset:256
	s_and_saveexec_b64 s[48:49], s[0:1]
	s_cbranch_execz .LBB0_404
	s_waitcnt lgkmcnt(0)
	v_add_f32_e32 v66, v64, v65
	v_lshlrev_b64 v[64:65], 6, v[214:215]
	v_lshl_add_u64 v[64:65], s[34:35], 0, v[64:65]
	v_lshl_add_u64 v[64:65], s[46:47], 2, v[64:65]
	s_lshl_b32 s12, s30, 2
	v_lshl_add_u64 v[64:65], v[64:65], 0, s[12:13]
	global_store_dword v[64:65], v66, off
.LBB0_404:
	s_or_b64 exec, exec, s[48:49]
	s_waitcnt vmcnt(14)
	v_lshlrev_b32_e32 v66, 16, v156
	v_add_f32_e32 v60, v60, v66
	v_and_b32_e32 v66, 0xffff0000, v156
	v_add_f32_e32 v61, v61, v66
	v_lshlrev_b32_e32 v66, 16, v157
	v_add_f32_e32 v62, v62, v66
	v_and_b32_e32 v66, 0xffff0000, v157
	v_add_f32_e32 v63, v63, v66
	v_lshlrev_b32_e32 v66, 16, v158
	v_add_f32_e32 v66, v56, v66
	v_and_b32_e32 v56, 0xffff0000, v158
	v_add_f32_e32 v67, v57, v56
	v_lshlrev_b32_e32 v56, 16, v159
	v_add_f32_e32 v68, v58, v56
	v_and_b32_e32 v56, 0xffff0000, v159
	v_mul_f32_e32 v58, v61, v61
	v_add_f32_e32 v59, v59, v56
	v_cvt_pk_bf16_f32 v56, v60, v61
	v_fmac_f32_e32 v58, v60, v60
	v_mul_f32_e32 v60, v63, v63
	v_fmac_f32_e32 v60, v62, v62
	v_add_f32_e32 v58, v58, v60
	v_mul_f32_e32 v60, v67, v67
	v_fmac_f32_e32 v60, v66, v66
	v_add_f32_e32 v58, v60, v58
	v_mul_f32_e32 v60, v59, v59
	v_fmac_f32_e32 v60, v68, v68
	v_add_f32_e32 v58, v60, v58
	v_lshlrev_b32_e32 v60, 16, v152
	v_add_f32_e32 v52, v52, v60
	v_and_b32_e32 v60, 0xffff0000, v152
	v_add_f32_e32 v53, v53, v60
	v_lshlrev_b32_e32 v60, 16, v153
	v_add_f32_e32 v54, v54, v60
	v_and_b32_e32 v60, 0xffff0000, v153
	v_add_f32_e32 v55, v55, v60
	v_lshlrev_b32_e32 v60, 16, v154
	v_add_f32_e32 v60, v48, v60
	v_and_b32_e32 v48, 0xffff0000, v154
	v_add_f32_e32 v61, v49, v48
	v_lshlrev_b32_e32 v48, 16, v155
	v_cvt_pk_bf16_f32 v57, v62, v63
	v_add_f32_e32 v62, v50, v48
	v_and_b32_e32 v48, 0xffff0000, v155
	v_add_f32_e32 v63, v51, v48
	v_mul_f32_e32 v48, v53, v53
	v_mul_f32_e32 v49, v55, v55
	v_fmac_f32_e32 v48, v52, v52
	v_fmac_f32_e32 v49, v54, v54
	v_add_f32_e32 v48, v48, v49
	v_mul_f32_e32 v49, v61, v61
	v_fmac_f32_e32 v49, v60, v60
	v_add_f32_e32 v48, v49, v48
	v_mul_f32_e32 v49, v63, v63
	v_fmac_f32_e32 v49, v62, v62
	v_add_f32_e32 v48, v49, v48
	v_add_f32_e32 v48, v58, v48
	v_mov_b32_e32 v49, v48
	s_nop 1
	v_permlane16_swap_b32_e32 v48, v49
	s_waitcnt lgkmcnt(1)
	v_lshl_add_u64 v[64:65], s[70:71], 0, v[216:217]
	v_lshl_add_u64 v[64:65], v[200:201], 1, v[64:65]
	v_cvt_pk_bf16_f32 v58, v66, v67
	v_cvt_pk_bf16_f32 v59, v68, v59
	s_waitcnt lgkmcnt(0)
	v_add_f32_e32 v48, v48, v49
	v_mov_b32_e32 v49, v48
	s_nop 1
	v_permlane32_swap_b32_e32 v48, v49
	global_store_dwordx4 v[64:65], v[56:59], off
	v_cvt_pk_bf16_f32 v50, v52, v53
	v_cvt_pk_bf16_f32 v51, v54, v55
	v_cvt_pk_bf16_f32 v52, v60, v61
	v_cvt_pk_bf16_f32 v53, v62, v63
	global_store_dwordx4 v[64:65], v[50:53], off offset:256
	s_and_saveexec_b64 s[48:49], s[0:1]
	s_cbranch_execz .LBB0_406
	s_waitcnt lgkmcnt(0)
	v_add_f32_e32 v50, v48, v49
	v_lshlrev_b64 v[48:49], 6, v[210:211]
	v_lshl_add_u64 v[48:49], s[34:35], 0, v[48:49]
	v_lshl_add_u64 v[48:49], s[46:47], 2, v[48:49]
	s_lshl_b32 s12, s30, 2
	v_lshl_add_u64 v[48:49], v[48:49], 0, s[12:13]
	global_store_dword v[48:49], v50, off
; __device__ __forceinline__ unsigned cvt_pk_bf16(float lo, float hi) { unsigned r; asm volatile("v_cvt_pk_bf16_f32 %0, %1, %2" : "=v"(r) : "v"(lo), "v"(hi)); return r; }
; __device__ __forceinline__ float bf_lo(unsigned w) { return __uint_as_float(w << 16); }
; __device__ __forceinline__ float bf_hi(unsigned w) { return __uint_as_float(w & 0xffff0000u); }
;     __device__ __forceinline__ void operator()(const f32x4 (&acc)[2][2][4][2], const Unit& u, int wr, int wc, int fr, int fq) const {
;     ...
;         for (int ai = 0; ai < 2; ++ai)
; #pragma unroll
;             for (int m = 0; m < 4; ++m) {
;                 const int row = u.pm * BM + ai * HALF + wr * 64 + m * 16 + fr;
;                 float ss = 0.f;
; #pragma unroll
;                 for (int bj = 0; bj < 2; ++bj) {
;                     bf16_t* xp = X + (size_t)row * 1024 + col0 + bj * HALF;
;                     const u32x4 xv = xin[ai][m][bj];
;                     f32x4 y0 = acc[ai][bj][m][0], y1 = acc[ai][bj][m][1];
;                     y0[0] += bf_lo(xv.x); y0[1] += bf_hi(xv.x); y0[2] += bf_lo(xv.y); y0[3] += bf_hi(xv.y);
;                     y1[0] += bf_lo(xv.z); y1[1] += bf_hi(xv.z); y1[2] += bf_lo(xv.w); y1[3] += bf_hi(xv.w);
;                     if (FINAL) {
;                         float* op = out + (size_t)row * 1024 + col0 + bj * HALF;
;                         __builtin_nontemporal_store(y0, (f32x4*)op); __builtin_nontemporal_store(y1, (f32x4*)(op + 4));
;                     } else {
;                         u32x4 w; w.x = cvt_pk_bf16(y0[0], y0[1]); w.y = cvt_pk_bf16(y0[2], y0[3]); w.z = cvt_pk_bf16(y1[0], y1[1]); w.w = cvt_pk_bf16(y1[2], y1[3]);
;                         *(u32x4*)xp = w;
;                         ss += (y0[0] * y0[0] + y0[1] * y0[1]) + (y0[2] * y0[2] + y0[3] * y0[3]) + (y1[0] * y1[0] + y1[1] * y1[1]) + (y1[2] * y1[2] + y1[3] * y1[3]);
;                     }
;                 }
;                 if (!FINAL) {
;                     ss += __shfl_xor(ss, 16); ss += __shfl_xor(ss, 32);
;                     if (fq == 0) ssq[(size_t)row * 16 + u.pn * 4 + wc] = ss;
;                 }
.LBB0_406:
	s_or_b64 exec, exec, s[48:49]
	s_waitcnt vmcnt(14)
	v_lshlrev_b32_e32 v50, 16, v148
	v_add_f32_e32 v44, v44, v50
	v_and_b32_e32 v50, 0xffff0000, v148
	v_add_f32_e32 v45, v45, v50
	v_lshlrev_b32_e32 v50, 16, v149
	v_add_f32_e32 v46, v46, v50
	v_and_b32_e32 v50, 0xffff0000, v149
	v_add_f32_e32 v47, v47, v50
	v_lshlrev_b32_e32 v50, 16, v150
	v_add_f32_e32 v50, v40, v50
	v_and_b32_e32 v40, 0xffff0000, v150
	v_add_f32_e32 v51, v41, v40
	v_lshlrev_b32_e32 v40, 16, v151
	v_add_f32_e32 v52, v42, v40
	v_and_b32_e32 v40, 0xffff0000, v151
	v_mul_f32_e32 v42, v45, v45
	v_add_f32_e32 v43, v43, v40
	v_cvt_pk_bf16_f32 v40, v44, v45
	v_fmac_f32_e32 v42, v44, v44
	v_mul_f32_e32 v44, v47, v47
	v_fmac_f32_e32 v44, v46, v46
	v_add_f32_e32 v42, v42, v44
	v_mul_f32_e32 v44, v51, v51
	v_fmac_f32_e32 v44, v50, v50
	v_add_f32_e32 v42, v44, v42
	v_mul_f32_e32 v44, v43, v43
	v_fmac_f32_e32 v44, v52, v52
	v_add_f32_e32 v42, v44, v42
	v_lshlrev_b32_e32 v44, 16, v144
	v_add_f32_e32 v36, v36, v44
	v_and_b32_e32 v44, 0xffff0000, v144
	v_add_f32_e32 v37, v37, v44
	v_lshlrev_b32_e32 v44, 16, v145
	v_add_f32_e32 v38, v38, v44
	v_and_b32_e32 v44, 0xffff0000, v145
	v_add_f32_e32 v39, v39, v44
	v_lshlrev_b32_e32 v44, 16, v146
	v_add_f32_e32 v44, v32, v44
	v_and_b32_e32 v32, 0xffff0000, v146
	v_add_f32_e32 v45, v33, v32
	v_lshlrev_b32_e32 v32, 16, v147
	v_cvt_pk_bf16_f32 v41, v46, v47
	v_add_f32_e32 v46, v34, v32
	v_and_b32_e32 v32, 0xffff0000, v147
	v_add_f32_e32 v47, v35, v32
	v_mul_f32_e32 v32, v37, v37
	v_mul_f32_e32 v33, v39, v39
	v_fmac_f32_e32 v32, v36, v36
	v_fmac_f32_e32 v33, v38, v38
	v_add_f32_e32 v32, v32, v33
	v_mul_f32_e32 v33, v45, v45
	v_fmac_f32_e32 v33, v44, v44
	v_add_f32_e32 v32, v33, v32
	v_mul_f32_e32 v33, v47, v47
	v_fmac_f32_e32 v33, v46, v46
	v_add_f32_e32 v32, v33, v32
	v_add_f32_e32 v32, v42, v32
	v_mov_b32_e32 v33, v32
	s_nop 1
	v_permlane16_swap_b32_e32 v32, v33
	s_waitcnt lgkmcnt(1)
	v_lshl_add_u64 v[48:49], s[70:71], 0, v[212:213]
	v_lshl_add_u64 v[48:49], v[200:201], 1, v[48:49]
	v_cvt_pk_bf16_f32 v42, v50, v51
	v_cvt_pk_bf16_f32 v43, v52, v43
	s_waitcnt lgkmcnt(0)
	v_add_f32_e32 v32, v32, v33
	v_mov_b32_e32 v33, v32
	s_nop 1
	v_permlane32_swap_b32_e32 v32, v33
	global_store_dwordx4 v[48:49], v[40:43], off
	v_cvt_pk_bf16_f32 v34, v36, v37
	v_cvt_pk_bf16_f32 v35, v38, v39
	v_cvt_pk_bf16_f32 v36, v44, v45
	v_cvt_pk_bf16_f32 v37, v46, v47
	global_store_dwordx4 v[48:49], v[34:37], off offset:256
	s_and_saveexec_b64 s[48:49], s[0:1]
	s_cbranch_execz .LBB0_408
	s_waitcnt lgkmcnt(0)
	v_add_f32_e32 v34, v32, v33
	v_lshlrev_b64 v[32:33], 6, v[206:207]
	v_lshl_add_u64 v[32:33], s[34:35], 0, v[32:33]
	v_lshl_add_u64 v[32:33], s[46:47], 2, v[32:33]
	s_lshl_b32 s12, s30, 2
	v_lshl_add_u64 v[32:33], v[32:33], 0, s[12:13]
	global_store_dword v[32:33], v34, off
; __device__ __forceinline__ unsigned cvt_pk_bf16(float lo, float hi) { unsigned r; asm volatile("v_cvt_pk_bf16_f32 %0, %1, %2" : "=v"(r) : "v"(lo), "v"(hi)); return r; }
; __device__ __forceinline__ float bf_lo(unsigned w) { return __uint_as_float(w << 16); }
; __device__ __forceinline__ float bf_hi(unsigned w) { return __uint_as_float(w & 0xffff0000u); }
;     __device__ __forceinline__ void operator()(const f32x4 (&acc)[2][2][4][2], const Unit& u, int wr, int wc, int fr, int fq) const {
;     ...
;         for (int ai = 0; ai < 2; ++ai)
; #pragma unroll
;             for (int m = 0; m < 4; ++m) {
;                 const int row = u.pm * BM + ai * HALF + wr * 64 + m * 16 + fr;
;                 float ss = 0.f;
; #pragma unroll
;                 for (int bj = 0; bj < 2; ++bj) {
;                     bf16_t* xp = X + (size_t)row * 1024 + col0 + bj * HALF;
;                     const u32x4 xv = xin[ai][m][bj];
;                     f32x4 y0 = acc[ai][bj][m][0], y1 = acc[ai][bj][m][1];
;                     y0[0] += bf_lo(xv.x); y0[1] += bf_hi(xv.x); y0[2] += bf_lo(xv.y); y0[3] += bf_hi(xv.y);
;                     y1[0] += bf_lo(xv.z); y1[1] += bf_hi(xv.z); y1[2] += bf_lo(xv.w); y1[3] += bf_hi(xv.w);
;                     if (FINAL) {
;                         float* op = out + (size_t)row * 1024 + col0 + bj * HALF;
;                         __builtin_nontemporal_store(y0, (f32x4*)op); __builtin_nontemporal_store(y1, (f32x4*)(op + 4));
;                     } else {
;                         u32x4 w; w.x = cvt_pk_bf16(y0[0], y0[1]); w.y = cvt_pk_bf16(y0[2], y0[3]); w.z = cvt_pk_bf16(y1[0], y1[1]); w.w = cvt_pk_bf16(y1[2], y1[3]);
;                         *(u32x4*)xp = w;
;                         ss += (y0[0] * y0[0] + y0[1] * y0[1]) + (y0[2] * y0[2] + y0[3] * y0[3]) + (y1[0] * y1[0] + y1[1] * y1[1]) + (y1[2] * y1[2] + y1[3] * y1[3]);
;                     }
;                 }
;                 if (!FINAL) {
;                     ss += __shfl_xor(ss, 16); ss += __shfl_xor(ss, 32);
;                     if (fq == 0) ssq[(size_t)row * 16 + u.pn * 4 + wc] = ss;
;                 }
.LBB0_408:
	s_or_b64 exec, exec, s[48:49]
	s_waitcnt vmcnt(14)
	v_lshlrev_b32_e32 v34, 16, v140
	v_add_f32_e32 v28, v28, v34
	v_and_b32_e32 v34, 0xffff0000, v140
	v_add_f32_e32 v29, v29, v34
	v_lshlrev_b32_e32 v34, 16, v141
	v_add_f32_e32 v30, v30, v34
	v_and_b32_e32 v34, 0xffff0000, v141
	v_add_f32_e32 v31, v31, v34
	v_lshlrev_b32_e32 v34, 16, v142
	v_add_f32_e32 v34, v24, v34
	v_and_b32_e32 v24, 0xffff0000, v142
	v_add_f32_e32 v35, v25, v24
	v_lshlrev_b32_e32 v24, 16, v143
	v_add_f32_e32 v36, v26, v24
	v_and_b32_e32 v24, 0xffff0000, v143
	v_mul_f32_e32 v26, v29, v29
	v_add_f32_e32 v27, v27, v24
	v_cvt_pk_bf16_f32 v24, v28, v29
	v_fmac_f32_e32 v26, v28, v28
	v_mul_f32_e32 v28, v31, v31
	v_fmac_f32_e32 v28, v30, v30
	v_add_f32_e32 v26, v26, v28
	v_mul_f32_e32 v28, v35, v35
	v_fmac_f32_e32 v28, v34, v34
	v_add_f32_e32 v26, v28, v26
	v_mul_f32_e32 v28, v27, v27
	v_fmac_f32_e32 v28, v36, v36
	v_add_f32_e32 v26, v28, v26
	v_lshlrev_b32_e32 v28, 16, v136
	v_add_f32_e32 v20, v20, v28
	v_and_b32_e32 v28, 0xffff0000, v136
	v_add_f32_e32 v21, v21, v28
	v_lshlrev_b32_e32 v28, 16, v137
	v_add_f32_e32 v22, v22, v28
	v_and_b32_e32 v28, 0xffff0000, v137
	v_add_f32_e32 v23, v23, v28
	v_lshlrev_b32_e32 v28, 16, v138
	v_add_f32_e32 v28, v16, v28
	v_and_b32_e32 v16, 0xffff0000, v138
	v_add_f32_e32 v29, v17, v16
	v_lshlrev_b32_e32 v16, 16, v139
	v_cvt_pk_bf16_f32 v25, v30, v31
	v_add_f32_e32 v30, v18, v16
	v_and_b32_e32 v16, 0xffff0000, v139
	v_add_f32_e32 v31, v19, v16
	v_mul_f32_e32 v16, v21, v21
	v_mul_f32_e32 v17, v23, v23
	v_fmac_f32_e32 v16, v20, v20
	v_fmac_f32_e32 v17, v22, v22
	v_add_f32_e32 v16, v16, v17
	v_mul_f32_e32 v17, v29, v29
	v_fmac_f32_e32 v17, v28, v28
	v_add_f32_e32 v16, v17, v16
	v_mul_f32_e32 v17, v31, v31
	v_fmac_f32_e32 v17, v30, v30
	v_add_f32_e32 v16, v17, v16
	v_add_f32_e32 v16, v26, v16
	v_mov_b32_e32 v17, v16
	s_nop 1
	v_permlane16_swap_b32_e32 v16, v17
	s_waitcnt lgkmcnt(1)
	v_lshl_add_u64 v[32:33], s[70:71], 0, v[208:209]
	v_lshl_add_u64 v[32:33], v[200:201], 1, v[32:33]
	v_cvt_pk_bf16_f32 v26, v34, v35
	v_cvt_pk_bf16_f32 v27, v36, v27
	s_waitcnt lgkmcnt(0)
	v_add_f32_e32 v16, v16, v17
	v_mov_b32_e32 v17, v16
	s_nop 1
	v_permlane32_swap_b32_e32 v16, v17
	global_store_dwordx4 v[32:33], v[24:27], off
	v_cvt_pk_bf16_f32 v18, v20, v21
	v_cvt_pk_bf16_f32 v19, v22, v23
	v_cvt_pk_bf16_f32 v20, v28, v29
	v_cvt_pk_bf16_f32 v21, v30, v31
	global_store_dwordx4 v[32:33], v[18:21], off offset:256
	s_and_saveexec_b64 s[48:49], s[0:1]
	s_cbranch_execz .LBB0_410
	s_waitcnt lgkmcnt(0)
	v_add_f32_e32 v18, v16, v17
	v_lshlrev_b64 v[16:17], 6, v[202:203]
	v_lshl_add_u64 v[16:17], s[34:35], 0, v[16:17]
	v_lshl_add_u64 v[16:17], s[46:47], 2, v[16:17]
	s_lshl_b32 s12, s30, 2
	v_lshl_add_u64 v[16:17], v[16:17], 0, s[12:13]
	global_store_dword v[16:17], v18, off
.LBB0_410:
	s_or_b64 exec, exec, s[48:49]
	s_waitcnt vmcnt(14)
	v_lshlrev_b32_e32 v18, 16, v132
	v_add_f32_e32 v12, v12, v18
	v_and_b32_e32 v18, 0xffff0000, v132
	v_add_f32_e32 v13, v13, v18
	v_lshlrev_b32_e32 v18, 16, v133
	v_add_f32_e32 v14, v14, v18
	v_and_b32_e32 v18, 0xffff0000, v133
	v_add_f32_e32 v15, v15, v18
	v_lshlrev_b32_e32 v18, 16, v134
	v_add_f32_e32 v18, v8, v18
	v_and_b32_e32 v8, 0xffff0000, v134
	v_add_f32_e32 v19, v9, v8
	v_lshlrev_b32_e32 v8, 16, v135
	v_add_f32_e32 v20, v10, v8
	v_and_b32_e32 v8, 0xffff0000, v135
	v_mul_f32_e32 v10, v13, v13
	v_add_f32_e32 v11, v11, v8
	v_cvt_pk_bf16_f32 v8, v12, v13
	v_fmac_f32_e32 v10, v12, v12
	v_mul_f32_e32 v12, v15, v15
	v_fmac_f32_e32 v12, v14, v14
	v_add_f32_e32 v10, v10, v12
	v_mul_f32_e32 v12, v19, v19
	v_fmac_f32_e32 v12, v18, v18
	v_add_f32_e32 v10, v12, v10
	v_mul_f32_e32 v12, v11, v11
	v_fmac_f32_e32 v12, v20, v20
	v_add_f32_e32 v10, v12, v10
	v_lshlrev_b32_e32 v12, 16, v124
	v_add_f32_e32 v4, v4, v12
	v_and_b32_e32 v12, 0xffff0000, v124
	v_add_f32_e32 v5, v5, v12
	v_lshlrev_b32_e32 v12, 16, v125
	v_add_f32_e32 v6, v6, v12
	v_and_b32_e32 v12, 0xffff0000, v125
	v_add_f32_e32 v7, v7, v12
	v_lshlrev_b32_e32 v12, 16, v126
	v_add_f32_e32 v12, v0, v12
	v_and_b32_e32 v0, 0xffff0000, v126
	v_add_f32_e32 v13, v1, v0
	v_lshlrev_b32_e32 v0, 16, v127
	v_cvt_pk_bf16_f32 v9, v14, v15
	v_add_f32_e32 v14, v2, v0
	v_and_b32_e32 v0, 0xffff0000, v127
	v_add_f32_e32 v15, v3, v0
	v_mul_f32_e32 v0, v5, v5
	v_mul_f32_e32 v1, v7, v7
	v_fmac_f32_e32 v0, v4, v4
	v_fmac_f32_e32 v1, v6, v6
	v_add_f32_e32 v0, v0, v1
	v_mul_f32_e32 v1, v13, v13
	v_fmac_f32_e32 v1, v12, v12
	v_add_f32_e32 v0, v1, v0
	v_mul_f32_e32 v1, v15, v15
	v_fmac_f32_e32 v1, v14, v14
	v_add_f32_e32 v0, v1, v0
	v_add_f32_e32 v0, v10, v0
	v_mov_b32_e32 v1, v0
	s_nop 1
	v_permlane16_swap_b32_e32 v0, v1
	s_waitcnt lgkmcnt(1)
	v_lshl_add_u64 v[16:17], s[70:71], 0, v[204:205]
	v_lshl_add_u64 v[16:17], v[200:201], 1, v[16:17]
	v_cvt_pk_bf16_f32 v10, v18, v19
	v_cvt_pk_bf16_f32 v11, v20, v11
	s_waitcnt lgkmcnt(0)
	v_add_f32_e32 v0, v0, v1
	v_mov_b32_e32 v1, v0
	s_nop 1
	v_permlane32_swap_b32_e32 v0, v1
	global_store_dwordx4 v[16:17], v[8:11], off
	v_cvt_pk_bf16_f32 v2, v4, v5
	v_cvt_pk_bf16_f32 v3, v6, v7
	v_cvt_pk_bf16_f32 v4, v12, v13
	v_cvt_pk_bf16_f32 v5, v14, v15
	global_store_dwordx4 v[16:17], v[2:5], off offset:256
	s_and_saveexec_b64 s[48:49], s[0:1]
	s_cbranch_execz .LBB0_412
	s_waitcnt lgkmcnt(0)
	v_add_f32_e32 v2, v0, v1
	v_lshlrev_b64 v[0:1], 6, v[198:199]
	v_lshl_add_u64 v[0:1], s[34:35], 0, v[0:1]
	v_lshl_add_u64 v[0:1], s[46:47], 2, v[0:1]
	s_lshl_b32 s12, s30, 2
	v_lshl_add_u64 v[0:1], v[0:1], 0, s[12:13]
	global_store_dword v[0:1], v2, off

; __device__ __forceinline__ float fast_sigmoid(float x) { return __builtin_amdgcn_rcpf(1.0f + __expf(-x)); }
; __device__ __forceinline__ void rows_rstd(const float* ssq, int row0, int fq, float (&rs)[2][4]) {
;     ...
;         for (int m = 0; m < 4; ++m) pr[ai][m] = *(const f32x4*)(ssq + (size_t)(row0 + ai * HALF + m * 16) * 16 + 4 * fq);
; #pragma unroll
;     for (int ai = 0; ai < 2; ++ai)
; #pragma unroll
;         for (int m = 0; m < 4; ++m) { float t = (pr[ai][m][0] + pr[ai][m][1]) + (pr[ai][m][2] + pr[ai][m][3]); t += __shfl_xor(t, 16); t += __shfl_xor(t, 32); rs[ai][m] = __builtin_amdgcn_rsqf(t * (1.0f / 1024.0f) + 1e-6f); }
;     __device__ __forceinline__ void operator()(const f32x4 (&acc)[2][2][4][2], const Unit& u, int wr, int wc, int fr, int fq) const {
;         const int col0 = u.pn * HALF + wc * 32 + 8 * fq;
;         float rsv[2][4]; rows_rstd(ssq, u.pm * BM + wr * 64 + fr, fq, rsv);
; #pragma unroll
;         for (int ai = 0; ai < 2; ++ai)
; #pragma unroll
;             for (int m = 0; m < 4; ++m) {
;                 const int row = u.pm * BM + ai * HALF + wr * 64 + m * 16 + fr;
;                 const float rs = rsv[ai][m];
;                 float h[8];
; #pragma unroll
;                 for (int n = 0; n < 2; ++n)
; #pragma unroll
;                     for (int i = 0; i < 4; ++i) { const float g = acc[ai][0][m][n][i] * rs, up = acc[ai][1][m][n][i] * rs; h[4 * n + i] = g * up * fast_sigmoid(g); }
.LBB0_485:
	v_mbcnt_lo_u32_b32 v252, -1, 0
	v_mbcnt_hi_u32_b32 v252, -1, v252
	v_and_b32_e32 v252, 48, v252
	v_lshl_add_u32 v252, v149, 6, v252
	v_add_u32_e32 v252, 0x20000, v252
	v_lshl_add_u32 v170, s40, 8, v149
	v_ashrrev_i32_e32 v171, 31, v170
	v_or_b32_e32 v166, 16, v170
	v_lshlrev_b64 v[144:145], 6, v[170:171]
	v_ashrrev_i32_e32 v167, 31, v166
	v_or_b32_e32 v162, 32, v170
	v_lshl_add_u64 v[144:145], v[136:137], 0, v[144:145]
	v_lshlrev_b64 v[146:147], 6, v[166:167]
	v_ashrrev_i32_e32 v163, 31, v162
	v_or_b32_e32 v158, 48, v170
	v_lshl_add_u64 v[146:147], v[136:137], 0, v[146:147]
	ds_read_b128 v[178:181], v252 offset:0
	ds_read_b128 v[182:185], v252 offset:1024
	v_lshlrev_b64 v[144:145], 6, v[162:163]
	v_ashrrev_i32_e32 v159, 31, v158
	v_add_u32_e32 v154, 0x80, v170
	v_lshl_add_u64 v[144:145], v[136:137], 0, v[144:145]
	v_lshlrev_b64 v[146:147], 6, v[158:159]
	v_ashrrev_i32_e32 v155, 31, v154
	v_lshl_add_u64 v[146:147], v[136:137], 0, v[146:147]
	ds_read_b128 v[186:189], v252 offset:2048
	ds_read_b128 v[190:193], v252 offset:3072
	v_lshlrev_b64 v[144:145], 6, v[154:155]
	v_lshl_add_u64 v[144:145], v[136:137], 0, v[144:145]
	ds_read_b128 v[194:197], v252 offset:8192
	v_add_u32_e32 v150, 0x90, v170
	v_ashrrev_i32_e32 v151, 31, v150
	v_lshlrev_b64 v[144:145], 6, v[150:151]
	v_add_u32_e32 v146, 0xa0, v170
	v_lshl_add_u64 v[144:145], v[136:137], 0, v[144:145]
	v_ashrrev_i32_e32 v147, 31, v146
	ds_read_b128 v[198:201], v252 offset:9216
	v_lshlrev_b64 v[144:145], 6, v[146:147]
	v_lshl_add_u64 v[144:145], v[136:137], 0, v[144:145]
	ds_read_b128 v[202:205], v252 offset:10240
	v_add_u32_e32 v144, 0xb0, v170
	v_ashrrev_i32_e32 v145, 31, v144
	v_lshlrev_b64 v[206:207], 6, v[144:145]
	v_lshl_add_u64 v[206:207], v[136:137], 0, v[206:207]
	ds_read_b128 v[206:209], v252 offset:11264
	v_and_b32_e32 v147, 64, v175
	v_xor_b32_e32 v145, 16, v175
	v_add_u32_e32 v147, 64, v147
	v_xor_b32_e32 v148, 32, v175
	v_cmp_lt_i32_e32 vcc, v145, v147
	v_lshl_or_b32 v172, s54, 7, v157
	v_ashrrev_i32_e32 v173, 31, v172
	v_cndmask_b32_e32 v145, v175, v145, vcc
	v_cmp_lt_i32_e32 vcc, v148, v147
	v_lshlrev_b32_e32 v145, 2, v145
	s_waitcnt lgkmcnt(0)
	v_mov_b32_e32 v210, v179
	v_mov_b32_e32 v211, v180
	v_mov_b32_e32 v179, v181
	v_pk_add_f32 v[178:179], v[210:211], v[178:179]
	v_mov_b32_e32 v180, v183
	v_mov_b32_e32 v181, v184
	v_mov_b32_e32 v183, v185
	v_cndmask_b32_e32 v147, v175, v148, vcc
	v_mov_b32_e32 v184, v187
	v_mov_b32_e32 v185, v188
	v_mov_b32_e32 v187, v189
	v_mov_b32_e32 v188, v191
	v_mov_b32_e32 v189, v192
	v_mov_b32_e32 v191, v193
	v_add_f32_e32 v148, v178, v179
	v_pk_add_f32 v[178:179], v[180:181], v[182:183]
	v_pk_add_f32 v[180:181], v[184:185], v[186:187]
	v_pk_add_f32 v[182:183], v[188:189], v[190:191]
	v_mov_b32_e32 v192, v195
	v_mov_b32_e32 v193, v196
	v_mov_b32_e32 v195, v197
	v_mov_b32_e32 v151, v148
	s_nop 1
	v_permlane16_swap_b32_e32 v148, v151
	v_add_f32_e32 v152, v178, v179
	v_add_f32_e32 v155, v180, v181
	v_add_f32_e32 v156, v182, v183
	v_pk_add_f32 v[184:185], v[192:193], v[194:195]
	v_mov_b32_e32 v160, v152
	s_nop 1
	v_permlane16_swap_b32_e32 v152, v160
	v_mov_b32_e32 v163, v155
	s_nop 1
	v_permlane16_swap_b32_e32 v155, v163
	v_mov_b32_e32 v164, v156
	s_nop 1
	v_permlane16_swap_b32_e32 v156, v164
	v_add_f32_e32 v159, v184, v185
	v_mov_b32_e32 v167, v159
	s_nop 1
	v_permlane16_swap_b32_e32 v159, v167
	v_lshlrev_b32_e32 v147, 2, v147
	s_waitcnt lgkmcnt(4)
	v_add_f32_e32 v148, v148, v151
	v_mov_b32_e32 v151, v148
	s_nop 1
	v_permlane32_swap_b32_e32 v148, v151
	s_waitcnt lgkmcnt(4)
	v_add_f32_e32 v152, v152, v160
	s_waitcnt lgkmcnt(3)
	v_add_f32_e32 v155, v155, v163
	s_waitcnt lgkmcnt(2)
	v_add_f32_e32 v156, v156, v164
	v_mov_b32_e32 v160, v152
	s_nop 1
	v_permlane32_swap_b32_e32 v152, v160
	v_mov_b32_e32 v163, v155
	s_nop 1
	v_permlane32_swap_b32_e32 v155, v163
	v_mov_b32_e32 v164, v156
	s_nop 1
	v_permlane32_swap_b32_e32 v156, v164
	s_waitcnt lgkmcnt(4)
	v_add_f32_e32 v159, v159, v167
	v_mov_b32_e32 v167, v159
	s_nop 1
	v_permlane32_swap_b32_e32 v159, v167
	s_waitcnt lgkmcnt(4)
	v_add_f32_e32 v148, v148, v151
	v_fmamk_f32 v148, v148, 0x3a800000, v176
	s_waitcnt lgkmcnt(3)
	v_add_f32_e32 v151, v152, v160
	s_waitcnt lgkmcnt(2)
	v_add_f32_e32 v152, v155, v163
	s_waitcnt lgkmcnt(1)
	v_add_f32_e32 v155, v156, v164
	v_mov_b32_e32 v180, v199
	v_mov_b32_e32 v181, v200
	v_mov_b32_e32 v199, v201
	v_rsq_f32_e32 v178, v148
	v_fmamk_f32 v148, v151, 0x3a800000, v176
	v_fmamk_f32 v151, v152, 0x3a800000, v176
	v_fmamk_f32 v152, v155, 0x3a800000, v176
	v_pk_add_f32 v[180:181], v[180:181], v[198:199]
	v_rsq_f32_e32 v174, v148
	v_add_f32_e32 v148, v180, v181
	v_rsq_f32_e32 v164, v152
	s_waitcnt lgkmcnt(0)
	v_add_f32_e32 v152, v159, v167
	v_mov_b32_e32 v180, v203
	v_mov_b32_e32 v181, v204
	v_mov_b32_e32 v203, v205
	v_fmamk_f32 v152, v152, 0x3a800000, v176
	v_pk_add_f32 v[180:181], v[180:181], v[202:203]
	v_rsq_f32_e32 v160, v152
	v_add_f32_e32 v152, v180, v181
	v_mov_b32_e32 v180, v207
	v_mov_b32_e32 v181, v208
	v_mov_b32_e32 v207, v209
	v_pk_add_f32 v[180:181], v[180:181], v[206:207]
	v_rsq_f32_e32 v168, v151
	v_add_f32_e32 v156, v180, v181
	v_mul_f32_e32 v180, v124, v178
	v_mul_f32_e32 v181, v120, v178
	v_mov_b32_e32 v151, v148
	s_nop 1
	v_permlane16_swap_b32_e32 v148, v151
	v_mul_f32_e32 v120, 0xbfb8aa3b, v180
	v_exp_f32_e32 v124, v120
	v_mul_f32_e32 v120, v125, v178
	v_mul_f32_e32 v121, v121, v178
	s_waitcnt lgkmcnt(0)
	v_add_f32_e32 v148, v148, v151
	v_mul_f32_e32 v125, 0xbfb8aa3b, v120
	v_exp_f32_e32 v125, v125
	v_mov_b32_e32 v151, v148
	s_nop 1
	v_permlane32_swap_b32_e32 v148, v151
	v_mov_b32_e32 v155, v152
	s_nop 1
	v_permlane16_swap_b32_e32 v152, v155
	v_mov_b32_e32 v145, v156
	s_nop 1
	v_permlane16_swap_b32_e32 v156, v145
	v_add_f32_e32 v125, 1.0, v125
	v_rcp_f32_e32 v125, v125
	v_mul_f32_e32 v120, v120, v121
	s_waitcnt lgkmcnt(2)
; __device__ __forceinline__ unsigned cvt_pk_bf16(float lo, float hi) { unsigned r; asm volatile("v_cvt_pk_bf16_f32 %0, %1, %2" : "=v"(r) : "v"(lo), "v"(hi)); return r; }
; __device__ __forceinline__ float fast_sigmoid(float x) { return __builtin_amdgcn_rcpf(1.0f + __expf(-x)); }
; __device__ __forceinline__ void rows_rstd(const float* ssq, int row0, int fq, float (&rs)[2][4]) {
;     ...
;         for (int m = 0; m < 4; ++m) { float t = (pr[ai][m][0] + pr[ai][m][1]) + (pr[ai][m][2] + pr[ai][m][3]); t += __shfl_xor(t, 16); t += __shfl_xor(t, 32); rs[ai][m] = __builtin_amdgcn_rsqf(t * (1.0f / 1024.0f) + 1e-6f); }
;     __device__ __forceinline__ void operator()(const f32x4 (&acc)[2][2][4][2], const Unit& u, int wr, int wc, int fr, int fq) const {
;     ...
;                 const int row = u.pm * BM + ai * HALF + wr * 64 + m * 16 + fr;
;                 const float rs = rsv[ai][m];
;                 float h[8];
; #pragma unroll
;                 for (int n = 0; n < 2; ++n)
; #pragma unroll
;                     for (int i = 0; i < 4; ++i) { const float g = acc[ai][0][m][n][i] * rs, up = acc[ai][1][m][n][i] * rs; h[4 * n + i] = g * up * fast_sigmoid(g); }
;                 u32x4 w; w.x = cvt_pk_bf16(h[0], h[1]); w.y = cvt_pk_bf16(h[2], h[3]); w.z = cvt_pk_bf16(h[4], h[5]); w.w = cvt_pk_bf16(h[6], h[7]);
;                 *(u32x4*)(H + (size_t)row * 2816 + col0) = w;
	v_add_f32_e32 v148, v148, v151
	s_waitcnt lgkmcnt(1)
	v_add_f32_e32 v151, v152, v155
	s_waitcnt lgkmcnt(0)
	v_add_f32_e32 v145, v156, v145
	v_mul_f32_e32 v125, v120, v125
	v_mov_b32_e32 v152, v151
	s_nop 1
	v_permlane32_swap_b32_e32 v151, v152
	v_mov_b32_e32 v147, v145
	s_nop 1
	v_permlane32_swap_b32_e32 v145, v147
	v_mul_f32_e32 v120, v126, v178
	v_mul_f32_e32 v121, v122, v178
	v_add_f32_e32 v124, 1.0, v124
	v_mul_f32_e32 v122, 0xbfb8aa3b, v120
	v_exp_f32_e32 v126, v122
	v_mul_f32_e32 v122, v127, v178
	v_mul_f32_e32 v123, v123, v178
	v_fmamk_f32 v148, v148, 0x3a800000, v176
	v_rcp_f32_e32 v124, v124
	v_mul_f32_e32 v127, 0xbfb8aa3b, v122
	v_rsq_f32_e32 v156, v148
	s_waitcnt lgkmcnt(1)
	v_add_f32_e32 v148, v151, v152
	s_waitcnt lgkmcnt(0)
	v_add_f32_e32 v145, v145, v147
	v_exp_f32_e32 v127, v127
	v_fmamk_f32 v148, v148, 0x3a800000, v176
	v_fmamk_f32 v145, v145, 0x3a800000, v176
	v_rsq_f32_e32 v152, v148
	v_rsq_f32_e32 v148, v145
	v_mul_f32_e32 v145, v180, v181
	v_mul_f32_e32 v124, v145, v124
	v_mul_f32_e32 v145, v120, v121
	v_add_f32_e32 v120, 1.0, v126
	v_rcp_f32_e32 v126, v120
	v_add_f32_e32 v120, 1.0, v127
	v_rcp_f32_e32 v127, v120
	v_mul_f32_e32 v120, v116, v178
	v_mul_f32_e32 v121, v112, v178
	v_mul_f32_e32 v116, v122, v123
	v_mul_f32_e32 v112, 0xbfb8aa3b, v120
	v_exp_f32_e32 v112, v112
	v_mul_f32_e32 v122, v116, v127
	v_mul_f32_e32 v120, v120, v121
	v_mul_f32_e32 v126, v145, v126
	v_add_f32_e32 v112, 1.0, v112
	v_rcp_f32_e32 v116, v112
	v_mul_f32_e32 v112, v117, v178
	v_mul_f32_e32 v113, v113, v178
	v_mov_b32_e32 v123, v104
	v_mul_f32_e32 v117, 0xbfb8aa3b, v112
	v_exp_f32_e32 v117, v117
	v_mul_f32_e32 v120, v120, v116
	v_mul_f32_e32 v116, v112, v113
	v_add_f32_e32 v112, 1.0, v117
	v_rcp_f32_e32 v117, v112
	v_mul_f32_e32 v112, v118, v178
	v_mul_f32_e32 v113, v114, v178
	s_andn2_b64 vcc, exec, s[20:21]
	v_mul_f32_e32 v114, 0xbfb8aa3b, v112
	v_exp_f32_e32 v118, v114
	v_mul_f32_e32 v114, v119, v178
	v_mul_f32_e32 v115, v115, v178
	v_mul_f32_e32 v121, v116, v117
	v_mul_f32_e32 v119, 0xbfb8aa3b, v114
	v_exp_f32_e32 v119, v119
	v_add_f32_e32 v116, 1.0, v118
	v_rcp_f32_e32 v116, v116
	v_mul_f32_e32 v112, v112, v113
	v_add_f32_e32 v117, 1.0, v119
	v_rcp_f32_e32 v117, v117
	v_mul_f32_e32 v113, v114, v115
	v_mul_f32_e32 v112, v112, v116
	v_cvt_pk_bf16_f32 v116, v124, v125
	v_mul_f32_e32 v113, v113, v117
	v_cvt_pk_bf16_f32 v117, v126, v122
	v_mul_f32_e32 v122, v108, v174
	v_mul_f32_e32 v123, v123, v174
	v_cvt_pk_bf16_f32 v118, v120, v121
	v_cvt_pk_bf16_f32 v119, v112, v113
	v_mov_b64_e32 v[112:113], s[6:7]
	v_mul_f32_e32 v104, 0xbfb8aa3b, v122
	v_exp_f32_e32 v108, v104
	v_mul_f32_e32 v104, v109, v174
	v_mul_f32_e32 v105, v105, v174
	v_mad_i64_i32 v[120:121], s[42:43], v170, s53, v[112:113]
	v_mul_f32_e32 v109, 0xbfb8aa3b, v104
	v_exp_f32_e32 v109, v109
	v_mul_f32_e32 v104, v104, v105
	v_mov_b32_e32 v105, v106
	v_add_f32_e32 v108, 1.0, v108
	v_add_f32_e32 v109, 1.0, v109
	v_rcp_f32_e32 v109, v109
	v_rcp_f32_e32 v108, v108
	v_lshlrev_b64 v[114:115], 1, v[172:173]
	v_lshl_add_u64 v[120:121], v[120:121], 0, v[114:115]
	v_mul_f32_e32 v109, v104, v109
	v_mul_f32_e32 v104, v110, v174
	v_mul_f32_e32 v105, v105, v174
	global_store_dwordx4 v[120:121], v[116:119], off
	v_mul_f32_e32 v106, 0xbfb8aa3b, v104
	v_exp_f32_e32 v110, v106
	v_mul_f32_e32 v106, v111, v174
	v_mul_f32_e32 v107, v107, v174
	v_mul_f32_e32 v116, v122, v123
	v_mul_f32_e32 v111, 0xbfb8aa3b, v106
	v_exp_f32_e32 v111, v111
	v_mul_f32_e32 v108, v116, v108
	v_mul_f32_e32 v116, v104, v105
	v_add_f32_e32 v104, 1.0, v110
	v_rcp_f32_e32 v110, v104
	v_add_f32_e32 v104, 1.0, v111
	v_rcp_f32_e32 v111, v104
	v_mul_f32_e32 v104, v100, v174
	v_mul_f32_e32 v105, v96, v174
	v_mul_f32_e32 v106, v106, v107
	v_mul_f32_e32 v96, 0xbfb8aa3b, v104
	v_exp_f32_e32 v96, v96
	v_mul_f32_e32 v104, v104, v105
	v_mul_f32_e32 v100, v116, v110
	v_mul_f32_e32 v106, v106, v111
	v_add_f32_e32 v96, 1.0, v96
	v_rcp_f32_e32 v107, v96
	v_mul_f32_e32 v96, v101, v174
	v_mul_f32_e32 v97, v97, v174
	s_mov_b64 s[20:21], -1
	v_mul_f32_e32 v101, 0xbfb8aa3b, v96
	v_exp_f32_e32 v101, v101
	v_mul_f32_e32 v105, v96, v97
	v_mov_b32_e32 v97, v98
	v_mul_f32_e32 v104, v104, v107
	v_add_f32_e32 v96, 1.0, v101
	v_rcp_f32_e32 v101, v96
	v_mul_f32_e32 v96, v102, v174
	v_mul_f32_e32 v97, v97, v174
	v_mul_f32_e32 v101, v105, v101
	v_mul_f32_e32 v98, 0xbfb8aa3b, v96
	v_exp_f32_e32 v102, v98
	v_mul_f32_e32 v98, v103, v174
	v_mul_f32_e32 v99, v99, v174
	v_mul_f32_e32 v96, v96, v97
	v_mul_f32_e32 v103, 0xbfb8aa3b, v98
	v_exp_f32_e32 v103, v103
	v_add_f32_e32 v102, 1.0, v102
	v_rcp_f32_e32 v102, v102
	v_add_f32_e32 v103, 1.0, v103
	v_rcp_f32_e32 v103, v103
	v_mul_f32_e32 v102, v96, v102
	v_mul_f32_e32 v96, v98, v99
	v_mul_f32_e32 v99, v96, v103
	v_cvt_pk_bf16_f32 v96, v108, v109
	v_cvt_pk_bf16_f32 v97, v100, v106
	v_cvt_pk_bf16_f32 v98, v104, v101
	v_cvt_pk_bf16_f32 v99, v102, v99
	v_mul_f32_e32 v102, v92, v168
	v_mul_f32_e32 v103, v88, v168
	v_mad_i64_i32 v[100:101], s[42:43], v166, s53, v[112:113]
	v_mul_f32_e32 v88, 0xbfb8aa3b, v102
	v_exp_f32_e32 v92, v88
	v_mul_f32_e32 v88, v93, v168
	v_mul_f32_e32 v89, v89, v168
	v_lshl_add_u64 v[100:101], v[100:101], 0, v[114:115]
	v_mul_f32_e32 v93, 0xbfb8aa3b, v88
	v_exp_f32_e32 v93, v93
	v_mul_f32_e32 v88, v88, v89
	v_mov_b32_e32 v89, v90
	v_add_f32_e32 v92, 1.0, v92
	v_add_f32_e32 v93, 1.0, v93
	v_rcp_f32_e32 v93, v93
	v_rcp_f32_e32 v92, v92
	global_store_dwordx4 v[100:101], v[96:99], off
	v_mul_f32_e32 v93, v88, v93
	v_mul_f32_e32 v88, v94, v168
	v_mul_f32_e32 v89, v89, v168
	v_mul_f32_e32 v96, v102, v103
	v_mul_f32_e32 v90, 0xbfb8aa3b, v88
	v_exp_f32_e32 v94, v90
	v_mul_f32_e32 v90, v95, v168
; __device__ __forceinline__ unsigned cvt_pk_bf16(float lo, float hi) { unsigned r; asm volatile("v_cvt_pk_bf16_f32 %0, %1, %2" : "=v"(r) : "v"(lo), "v"(hi)); return r; }
; __device__ __forceinline__ float fast_sigmoid(float x) { return __builtin_amdgcn_rcpf(1.0f + __expf(-x)); }
;     __device__ __forceinline__ void operator()(const f32x4 (&acc)[2][2][4][2], const Unit& u, int wr, int wc, int fr, int fq) const {
;     ...
;                 const int row = u.pm * BM + ai * HALF + wr * 64 + m * 16 + fr;
;                 const float rs = rsv[ai][m];
;                 float h[8];
; #pragma unroll
;                 for (int n = 0; n < 2; ++n)
; #pragma unroll
;                     for (int i = 0; i < 4; ++i) { const float g = acc[ai][0][m][n][i] * rs, up = acc[ai][1][m][n][i] * rs; h[4 * n + i] = g * up * fast_sigmoid(g); }
;                 u32x4 w; w.x = cvt_pk_bf16(h[0], h[1]); w.y = cvt_pk_bf16(h[2], h[3]); w.z = cvt_pk_bf16(h[4], h[5]); w.w = cvt_pk_bf16(h[6], h[7]);
;                 *(u32x4*)(H + (size_t)row * 2816 + col0) = w;
	v_mul_f32_e32 v91, v91, v168
	v_mul_f32_e32 v92, v96, v92
	v_mul_f32_e32 v95, 0xbfb8aa3b, v90
	v_exp_f32_e32 v95, v95
	v_mul_f32_e32 v96, v88, v89
	v_add_f32_e32 v88, 1.0, v94
	v_rcp_f32_e32 v94, v88
	v_add_f32_e32 v88, 1.0, v95
	v_rcp_f32_e32 v95, v88
	v_mul_f32_e32 v88, v84, v168
	v_mul_f32_e32 v89, v80, v168
	v_mul_f32_e32 v90, v90, v91
	v_mul_f32_e32 v80, 0xbfb8aa3b, v88
	v_exp_f32_e32 v80, v80
	v_mul_f32_e32 v88, v88, v89
	v_mul_f32_e32 v84, v96, v94
	v_mul_f32_e32 v90, v90, v95
	v_add_f32_e32 v80, 1.0, v80
	v_rcp_f32_e32 v91, v80
	v_mul_f32_e32 v80, v85, v168
	v_mul_f32_e32 v81, v81, v168
	v_mul_f32_e32 v88, v88, v91
	v_mul_f32_e32 v85, 0xbfb8aa3b, v80
	v_exp_f32_e32 v85, v85
	v_mul_f32_e32 v89, v80, v81
	v_add_f32_e32 v80, 1.0, v85
	v_rcp_f32_e32 v85, v80
	v_mul_f32_e32 v80, v86, v168
	v_mul_f32_e32 v81, v82, v168
	v_mul_f32_e32 v85, v89, v85
	v_mul_f32_e32 v82, 0xbfb8aa3b, v80
	v_exp_f32_e32 v86, v82
	v_mul_f32_e32 v82, v87, v168
	v_mul_f32_e32 v83, v83, v168
	v_mul_f32_e32 v80, v80, v81
	v_mul_f32_e32 v87, 0xbfb8aa3b, v82
	v_exp_f32_e32 v87, v87
	v_add_f32_e32 v86, 1.0, v86
	v_rcp_f32_e32 v86, v86
	v_add_f32_e32 v87, 1.0, v87
	v_rcp_f32_e32 v87, v87
	v_mul_f32_e32 v86, v80, v86
	v_mul_f32_e32 v80, v82, v83
	v_mul_f32_e32 v83, v80, v87
	v_cvt_pk_bf16_f32 v80, v92, v93
	v_cvt_pk_bf16_f32 v81, v84, v90
	v_cvt_pk_bf16_f32 v82, v88, v85
	v_cvt_pk_bf16_f32 v83, v86, v83
	v_mul_f32_e32 v86, v76, v164
	v_mul_f32_e32 v87, v72, v164
	v_mad_i64_i32 v[84:85], s[42:43], v162, s53, v[112:113]
	v_mul_f32_e32 v72, 0xbfb8aa3b, v86
	v_exp_f32_e32 v76, v72
	v_mul_f32_e32 v72, v77, v164
	v_mul_f32_e32 v73, v73, v164
	v_lshl_add_u64 v[84:85], v[84:85], 0, v[114:115]
	v_mul_f32_e32 v77, 0xbfb8aa3b, v72
	v_exp_f32_e32 v77, v77
	v_mul_f32_e32 v72, v72, v73
	v_mov_b32_e32 v73, v74
	v_add_f32_e32 v76, 1.0, v76
	v_add_f32_e32 v77, 1.0, v77
	v_rcp_f32_e32 v77, v77
	v_rcp_f32_e32 v76, v76
	global_store_dwordx4 v[84:85], v[80:83], off
	v_mul_f32_e32 v77, v72, v77
	v_mul_f32_e32 v72, v78, v164
	v_mul_f32_e32 v73, v73, v164
	v_mul_f32_e32 v80, v86, v87
	v_mul_f32_e32 v74, 0xbfb8aa3b, v72
	v_exp_f32_e32 v78, v74
	v_mul_f32_e32 v74, v79, v164
	v_mul_f32_e32 v75, v75, v164
	v_mul_f32_e32 v76, v80, v76
	v_mul_f32_e32 v79, 0xbfb8aa3b, v74
	v_exp_f32_e32 v79, v79
	v_mul_f32_e32 v80, v72, v73
	v_add_f32_e32 v72, 1.0, v78
	v_rcp_f32_e32 v78, v72
	v_add_f32_e32 v72, 1.0, v79
	v_rcp_f32_e32 v79, v72
	v_mul_f32_e32 v72, v68, v164
	v_mul_f32_e32 v73, v64, v164
	v_mul_f32_e32 v74, v74, v75
	v_mul_f32_e32 v64, 0xbfb8aa3b, v72
	v_exp_f32_e32 v64, v64
	v_mul_f32_e32 v72, v72, v73
	v_mul_f32_e32 v68, v80, v78
	v_mul_f32_e32 v74, v74, v79
	v_add_f32_e32 v64, 1.0, v64
	v_rcp_f32_e32 v75, v64
	v_mul_f32_e32 v64, v69, v164
	v_mul_f32_e32 v65, v65, v164
	v_mul_f32_e32 v72, v72, v75
	v_mul_f32_e32 v69, 0xbfb8aa3b, v64
	v_exp_f32_e32 v69, v69
	v_mul_f32_e32 v73, v64, v65
	v_add_f32_e32 v64, 1.0, v69
	v_rcp_f32_e32 v69, v64
	v_mul_f32_e32 v64, v70, v164
	v_mul_f32_e32 v65, v66, v164
	v_mul_f32_e32 v69, v73, v69
	v_mul_f32_e32 v66, 0xbfb8aa3b, v64
	v_exp_f32_e32 v70, v66
	v_mul_f32_e32 v66, v71, v164
	v_mul_f32_e32 v67, v67, v164
	v_mul_f32_e32 v64, v64, v65
	v_mul_f32_e32 v71, 0xbfb8aa3b, v66
	v_exp_f32_e32 v71, v71
	v_add_f32_e32 v70, 1.0, v70
	v_rcp_f32_e32 v70, v70
	v_add_f32_e32 v71, 1.0, v71
	v_rcp_f32_e32 v71, v71
	v_mul_f32_e32 v70, v64, v70
	v_mul_f32_e32 v64, v66, v67
	v_mul_f32_e32 v67, v64, v71
	v_cvt_pk_bf16_f32 v64, v76, v77
	v_cvt_pk_bf16_f32 v65, v68, v74
	v_cvt_pk_bf16_f32 v66, v72, v69
	v_cvt_pk_bf16_f32 v67, v70, v67
	v_mul_f32_e32 v70, v60, v160
	v_mul_f32_e32 v71, v56, v160
	v_mad_i64_i32 v[68:69], s[42:43], v158, s53, v[112:113]
	v_mul_f32_e32 v56, 0xbfb8aa3b, v70
	v_exp_f32_e32 v60, v56
	v_mul_f32_e32 v56, v61, v160
	v_mul_f32_e32 v57, v57, v160
	v_lshl_add_u64 v[68:69], v[68:69], 0, v[114:115]
	v_mul_f32_e32 v61, 0xbfb8aa3b, v56
	v_exp_f32_e32 v61, v61
	v_mul_f32_e32 v56, v56, v57
	v_mov_b32_e32 v57, v58
	v_add_f32_e32 v60, 1.0, v60
	v_add_f32_e32 v61, 1.0, v61
	v_rcp_f32_e32 v61, v61
	v_rcp_f32_e32 v60, v60
	global_store_dwordx4 v[68:69], v[64:67], off
	v_mul_f32_e32 v61, v56, v61
	v_mul_f32_e32 v56, v62, v160
	v_mul_f32_e32 v57, v57, v160
	v_mul_f32_e32 v64, v70, v71
	v_mul_f32_e32 v58, 0xbfb8aa3b, v56
	v_exp_f32_e32 v62, v58
	v_mul_f32_e32 v58, v63, v160
	v_mul_f32_e32 v59, v59, v160
	v_mul_f32_e32 v60, v64, v60
	v_mul_f32_e32 v63, 0xbfb8aa3b, v58
	v_exp_f32_e32 v63, v63
	v_mul_f32_e32 v64, v56, v57
	v_add_f32_e32 v56, 1.0, v62
	v_rcp_f32_e32 v62, v56
	v_add_f32_e32 v56, 1.0, v63
	v_rcp_f32_e32 v63, v56
	v_mul_f32_e32 v56, v52, v160
	v_mul_f32_e32 v57, v48, v160
	v_mul_f32_e32 v58, v58, v59
	v_mul_f32_e32 v48, 0xbfb8aa3b, v56
	v_exp_f32_e32 v48, v48
	v_mul_f32_e32 v56, v56, v57
	v_mul_f32_e32 v52, v64, v62
	v_mul_f32_e32 v58, v58, v63
	v_add_f32_e32 v48, 1.0, v48
	v_rcp_f32_e32 v59, v48
	v_mul_f32_e32 v48, v53, v160
	v_mul_f32_e32 v49, v49, v160
	v_mul_f32_e32 v56, v56, v59
	v_mul_f32_e32 v53, 0xbfb8aa3b, v48
	v_exp_f32_e32 v53, v53
	v_mul_f32_e32 v57, v48, v49
	v_add_f32_e32 v48, 1.0, v53
	v_rcp_f32_e32 v53, v48
	v_mul_f32_e32 v48, v54, v160
	v_mul_f32_e32 v49, v50, v160
	v_mul_f32_e32 v53, v57, v53
	v_mul_f32_e32 v50, 0xbfb8aa3b, v48
	v_exp_f32_e32 v54, v50
	v_mul_f32_e32 v50, v55, v160
	v_mul_f32_e32 v51, v51, v160
	v_mul_f32_e32 v48, v48, v49
	v_mul_f32_e32 v55, 0xbfb8aa3b, v50
	v_exp_f32_e32 v55, v55
	v_add_f32_e32 v54, 1.0, v54
	v_rcp_f32_e32 v54, v54
	v_add_f32_e32 v55, 1.0, v55
	v_rcp_f32_e32 v55, v55
	v_mul_f32_e32 v54, v48, v54
	v_mul_f32_e32 v48, v50, v51
	v_mul_f32_e32 v51, v48, v55
	v_cvt_pk_bf16_f32 v48, v60, v61
	v_cvt_pk_bf16_f32 v49, v52, v58
; __device__ __forceinline__ unsigned cvt_pk_bf16(float lo, float hi) { unsigned r; asm volatile("v_cvt_pk_bf16_f32 %0, %1, %2" : "=v"(r) : "v"(lo), "v"(hi)); return r; }
; __device__ __forceinline__ float fast_sigmoid(float x) { return __builtin_amdgcn_rcpf(1.0f + __expf(-x)); }
; #define PG8_BAR __builtin_amdgcn_s_barrier()
;     __device__ __forceinline__ void operator()(const f32x4 (&acc)[2][2][4][2], const Unit& u, int wr, int wc, int fr, int fq) const {
;     ...
;                 const int row = u.pm * BM + ai * HALF + wr * 64 + m * 16 + fr;
;                 const float rs = rsv[ai][m];
;                 float h[8];
; #pragma unroll
;                 for (int n = 0; n < 2; ++n)
; #pragma unroll
;                     for (int i = 0; i < 4; ++i) { const float g = acc[ai][0][m][n][i] * rs, up = acc[ai][1][m][n][i] * rs; h[4 * n + i] = g * up * fast_sigmoid(g); }
;                 u32x4 w; w.x = cvt_pk_bf16(h[0], h[1]); w.y = cvt_pk_bf16(h[2], h[3]); w.z = cvt_pk_bf16(h[4], h[5]); w.w = cvt_pk_bf16(h[6], h[7]);
;                 *(u32x4*)(H + (size_t)row * 2816 + col0) = w;
; template <class Epi, class Sched, bool ALIGN_EPI = false, bool SP2 = false>
; __device__ __forceinline__ void gemm_phase(PG8_LAS unsigned char* lds, const Gemm g, const Sched& S, const Epi& E) {
;     ...
;         if (!has_next) break;
; #pragma unroll
;         for (int a = 0; a < 2; ++a)
; #pragma unroll
;             for (int b = 0; b < 2; ++b)
; #pragma unroll
;                 for (int m = 0; m < 4; ++m)
; #pragma unroll
;                     for (int n = 0; n < 2; ++n) acc[a][b][m][n] = (f32x4){0.f, 0.f, 0.f, 0.f};
;         cur = nxt; cA = nA; cB = nB; ++ui;
;         if constexpr (ALIGN_EPI) { if (wr == 1) PG8_BAR; }
	v_cvt_pk_bf16_f32 v50, v56, v53
	v_cvt_pk_bf16_f32 v51, v54, v51
	v_mul_f32_e32 v54, v44, v156
	v_mul_f32_e32 v55, v40, v156
	v_mad_i64_i32 v[52:53], s[42:43], v154, s53, v[112:113]
	v_mul_f32_e32 v40, 0xbfb8aa3b, v54
	v_exp_f32_e32 v44, v40
	v_mul_f32_e32 v40, v45, v156
	v_mul_f32_e32 v41, v41, v156
	v_lshl_add_u64 v[52:53], v[52:53], 0, v[114:115]
	v_mul_f32_e32 v45, 0xbfb8aa3b, v40
	v_exp_f32_e32 v45, v45
	v_mul_f32_e32 v40, v40, v41
	v_mov_b32_e32 v41, v42
	v_add_f32_e32 v44, 1.0, v44
	v_add_f32_e32 v45, 1.0, v45
	v_rcp_f32_e32 v45, v45
	v_rcp_f32_e32 v44, v44
	global_store_dwordx4 v[52:53], v[48:51], off
	v_mul_f32_e32 v45, v40, v45
	v_mul_f32_e32 v40, v46, v156
	v_mul_f32_e32 v41, v41, v156
	v_mul_f32_e32 v48, v54, v55
	v_mul_f32_e32 v42, 0xbfb8aa3b, v40
	v_exp_f32_e32 v46, v42
	v_mul_f32_e32 v42, v47, v156
	v_mul_f32_e32 v43, v43, v156
	v_mul_f32_e32 v44, v48, v44
	v_mul_f32_e32 v47, 0xbfb8aa3b, v42
	v_exp_f32_e32 v47, v47
	v_mul_f32_e32 v48, v40, v41
	v_add_f32_e32 v40, 1.0, v46
	v_rcp_f32_e32 v46, v40
	v_add_f32_e32 v40, 1.0, v47
	v_rcp_f32_e32 v47, v40
	v_mul_f32_e32 v40, v36, v156
	v_mul_f32_e32 v41, v32, v156
	v_mul_f32_e32 v42, v42, v43
	v_mul_f32_e32 v32, 0xbfb8aa3b, v40
	v_exp_f32_e32 v32, v32
	v_mul_f32_e32 v40, v40, v41
	v_mul_f32_e32 v36, v48, v46
	v_mul_f32_e32 v42, v42, v47
	v_add_f32_e32 v32, 1.0, v32
	v_rcp_f32_e32 v43, v32
	v_mul_f32_e32 v32, v37, v156
	v_mul_f32_e32 v33, v33, v156
	v_mul_f32_e32 v40, v40, v43
	v_mul_f32_e32 v37, 0xbfb8aa3b, v32
	v_exp_f32_e32 v37, v37
	v_mul_f32_e32 v41, v32, v33
	v_add_f32_e32 v32, 1.0, v37
	v_rcp_f32_e32 v37, v32
	v_mul_f32_e32 v32, v38, v156
	v_mul_f32_e32 v33, v34, v156
	v_mul_f32_e32 v37, v41, v37
	v_mul_f32_e32 v34, 0xbfb8aa3b, v32
	v_exp_f32_e32 v38, v34
	v_mul_f32_e32 v34, v39, v156
	v_mul_f32_e32 v35, v35, v156
	v_mul_f32_e32 v32, v32, v33
	v_mul_f32_e32 v39, 0xbfb8aa3b, v34
	v_exp_f32_e32 v39, v39
	v_add_f32_e32 v38, 1.0, v38
	v_rcp_f32_e32 v38, v38
	v_add_f32_e32 v39, 1.0, v39
	v_rcp_f32_e32 v39, v39
	v_mul_f32_e32 v38, v32, v38
	v_mul_f32_e32 v32, v34, v35
	v_mul_f32_e32 v35, v32, v39
	v_cvt_pk_bf16_f32 v32, v44, v45
	v_cvt_pk_bf16_f32 v33, v36, v42
	v_cvt_pk_bf16_f32 v34, v40, v37
	v_cvt_pk_bf16_f32 v35, v38, v35
	v_mul_f32_e32 v38, v28, v152
	v_mul_f32_e32 v39, v24, v152
	v_mad_i64_i32 v[36:37], s[42:43], v150, s53, v[112:113]
	v_mul_f32_e32 v24, 0xbfb8aa3b, v38
	v_exp_f32_e32 v28, v24
	v_mul_f32_e32 v24, v29, v152
	v_mul_f32_e32 v25, v25, v152
	v_lshl_add_u64 v[36:37], v[36:37], 0, v[114:115]
	v_mul_f32_e32 v29, 0xbfb8aa3b, v24
	v_exp_f32_e32 v29, v29
	v_mul_f32_e32 v24, v24, v25
	v_mov_b32_e32 v25, v26
	v_add_f32_e32 v28, 1.0, v28
	v_add_f32_e32 v29, 1.0, v29
	v_rcp_f32_e32 v29, v29
	v_rcp_f32_e32 v28, v28
	global_store_dwordx4 v[36:37], v[32:35], off
	v_mul_f32_e32 v29, v24, v29
	v_mul_f32_e32 v24, v30, v152
	v_mul_f32_e32 v25, v25, v152
	v_mul_f32_e32 v32, v38, v39
	v_mul_f32_e32 v26, 0xbfb8aa3b, v24
	v_exp_f32_e32 v30, v26
	v_mul_f32_e32 v26, v31, v152
	v_mul_f32_e32 v27, v27, v152
	v_mul_f32_e32 v28, v32, v28
	v_mul_f32_e32 v31, 0xbfb8aa3b, v26
	v_exp_f32_e32 v31, v31
	v_mul_f32_e32 v32, v24, v25
	v_add_f32_e32 v24, 1.0, v30
	v_rcp_f32_e32 v30, v24
	v_add_f32_e32 v24, 1.0, v31
	v_rcp_f32_e32 v31, v24
	v_mul_f32_e32 v24, v20, v152
	v_mul_f32_e32 v25, v16, v152
	v_mul_f32_e32 v26, v26, v27
	v_mul_f32_e32 v16, 0xbfb8aa3b, v24
	v_exp_f32_e32 v16, v16
	v_mul_f32_e32 v24, v24, v25
	v_mul_f32_e32 v20, v32, v30
	v_mul_f32_e32 v26, v26, v31
	v_add_f32_e32 v16, 1.0, v16
	v_rcp_f32_e32 v27, v16
	v_mul_f32_e32 v16, v21, v152
	v_mul_f32_e32 v17, v17, v152
	v_mul_f32_e32 v24, v24, v27
	v_mul_f32_e32 v21, 0xbfb8aa3b, v16
	v_exp_f32_e32 v21, v21
	v_mul_f32_e32 v25, v16, v17
	v_add_f32_e32 v16, 1.0, v21
	v_rcp_f32_e32 v21, v16
	v_mul_f32_e32 v16, v22, v152
	v_mul_f32_e32 v17, v18, v152
	v_mul_f32_e32 v21, v25, v21
	v_mul_f32_e32 v18, 0xbfb8aa3b, v16
	v_exp_f32_e32 v22, v18
	v_mul_f32_e32 v18, v23, v152
	v_mul_f32_e32 v19, v19, v152
	v_mul_f32_e32 v16, v16, v17
	v_mul_f32_e32 v23, 0xbfb8aa3b, v18
	v_exp_f32_e32 v23, v23
	v_add_f32_e32 v22, 1.0, v22
	v_rcp_f32_e32 v22, v22
	v_add_f32_e32 v23, 1.0, v23
	v_rcp_f32_e32 v23, v23
	v_mul_f32_e32 v22, v16, v22
	v_mul_f32_e32 v16, v18, v19
	v_mul_f32_e32 v19, v16, v23
	v_cvt_pk_bf16_f32 v16, v28, v29
	v_cvt_pk_bf16_f32 v17, v20, v26
	v_cvt_pk_bf16_f32 v18, v24, v21
	v_cvt_pk_bf16_f32 v19, v22, v19
	v_mul_f32_e32 v22, v12, v148
	v_mul_f32_e32 v23, v8, v148
	v_mad_i64_i32 v[20:21], s[42:43], v146, s53, v[112:113]
	v_mul_f32_e32 v8, 0xbfb8aa3b, v22
	v_exp_f32_e32 v12, v8
	v_mul_f32_e32 v8, v13, v148
	v_mul_f32_e32 v9, v9, v148
	v_lshl_add_u64 v[20:21], v[20:21], 0, v[114:115]
	v_mul_f32_e32 v13, 0xbfb8aa3b, v8
	v_exp_f32_e32 v13, v13
	v_mul_f32_e32 v8, v8, v9
	v_mov_b32_e32 v9, v10
	v_add_f32_e32 v12, 1.0, v12
	v_add_f32_e32 v13, 1.0, v13
	v_rcp_f32_e32 v13, v13
	v_rcp_f32_e32 v12, v12
	global_store_dwordx4 v[20:21], v[16:19], off
	v_mul_f32_e32 v13, v8, v13
	v_mul_f32_e32 v8, v14, v148
	v_mul_f32_e32 v9, v9, v148
	v_mul_f32_e32 v16, v22, v23
	v_mul_f32_e32 v10, 0xbfb8aa3b, v8
	v_exp_f32_e32 v14, v10
	v_mul_f32_e32 v10, v15, v148
	v_mul_f32_e32 v11, v11, v148
	v_mul_f32_e32 v12, v16, v12
	v_mul_f32_e32 v15, 0xbfb8aa3b, v10
	v_exp_f32_e32 v15, v15
	v_mul_f32_e32 v16, v8, v9
	v_add_f32_e32 v8, 1.0, v14
	v_rcp_f32_e32 v14, v8
	v_add_f32_e32 v8, 1.0, v15
	v_rcp_f32_e32 v15, v8
	v_mul_f32_e32 v8, v4, v148
	v_mul_f32_e32 v9, v0, v148
	v_mul_f32_e32 v10, v10, v11
	v_mul_f32_e32 v0, 0xbfb8aa3b, v8
	v_exp_f32_e32 v0, v0
	v_mul_f32_e32 v8, v8, v9
	v_mul_f32_e32 v4, v16, v14
	v_mul_f32_e32 v10, v10, v15
	v_add_f32_e32 v0, 1.0, v0
	v_rcp_f32_e32 v11, v0
	v_mul_f32_e32 v0, v5, v148
	v_mul_f32_e32 v1, v1, v148
	v_mul_f32_e32 v8, v8, v11
	v_mul_f32_e32 v5, 0xbfb8aa3b, v0
	v_exp_f32_e32 v5, v5
	v_mul_f32_e32 v9, v0, v1
	v_add_f32_e32 v0, 1.0, v5
	v_rcp_f32_e32 v5, v0
	v_mul_f32_e32 v0, v6, v148
	v_mul_f32_e32 v1, v2, v148
	v_mul_f32_e32 v5, v9, v5
	v_mul_f32_e32 v2, 0xbfb8aa3b, v0
	v_exp_f32_e32 v6, v2
	v_mul_f32_e32 v2, v7, v148
	v_mul_f32_e32 v3, v3, v148
	v_mul_f32_e32 v0, v0, v1
	v_mul_f32_e32 v7, 0xbfb8aa3b, v2
	v_exp_f32_e32 v7, v7
	v_add_f32_e32 v6, 1.0, v6
	v_rcp_f32_e32 v6, v6
	v_add_f32_e32 v7, 1.0, v7
	v_rcp_f32_e32 v7, v7
	v_mul_f32_e32 v6, v0, v6
	v_mul_f32_e32 v0, v2, v3
	v_mul_f32_e32 v3, v0, v7
	v_cvt_pk_bf16_f32 v0, v12, v13
	v_cvt_pk_bf16_f32 v1, v4, v10
	v_cvt_pk_bf16_f32 v2, v8, v5
	v_mad_i64_i32 v[4:5], s[42:43], v144, s53, v[112:113]
	v_lshl_add_u64 v[4:5], v[4:5], 0, v[114:115]
	v_cvt_pk_bf16_f32 v3, v6, v3
	global_store_dwordx4 v[4:5], v[0:3], off
	s_cbranch_vccnz .LBB0_477
	s_andn2_b64 vcc, exec, s[4:5]
	s_cbranch_vccnz .LBB0_476
	s_barrier
	s_branch .LBB0_476

; __device__ __forceinline__ unsigned cvt_pk_bf16(float lo, float hi) { unsigned r; asm volatile("v_cvt_pk_bf16_f32 %0, %1, %2" : "=v"(r) : "v"(lo), "v"(hi)); return r; }
; __device__ __forceinline__ float bf_lo(unsigned w) { return __uint_as_float(w << 16); }
; __device__ __forceinline__ float bf_hi(unsigned w) { return __uint_as_float(w & 0xffff0000u); }
;     __device__ __forceinline__ void operator()(const f32x4 (&acc)[2][2][4][2], const Unit& u, int wr, int wc, int fr, int fq) const {
;     ...
;                 for (int bj = 0; bj < 2; ++bj) xin[ai][m][bj] = *(const u32x4*)(X + (size_t)(u.pm * BM + ai * HALF + wr * 64 + m * 16 + fr) * 1024 + col0 + bj * HALF);
; #pragma unroll
;         for (int ai = 0; ai < 2; ++ai)
; #pragma unroll
;             for (int m = 0; m < 4; ++m) {
;                 const int row = u.pm * BM + ai * HALF + wr * 64 + m * 16 + fr;
;                 float ss = 0.f;
; #pragma unroll
;                 for (int bj = 0; bj < 2; ++bj) {
;                     bf16_t* xp = X + (size_t)row * 1024 + col0 + bj * HALF;
;                     const u32x4 xv = xin[ai][m][bj];
;                     f32x4 y0 = acc[ai][bj][m][0], y1 = acc[ai][bj][m][1];
;                     y0[0] += bf_lo(xv.x); y0[1] += bf_hi(xv.x); y0[2] += bf_lo(xv.y); y0[3] += bf_hi(xv.y);
;                     y1[0] += bf_lo(xv.z); y1[1] += bf_hi(xv.z); y1[2] += bf_lo(xv.w); y1[3] += bf_hi(xv.w);
;                     if (FINAL) {
;                         float* op = out + (size_t)row * 1024 + col0 + bj * HALF;
;                         __builtin_nontemporal_store(y0, (f32x4*)op); __builtin_nontemporal_store(y1, (f32x4*)(op + 4));
;                     } else {
;                         u32x4 w; w.x = cvt_pk_bf16(y0[0], y0[1]); w.y = cvt_pk_bf16(y0[2], y0[3]); w.z = cvt_pk_bf16(y1[0], y1[1]); w.w = cvt_pk_bf16(y1[2], y1[3]);
;                         *(u32x4*)xp = w;
;                         ss += (y0[0] * y0[0] + y0[1] * y0[1]) + (y0[2] * y0[2] + y0[3] * y0[3]) + (y1[0] * y1[0] + y1[1] * y1[1]) + (y1[2] * y1[2] + y1[3] * y1[3]);
;                     }
;                 }
;                 if (!FINAL) {
;                     ss += __shfl_xor(ss, 16); ss += __shfl_xor(ss, 32);
;                     if (fq == 0) ssq[(size_t)row * 16 + u.pn * 4 + wc] = ss;
.LBB0_573:
	v_lshl_or_b32 v200, s16, 8, v233
	v_lshl_add_u32 v226, s55, 8, v231
	v_ashrrev_i32_e32 v201, 31, v200
	v_lshlrev_b64 v[246:247], 1, v[200:201]
	v_ashrrev_i32_e32 v227, 31, v226
	v_lshl_add_u64 v[124:125], s[70:71], 0, v[246:247]
	v_lshlrev_b64 v[126:127], 11, v[226:227]
	v_lshl_add_u64 v[132:133], v[124:125], 0, v[126:127]
	global_load_dwordx4 v[238:241], v[132:133], off
	global_load_dwordx4 v[242:245], v[132:133], off offset:256
	v_or_b32_e32 v222, 16, v226
	v_or_b32_e32 v218, 32, v226
	v_or_b32_e32 v214, 48, v226
	v_add_u32_e32 v210, 0x80, v226
	v_add_u32_e32 v206, 0x90, v226
	v_add_u32_e32 v202, 0xa0, v226
	v_add_u32_e32 v198, 0xb0, v226
	v_ashrrev_i32_e32 v223, 31, v222
	v_ashrrev_i32_e32 v219, 31, v218
	v_ashrrev_i32_e32 v215, 31, v214
	v_ashrrev_i32_e32 v211, 31, v210
	v_ashrrev_i32_e32 v207, 31, v206
	v_ashrrev_i32_e32 v203, 31, v202
	v_ashrrev_i32_e32 v199, 31, v198
	v_lshlrev_b64 v[228:229], 11, v[222:223]
	v_lshlrev_b64 v[224:225], 11, v[218:219]
	v_lshlrev_b64 v[220:221], 11, v[214:215]
	v_lshlrev_b64 v[216:217], 11, v[210:211]
	v_lshlrev_b64 v[212:213], 11, v[206:207]
	v_lshlrev_b64 v[208:209], 11, v[202:203]
	v_lshlrev_b64 v[204:205], 11, v[198:199]
	v_lshl_add_u64 v[248:249], s[70:71], 0, v[126:127]
	v_lshl_add_u64 v[126:127], v[124:125], 0, v[228:229]
	v_lshl_add_u64 v[132:133], v[124:125], 0, v[224:225]
	v_lshl_add_u64 v[134:135], v[124:125], 0, v[220:221]
	v_lshl_add_u64 v[136:137], v[124:125], 0, v[216:217]
	v_lshl_add_u64 v[138:139], v[124:125], 0, v[212:213]
	v_lshl_add_u64 v[250:251], v[124:125], 0, v[208:209]
	v_lshl_add_u64 v[124:125], v[124:125], 0, v[204:205]
	global_load_dwordx4 v[180:183], v[126:127], off
	global_load_dwordx4 v[176:179], v[126:127], off offset:256
	global_load_dwordx4 v[172:175], v[132:133], off
	global_load_dwordx4 v[168:171], v[132:133], off offset:256
	global_load_dwordx4 v[164:167], v[134:135], off
	global_load_dwordx4 v[160:163], v[134:135], off offset:256
	global_load_dwordx4 v[156:159], v[136:137], off
	global_load_dwordx4 v[152:155], v[136:137], off offset:256
	global_load_dwordx4 v[148:151], v[138:139], off
	global_load_dwordx4 v[144:147], v[138:139], off offset:256
	global_load_dwordx4 v[140:143], v[250:251], off
	s_nop 0
	global_load_dwordx4 v[136:139], v[250:251], off offset:256
	global_load_dwordx4 v[132:135], v[124:125], off
	s_nop 0
	global_load_dwordx4 v[124:127], v[124:125], off offset:256
	v_lshl_add_u64 v[246:247], v[248:249], 0, v[246:247]
	s_lshl_b32 s42, s16, 2
	s_ashr_i32 s43, s42, 31
	s_waitcnt vmcnt(14)
	v_lshlrev_b32_e32 v248, 16, v238
	v_and_b32_e32 v238, 0xffff0000, v238
	v_lshlrev_b32_e32 v249, 16, v239
	v_and_b32_e32 v239, 0xffff0000, v239
	v_lshlrev_b32_e32 v250, 16, v240
	v_and_b32_e32 v240, 0xffff0000, v240
	v_lshlrev_b32_e32 v252, 16, v242
	v_lshlrev_b32_e32 v253, 16, v243
	v_add_f32_e32 v129, v129, v238
	v_add_f32_e32 v131, v131, v239
	v_and_b32_e32 v243, 0xffff0000, v243
	v_add_f32_e32 v128, v128, v248
	v_add_f32_e32 v130, v130, v249
	v_add_f32_e32 v121, v121, v240
	v_add_f32_e32 v238, v116, v252
	v_add_f32_e32 v240, v118, v253
	v_cvt_pk_bf16_f32 v116, v128, v129
	v_mul_f32_e32 v118, v129, v129
	v_mul_f32_e32 v129, v131, v131
	v_lshlrev_b32_e32 v251, 16, v241
	v_and_b32_e32 v241, 0xffff0000, v241
	v_and_b32_e32 v242, 0xffff0000, v242
	v_fmac_f32_e32 v118, v128, v128
	v_fmac_f32_e32 v129, v130, v130
	v_add_f32_e32 v128, v119, v243
	v_lshlrev_b32_e32 v119, 16, v244
	v_add_f32_e32 v120, v120, v250
	v_add_f32_e32 v123, v123, v241
	v_add_f32_e32 v239, v117, v242
	v_cvt_pk_bf16_f32 v117, v130, v131
	v_mul_f32_e32 v131, v121, v121
	v_add_f32_e32 v118, v118, v129
	v_add_f32_e32 v129, v112, v119
	v_and_b32_e32 v112, 0xffff0000, v244
	v_add_f32_e32 v122, v122, v251
	v_mul_f32_e32 v241, v123, v123
	v_fmac_f32_e32 v131, v120, v120
	v_add_f32_e32 v130, v113, v112
	v_lshlrev_b32_e32 v112, 16, v245
	v_fmac_f32_e32 v241, v122, v122
	v_add_f32_e32 v118, v131, v118
	v_add_f32_e32 v131, v114, v112
	v_and_b32_e32 v112, 0xffff0000, v245
	v_add_f32_e32 v118, v241, v118
	v_add_f32_e32 v241, v115, v112
	v_mul_f32_e32 v112, v239, v239
	v_mul_f32_e32 v113, v128, v128
	v_fmac_f32_e32 v112, v238, v238
	v_fmac_f32_e32 v113, v240, v240
	v_add_f32_e32 v112, v112, v113
	v_mul_f32_e32 v113, v130, v130
	v_fmac_f32_e32 v113, v129, v129
	v_add_f32_e32 v112, v113, v112
	v_mul_f32_e32 v113, v241, v241
	v_fmac_f32_e32 v113, v131, v131
	v_add_f32_e32 v112, v113, v112
	v_and_b32_e32 v114, 64, v237
	v_add_f32_e32 v113, v118, v112
	v_xor_b32_e32 v112, 16, v237
	v_add_u32_e32 v115, 64, v114
	v_cmp_lt_i32_e32 vcc, v112, v115
	v_cvt_pk_bf16_f32 v118, v120, v121
	v_cvt_pk_bf16_f32 v119, v122, v123
	global_store_dwordx4 v[246:247], v[116:119], off
	s_nop 0
	v_cndmask_b32_e32 v112, v237, v112, vcc
	v_lshlrev_b32_e32 v112, 2, v112
	v_mov_b32_e32 v114, v113
	s_nop 1
	v_permlane16_swap_b32_e32 v113, v114
	v_cvt_pk_bf16_f32 v116, v238, v239
	v_cvt_pk_bf16_f32 v117, v240, v128
	v_cvt_pk_bf16_f32 v118, v129, v130
	v_cvt_pk_bf16_f32 v119, v131, v241
	s_waitcnt lgkmcnt(0)
	v_add_f32_e32 v114, v113, v114
	v_xor_b32_e32 v113, 32, v237
	v_cmp_lt_i32_e32 vcc, v113, v115
	global_store_dwordx4 v[246:247], v[116:119], off offset:256
	s_nop 0
	v_cndmask_b32_e32 v113, v237, v113, vcc
	v_lshlrev_b32_e32 v113, 2, v113
	v_mov_b32_e32 v115, v114
	s_nop 1
	v_permlane32_swap_b32_e32 v114, v115
	s_and_saveexec_b64 s[44:45], s[0:1]
	s_cbranch_execz .LBB0_575
	s_waitcnt lgkmcnt(0)
	v_add_f32_e32 v116, v114, v115
	v_lshlrev_b64 v[114:115], 6, v[226:227]
	v_lshl_add_u64 v[114:115], s[34:35], 0, v[114:115]
	v_lshl_add_u64 v[114:115], s[42:43], 2, v[114:115]
	s_lshl_b32 s16, s30, 2
	v_lshl_add_u64 v[114:115], v[114:115], 0, s[16:17]
	global_store_dword v[114:115], v116, off
; __device__ __forceinline__ unsigned cvt_pk_bf16(float lo, float hi) { unsigned r; asm volatile("v_cvt_pk_bf16_f32 %0, %1, %2" : "=v"(r) : "v"(lo), "v"(hi)); return r; }
; __device__ __forceinline__ float bf_lo(unsigned w) { return __uint_as_float(w << 16); }
; __device__ __forceinline__ float bf_hi(unsigned w) { return __uint_as_float(w & 0xffff0000u); }
;     __device__ __forceinline__ void operator()(const f32x4 (&acc)[2][2][4][2], const Unit& u, int wr, int wc, int fr, int fq) const {
;     ...
;         for (int ai = 0; ai < 2; ++ai)
; #pragma unroll
;             for (int m = 0; m < 4; ++m) {
;                 const int row = u.pm * BM + ai * HALF + wr * 64 + m * 16 + fr;
;                 float ss = 0.f;
; #pragma unroll
;                 for (int bj = 0; bj < 2; ++bj) {
;                     bf16_t* xp = X + (size_t)row * 1024 + col0 + bj * HALF;
;                     const u32x4 xv = xin[ai][m][bj];
;                     f32x4 y0 = acc[ai][bj][m][0], y1 = acc[ai][bj][m][1];
;                     y0[0] += bf_lo(xv.x); y0[1] += bf_hi(xv.x); y0[2] += bf_lo(xv.y); y0[3] += bf_hi(xv.y);
;                     y1[0] += bf_lo(xv.z); y1[1] += bf_hi(xv.z); y1[2] += bf_lo(xv.w); y1[3] += bf_hi(xv.w);
;                     if (FINAL) {
;                         float* op = out + (size_t)row * 1024 + col0 + bj * HALF;
;                         __builtin_nontemporal_store(y0, (f32x4*)op); __builtin_nontemporal_store(y1, (f32x4*)(op + 4));
;                     } else {
;                         u32x4 w; w.x = cvt_pk_bf16(y0[0], y0[1]); w.y = cvt_pk_bf16(y0[2], y0[3]); w.z = cvt_pk_bf16(y1[0], y1[1]); w.w = cvt_pk_bf16(y1[2], y1[3]);
;                         *(u32x4*)xp = w;
;                         ss += (y0[0] * y0[0] + y0[1] * y0[1]) + (y0[2] * y0[2] + y0[3] * y0[3]) + (y1[0] * y1[0] + y1[1] * y1[1]) + (y1[2] * y1[2] + y1[3] * y1[3]);
;                     }
;                 }
;                 if (!FINAL) {
;                     ss += __shfl_xor(ss, 16); ss += __shfl_xor(ss, 32);
;                     if (fq == 0) ssq[(size_t)row * 16 + u.pn * 4 + wc] = ss;
;                 }
.LBB0_575:
	s_or_b64 exec, exec, s[44:45]
	s_waitcnt vmcnt(14)
	v_lshlrev_b32_e32 v116, 16, v180
	v_add_f32_e32 v108, v108, v116
	v_and_b32_e32 v116, 0xffff0000, v180
	v_add_f32_e32 v109, v109, v116
	v_lshlrev_b32_e32 v116, 16, v181
	v_add_f32_e32 v110, v110, v116
	v_and_b32_e32 v116, 0xffff0000, v181
	v_add_f32_e32 v111, v111, v116
	v_lshlrev_b32_e32 v116, 16, v182
	v_add_f32_e32 v116, v104, v116
	v_and_b32_e32 v104, 0xffff0000, v182
	v_add_f32_e32 v117, v105, v104
	v_lshlrev_b32_e32 v104, 16, v183
	v_add_f32_e32 v118, v106, v104
	v_and_b32_e32 v104, 0xffff0000, v183
	v_mul_f32_e32 v106, v109, v109
	v_add_f32_e32 v107, v107, v104
	v_cvt_pk_bf16_f32 v104, v108, v109
	v_fmac_f32_e32 v106, v108, v108
	v_mul_f32_e32 v108, v111, v111
	v_fmac_f32_e32 v108, v110, v110
	v_add_f32_e32 v106, v106, v108
	v_mul_f32_e32 v108, v117, v117
	v_fmac_f32_e32 v108, v116, v116
	v_add_f32_e32 v106, v108, v106
	v_mul_f32_e32 v108, v107, v107
	v_fmac_f32_e32 v108, v118, v118
	v_add_f32_e32 v106, v108, v106
	v_lshlrev_b32_e32 v108, 16, v176
	v_add_f32_e32 v100, v100, v108
	v_and_b32_e32 v108, 0xffff0000, v176
	v_add_f32_e32 v101, v101, v108
	v_lshlrev_b32_e32 v108, 16, v177
	v_add_f32_e32 v102, v102, v108
	v_and_b32_e32 v108, 0xffff0000, v177
	v_add_f32_e32 v103, v103, v108
	v_lshlrev_b32_e32 v108, 16, v178
	v_add_f32_e32 v108, v96, v108
	v_and_b32_e32 v96, 0xffff0000, v178
	v_add_f32_e32 v109, v97, v96
	v_lshlrev_b32_e32 v96, 16, v179
	v_cvt_pk_bf16_f32 v105, v110, v111
	v_add_f32_e32 v110, v98, v96
	v_and_b32_e32 v96, 0xffff0000, v179
	v_add_f32_e32 v111, v99, v96
	v_mul_f32_e32 v96, v101, v101
	v_mul_f32_e32 v97, v103, v103
	v_fmac_f32_e32 v96, v100, v100
	v_fmac_f32_e32 v97, v102, v102
	v_add_f32_e32 v96, v96, v97
	v_mul_f32_e32 v97, v109, v109
	v_fmac_f32_e32 v97, v108, v108
	v_add_f32_e32 v96, v97, v96
	v_mul_f32_e32 v97, v111, v111
	v_fmac_f32_e32 v97, v110, v110
	v_add_f32_e32 v96, v97, v96
	v_add_f32_e32 v96, v106, v96
	v_mov_b32_e32 v97, v96
	s_nop 1
	v_permlane16_swap_b32_e32 v96, v97
	s_waitcnt lgkmcnt(1)
	v_lshl_add_u64 v[114:115], s[70:71], 0, v[228:229]
	v_lshl_add_u64 v[114:115], v[200:201], 1, v[114:115]
	v_cvt_pk_bf16_f32 v106, v116, v117
	v_cvt_pk_bf16_f32 v107, v118, v107
	s_waitcnt lgkmcnt(0)
	v_add_f32_e32 v96, v96, v97
	v_mov_b32_e32 v97, v96
	s_nop 1
	v_permlane32_swap_b32_e32 v96, v97
	global_store_dwordx4 v[114:115], v[104:107], off
	v_cvt_pk_bf16_f32 v98, v100, v101
	v_cvt_pk_bf16_f32 v99, v102, v103
	v_cvt_pk_bf16_f32 v100, v108, v109
	v_cvt_pk_bf16_f32 v101, v110, v111
	global_store_dwordx4 v[114:115], v[98:101], off offset:256
	s_and_saveexec_b64 s[44:45], s[0:1]
	s_cbranch_execz .LBB0_577
	s_waitcnt lgkmcnt(0)
	v_add_f32_e32 v98, v96, v97
	v_lshlrev_b64 v[96:97], 6, v[222:223]
	v_lshl_add_u64 v[96:97], s[34:35], 0, v[96:97]
	v_lshl_add_u64 v[96:97], s[42:43], 2, v[96:97]
	s_lshl_b32 s16, s30, 2
	v_lshl_add_u64 v[96:97], v[96:97], 0, s[16:17]
	global_store_dword v[96:97], v98, off
.LBB0_577:
	s_or_b64 exec, exec, s[44:45]
	s_waitcnt vmcnt(14)
	v_lshlrev_b32_e32 v98, 16, v172
	v_add_f32_e32 v92, v92, v98
	v_and_b32_e32 v98, 0xffff0000, v172
	v_add_f32_e32 v93, v93, v98
	v_lshlrev_b32_e32 v98, 16, v173
	v_add_f32_e32 v94, v94, v98
	v_and_b32_e32 v98, 0xffff0000, v173
	v_add_f32_e32 v95, v95, v98
	v_lshlrev_b32_e32 v98, 16, v174
	v_add_f32_e32 v98, v88, v98
	v_and_b32_e32 v88, 0xffff0000, v174
	v_add_f32_e32 v99, v89, v88
	v_lshlrev_b32_e32 v88, 16, v175
	v_add_f32_e32 v100, v90, v88
	v_and_b32_e32 v88, 0xffff0000, v175
	v_mul_f32_e32 v90, v93, v93
	v_add_f32_e32 v91, v91, v88
	v_cvt_pk_bf16_f32 v88, v92, v93
	v_fmac_f32_e32 v90, v92, v92
	v_mul_f32_e32 v92, v95, v95
	v_fmac_f32_e32 v92, v94, v94
	v_add_f32_e32 v90, v90, v92
	v_mul_f32_e32 v92, v99, v99
	v_fmac_f32_e32 v92, v98, v98
	v_add_f32_e32 v90, v92, v90
	v_mul_f32_e32 v92, v91, v91
	v_fmac_f32_e32 v92, v100, v100
	v_add_f32_e32 v90, v92, v90
	v_lshlrev_b32_e32 v92, 16, v168
	v_add_f32_e32 v84, v84, v92
	v_and_b32_e32 v92, 0xffff0000, v168
	v_add_f32_e32 v85, v85, v92
	v_lshlrev_b32_e32 v92, 16, v169
	v_add_f32_e32 v86, v86, v92
	v_and_b32_e32 v92, 0xffff0000, v169
	v_add_f32_e32 v87, v87, v92
	v_lshlrev_b32_e32 v92, 16, v170
	v_add_f32_e32 v92, v80, v92
	v_and_b32_e32 v80, 0xffff0000, v170
	v_add_f32_e32 v93, v81, v80
	v_lshlrev_b32_e32 v80, 16, v171
	v_cvt_pk_bf16_f32 v89, v94, v95
	v_add_f32_e32 v94, v82, v80
	v_and_b32_e32 v80, 0xffff0000, v171
	v_add_f32_e32 v95, v83, v80
	v_mul_f32_e32 v80, v85, v85
	v_mul_f32_e32 v81, v87, v87
	v_fmac_f32_e32 v80, v84, v84
	v_fmac_f32_e32 v81, v86, v86
	v_add_f32_e32 v80, v80, v81
	v_mul_f32_e32 v81, v93, v93
	v_fmac_f32_e32 v81, v92, v92
	v_add_f32_e32 v80, v81, v80
	v_mul_f32_e32 v81, v95, v95
	v_fmac_f32_e32 v81, v94, v94
	v_add_f32_e32 v80, v81, v80
	v_add_f32_e32 v80, v90, v80
	v_mov_b32_e32 v81, v80
	s_nop 1
	v_permlane16_swap_b32_e32 v80, v81
	s_waitcnt lgkmcnt(1)
	v_lshl_add_u64 v[96:97], s[70:71], 0, v[224:225]
	v_lshl_add_u64 v[96:97], v[200:201], 1, v[96:97]
	v_cvt_pk_bf16_f32 v90, v98, v99
	v_cvt_pk_bf16_f32 v91, v100, v91
	s_waitcnt lgkmcnt(0)
	v_add_f32_e32 v80, v80, v81
	v_mov_b32_e32 v81, v80
	s_nop 1
	v_permlane32_swap_b32_e32 v80, v81
	global_store_dwordx4 v[96:97], v[88:91], off
	v_cvt_pk_bf16_f32 v82, v84, v85
	v_cvt_pk_bf16_f32 v83, v86, v87
	v_cvt_pk_bf16_f32 v84, v92, v93
	v_cvt_pk_bf16_f32 v85, v94, v95
	global_store_dwordx4 v[96:97], v[82:85], off offset:256
	s_and_saveexec_b64 s[44:45], s[0:1]
	s_cbranch_execz .LBB0_579
	s_waitcnt lgkmcnt(0)
	v_add_f32_e32 v82, v80, v81
	v_lshlrev_b64 v[80:81], 6, v[218:219]
	v_lshl_add_u64 v[80:81], s[34:35], 0, v[80:81]
	v_lshl_add_u64 v[80:81], s[42:43], 2, v[80:81]
	s_lshl_b32 s16, s30, 2
	v_lshl_add_u64 v[80:81], v[80:81], 0, s[16:17]
	global_store_dword v[80:81], v82, off
; __device__ __forceinline__ unsigned cvt_pk_bf16(float lo, float hi) { unsigned r; asm volatile("v_cvt_pk_bf16_f32 %0, %1, %2" : "=v"(r) : "v"(lo), "v"(hi)); return r; }
; __device__ __forceinline__ float bf_lo(unsigned w) { return __uint_as_float(w << 16); }
; __device__ __forceinline__ float bf_hi(unsigned w) { return __uint_as_float(w & 0xffff0000u); }
;     __device__ __forceinline__ void operator()(const f32x4 (&acc)[2][2][4][2], const Unit& u, int wr, int wc, int fr, int fq) const {
;     ...
;         for (int ai = 0; ai < 2; ++ai)
; #pragma unroll
;             for (int m = 0; m < 4; ++m) {
;                 const int row = u.pm * BM + ai * HALF + wr * 64 + m * 16 + fr;
;                 float ss = 0.f;
; #pragma unroll
;                 for (int bj = 0; bj < 2; ++bj) {
;                     bf16_t* xp = X + (size_t)row * 1024 + col0 + bj * HALF;
;                     const u32x4 xv = xin[ai][m][bj];
;                     f32x4 y0 = acc[ai][bj][m][0], y1 = acc[ai][bj][m][1];
;                     y0[0] += bf_lo(xv.x); y0[1] += bf_hi(xv.x); y0[2] += bf_lo(xv.y); y0[3] += bf_hi(xv.y);
;                     y1[0] += bf_lo(xv.z); y1[1] += bf_hi(xv.z); y1[2] += bf_lo(xv.w); y1[3] += bf_hi(xv.w);
;                     if (FINAL) {
;                         float* op = out + (size_t)row * 1024 + col0 + bj * HALF;
;                         __builtin_nontemporal_store(y0, (f32x4*)op); __builtin_nontemporal_store(y1, (f32x4*)(op + 4));
;                     } else {
;                         u32x4 w; w.x = cvt_pk_bf16(y0[0], y0[1]); w.y = cvt_pk_bf16(y0[2], y0[3]); w.z = cvt_pk_bf16(y1[0], y1[1]); w.w = cvt_pk_bf16(y1[2], y1[3]);
;                         *(u32x4*)xp = w;
;                         ss += (y0[0] * y0[0] + y0[1] * y0[1]) + (y0[2] * y0[2] + y0[3] * y0[3]) + (y1[0] * y1[0] + y1[1] * y1[1]) + (y1[2] * y1[2] + y1[3] * y1[3]);
;                     }
;                 }
;                 if (!FINAL) {
;                     ss += __shfl_xor(ss, 16); ss += __shfl_xor(ss, 32);
;                     if (fq == 0) ssq[(size_t)row * 16 + u.pn * 4 + wc] = ss;
;                 }
.LBB0_579:
	s_or_b64 exec, exec, s[44:45]
	s_waitcnt vmcnt(14)
	v_lshlrev_b32_e32 v82, 16, v164
	v_add_f32_e32 v76, v76, v82
	v_and_b32_e32 v82, 0xffff0000, v164
	v_add_f32_e32 v77, v77, v82
	v_lshlrev_b32_e32 v82, 16, v165
	v_add_f32_e32 v78, v78, v82
	v_and_b32_e32 v82, 0xffff0000, v165
	v_add_f32_e32 v79, v79, v82
	v_lshlrev_b32_e32 v82, 16, v166
	v_add_f32_e32 v82, v72, v82
	v_and_b32_e32 v72, 0xffff0000, v166
	v_add_f32_e32 v83, v73, v72
	v_lshlrev_b32_e32 v72, 16, v167
	v_add_f32_e32 v84, v74, v72
	v_and_b32_e32 v72, 0xffff0000, v167
	v_mul_f32_e32 v74, v77, v77
	v_add_f32_e32 v75, v75, v72
	v_cvt_pk_bf16_f32 v72, v76, v77
	v_fmac_f32_e32 v74, v76, v76
	v_mul_f32_e32 v76, v79, v79
	v_fmac_f32_e32 v76, v78, v78
	v_add_f32_e32 v74, v74, v76
	v_mul_f32_e32 v76, v83, v83
	v_fmac_f32_e32 v76, v82, v82
	v_add_f32_e32 v74, v76, v74
	v_mul_f32_e32 v76, v75, v75
	v_fmac_f32_e32 v76, v84, v84
	v_add_f32_e32 v74, v76, v74
	v_lshlrev_b32_e32 v76, 16, v160
	v_add_f32_e32 v68, v68, v76
	v_and_b32_e32 v76, 0xffff0000, v160
	v_add_f32_e32 v69, v69, v76
	v_lshlrev_b32_e32 v76, 16, v161
	v_add_f32_e32 v70, v70, v76
	v_and_b32_e32 v76, 0xffff0000, v161
	v_add_f32_e32 v71, v71, v76
	v_lshlrev_b32_e32 v76, 16, v162
	v_add_f32_e32 v76, v64, v76
	v_and_b32_e32 v64, 0xffff0000, v162
	v_add_f32_e32 v77, v65, v64
	v_lshlrev_b32_e32 v64, 16, v163
	v_cvt_pk_bf16_f32 v73, v78, v79
	v_add_f32_e32 v78, v66, v64
	v_and_b32_e32 v64, 0xffff0000, v163
	v_add_f32_e32 v79, v67, v64
	v_mul_f32_e32 v64, v69, v69
	v_mul_f32_e32 v65, v71, v71
	v_fmac_f32_e32 v64, v68, v68
	v_fmac_f32_e32 v65, v70, v70
	v_add_f32_e32 v64, v64, v65
	v_mul_f32_e32 v65, v77, v77
	v_fmac_f32_e32 v65, v76, v76
	v_add_f32_e32 v64, v65, v64
	v_mul_f32_e32 v65, v79, v79
	v_fmac_f32_e32 v65, v78, v78
	v_add_f32_e32 v64, v65, v64
	v_add_f32_e32 v64, v74, v64
	v_mov_b32_e32 v65, v64
	s_nop 1
	v_permlane16_swap_b32_e32 v64, v65
	s_waitcnt lgkmcnt(1)
	v_lshl_add_u64 v[80:81], s[70:71], 0, v[220:221]
	v_lshl_add_u64 v[80:81], v[200:201], 1, v[80:81]
	v_cvt_pk_bf16_f32 v74, v82, v83
	v_cvt_pk_bf16_f32 v75, v84, v75
	s_waitcnt lgkmcnt(0)
	v_add_f32_e32 v64, v64, v65
	v_mov_b32_e32 v65, v64
	s_nop 1
	v_permlane32_swap_b32_e32 v64, v65
	global_store_dwordx4 v[80:81], v[72:75], off
	v_cvt_pk_bf16_f32 v66, v68, v69
	v_cvt_pk_bf16_f32 v67, v70, v71
	v_cvt_pk_bf16_f32 v68, v76, v77
	v_cvt_pk_bf16_f32 v69, v78, v79
	global_store_dwordx4 v[80:81], v[66:69], off offset:256
	s_and_saveexec_b64 s[44:45], s[0:1]
	s_cbranch_execz .LBB0_581
	s_waitcnt lgkmcnt(0)
	v_add_f32_e32 v66, v64, v65
	v_lshlrev_b64 v[64:65], 6, v[214:215]
	v_lshl_add_u64 v[64:65], s[34:35], 0, v[64:65]
	v_lshl_add_u64 v[64:65], s[42:43], 2, v[64:65]
	s_lshl_b32 s16, s30, 2
	v_lshl_add_u64 v[64:65], v[64:65], 0, s[16:17]
	global_store_dword v[64:65], v66, off
.LBB0_581:
	s_or_b64 exec, exec, s[44:45]
	s_waitcnt vmcnt(14)
	v_lshlrev_b32_e32 v66, 16, v156
	v_add_f32_e32 v60, v60, v66
	v_and_b32_e32 v66, 0xffff0000, v156
	v_add_f32_e32 v61, v61, v66
	v_lshlrev_b32_e32 v66, 16, v157
	v_add_f32_e32 v62, v62, v66
	v_and_b32_e32 v66, 0xffff0000, v157
	v_add_f32_e32 v63, v63, v66
	v_lshlrev_b32_e32 v66, 16, v158
	v_add_f32_e32 v66, v56, v66
	v_and_b32_e32 v56, 0xffff0000, v158
	v_add_f32_e32 v67, v57, v56
	v_lshlrev_b32_e32 v56, 16, v159
	v_add_f32_e32 v68, v58, v56
	v_and_b32_e32 v56, 0xffff0000, v159
	v_mul_f32_e32 v58, v61, v61
	v_add_f32_e32 v59, v59, v56
	v_cvt_pk_bf16_f32 v56, v60, v61
	v_fmac_f32_e32 v58, v60, v60
	v_mul_f32_e32 v60, v63, v63
	v_fmac_f32_e32 v60, v62, v62
	v_add_f32_e32 v58, v58, v60
	v_mul_f32_e32 v60, v67, v67
	v_fmac_f32_e32 v60, v66, v66
	v_add_f32_e32 v58, v60, v58
	v_mul_f32_e32 v60, v59, v59
	v_fmac_f32_e32 v60, v68, v68
	v_add_f32_e32 v58, v60, v58
	v_lshlrev_b32_e32 v60, 16, v152
	v_add_f32_e32 v52, v52, v60
	v_and_b32_e32 v60, 0xffff0000, v152
	v_add_f32_e32 v53, v53, v60
	v_lshlrev_b32_e32 v60, 16, v153
	v_add_f32_e32 v54, v54, v60
	v_and_b32_e32 v60, 0xffff0000, v153
	v_add_f32_e32 v55, v55, v60
	v_lshlrev_b32_e32 v60, 16, v154
	v_add_f32_e32 v60, v48, v60
	v_and_b32_e32 v48, 0xffff0000, v154
	v_add_f32_e32 v61, v49, v48
	v_lshlrev_b32_e32 v48, 16, v155
	v_cvt_pk_bf16_f32 v57, v62, v63
	v_add_f32_e32 v62, v50, v48
	v_and_b32_e32 v48, 0xffff0000, v155
	v_add_f32_e32 v63, v51, v48
	v_mul_f32_e32 v48, v53, v53
	v_mul_f32_e32 v49, v55, v55
	v_fmac_f32_e32 v48, v52, v52
	v_fmac_f32_e32 v49, v54, v54
	v_add_f32_e32 v48, v48, v49
	v_mul_f32_e32 v49, v61, v61
	v_fmac_f32_e32 v49, v60, v60
	v_add_f32_e32 v48, v49, v48
	v_mul_f32_e32 v49, v63, v63
	v_fmac_f32_e32 v49, v62, v62
	v_add_f32_e32 v48, v49, v48
	v_add_f32_e32 v48, v58, v48
	v_mov_b32_e32 v49, v48
	s_nop 1
	v_permlane16_swap_b32_e32 v48, v49
	s_waitcnt lgkmcnt(1)
	v_lshl_add_u64 v[64:65], s[70:71], 0, v[216:217]
	v_lshl_add_u64 v[64:65], v[200:201], 1, v[64:65]
	v_cvt_pk_bf16_f32 v58, v66, v67
	v_cvt_pk_bf16_f32 v59, v68, v59
	s_waitcnt lgkmcnt(0)
	v_add_f32_e32 v48, v48, v49
	v_mov_b32_e32 v49, v48
	s_nop 1
	v_permlane32_swap_b32_e32 v48, v49
	global_store_dwordx4 v[64:65], v[56:59], off
	v_cvt_pk_bf16_f32 v50, v52, v53
	v_cvt_pk_bf16_f32 v51, v54, v55
	v_cvt_pk_bf16_f32 v52, v60, v61
	v_cvt_pk_bf16_f32 v53, v62, v63
	global_store_dwordx4 v[64:65], v[50:53], off offset:256
	s_and_saveexec_b64 s[44:45], s[0:1]
	s_cbranch_execz .LBB0_583
	s_waitcnt lgkmcnt(0)
	v_add_f32_e32 v50, v48, v49
	v_lshlrev_b64 v[48:49], 6, v[210:211]
	v_lshl_add_u64 v[48:49], s[34:35], 0, v[48:49]
	v_lshl_add_u64 v[48:49], s[42:43], 2, v[48:49]
	s_lshl_b32 s16, s30, 2
	v_lshl_add_u64 v[48:49], v[48:49], 0, s[16:17]
	global_store_dword v[48:49], v50, off
; __device__ __forceinline__ unsigned cvt_pk_bf16(float lo, float hi) { unsigned r; asm volatile("v_cvt_pk_bf16_f32 %0, %1, %2" : "=v"(r) : "v"(lo), "v"(hi)); return r; }
; __device__ __forceinline__ float bf_lo(unsigned w) { return __uint_as_float(w << 16); }
; __device__ __forceinline__ float bf_hi(unsigned w) { return __uint_as_float(w & 0xffff0000u); }
;     __device__ __forceinline__ void operator()(const f32x4 (&acc)[2][2][4][2], const Unit& u, int wr, int wc, int fr, int fq) const {
;     ...
;         for (int ai = 0; ai < 2; ++ai)
; #pragma unroll
;             for (int m = 0; m < 4; ++m) {
;                 const int row = u.pm * BM + ai * HALF + wr * 64 + m * 16 + fr;
;                 float ss = 0.f;
; #pragma unroll
;                 for (int bj = 0; bj < 2; ++bj) {
;                     bf16_t* xp = X + (size_t)row * 1024 + col0 + bj * HALF;
;                     const u32x4 xv = xin[ai][m][bj];
;                     f32x4 y0 = acc[ai][bj][m][0], y1 = acc[ai][bj][m][1];
;                     y0[0] += bf_lo(xv.x); y0[1] += bf_hi(xv.x); y0[2] += bf_lo(xv.y); y0[3] += bf_hi(xv.y);
;                     y1[0] += bf_lo(xv.z); y1[1] += bf_hi(xv.z); y1[2] += bf_lo(xv.w); y1[3] += bf_hi(xv.w);
;                     if (FINAL) {
;                         float* op = out + (size_t)row * 1024 + col0 + bj * HALF;
;                         __builtin_nontemporal_store(y0, (f32x4*)op); __builtin_nontemporal_store(y1, (f32x4*)(op + 4));
;                     } else {
;                         u32x4 w; w.x = cvt_pk_bf16(y0[0], y0[1]); w.y = cvt_pk_bf16(y0[2], y0[3]); w.z = cvt_pk_bf16(y1[0], y1[1]); w.w = cvt_pk_bf16(y1[2], y1[3]);
;                         *(u32x4*)xp = w;
;                         ss += (y0[0] * y0[0] + y0[1] * y0[1]) + (y0[2] * y0[2] + y0[3] * y0[3]) + (y1[0] * y1[0] + y1[1] * y1[1]) + (y1[2] * y1[2] + y1[3] * y1[3]);
;                     }
;                 }
;                 if (!FINAL) {
;                     ss += __shfl_xor(ss, 16); ss += __shfl_xor(ss, 32);
;                     if (fq == 0) ssq[(size_t)row * 16 + u.pn * 4 + wc] = ss;
;                 }
.LBB0_583:
	s_or_b64 exec, exec, s[44:45]
	s_waitcnt vmcnt(14)
	v_lshlrev_b32_e32 v50, 16, v148
	v_add_f32_e32 v44, v44, v50
	v_and_b32_e32 v50, 0xffff0000, v148
	v_add_f32_e32 v45, v45, v50
	v_lshlrev_b32_e32 v50, 16, v149
	v_add_f32_e32 v46, v46, v50
	v_and_b32_e32 v50, 0xffff0000, v149
	v_add_f32_e32 v47, v47, v50
	v_lshlrev_b32_e32 v50, 16, v150
	v_add_f32_e32 v50, v40, v50
	v_and_b32_e32 v40, 0xffff0000, v150
	v_add_f32_e32 v51, v41, v40
	v_lshlrev_b32_e32 v40, 16, v151
	v_add_f32_e32 v52, v42, v40
	v_and_b32_e32 v40, 0xffff0000, v151
	v_mul_f32_e32 v42, v45, v45
	v_add_f32_e32 v43, v43, v40
	v_cvt_pk_bf16_f32 v40, v44, v45
	v_fmac_f32_e32 v42, v44, v44
	v_mul_f32_e32 v44, v47, v47
	v_fmac_f32_e32 v44, v46, v46
	v_add_f32_e32 v42, v42, v44
	v_mul_f32_e32 v44, v51, v51
	v_fmac_f32_e32 v44, v50, v50
	v_add_f32_e32 v42, v44, v42
	v_mul_f32_e32 v44, v43, v43
	v_fmac_f32_e32 v44, v52, v52
	v_add_f32_e32 v42, v44, v42
	v_lshlrev_b32_e32 v44, 16, v144
	v_add_f32_e32 v36, v36, v44
	v_and_b32_e32 v44, 0xffff0000, v144
	v_add_f32_e32 v37, v37, v44
	v_lshlrev_b32_e32 v44, 16, v145
	v_add_f32_e32 v38, v38, v44
	v_and_b32_e32 v44, 0xffff0000, v145
	v_add_f32_e32 v39, v39, v44
	v_lshlrev_b32_e32 v44, 16, v146
	v_add_f32_e32 v44, v32, v44
	v_and_b32_e32 v32, 0xffff0000, v146
	v_add_f32_e32 v45, v33, v32
	v_lshlrev_b32_e32 v32, 16, v147
	v_cvt_pk_bf16_f32 v41, v46, v47
	v_add_f32_e32 v46, v34, v32
	v_and_b32_e32 v32, 0xffff0000, v147
	v_add_f32_e32 v47, v35, v32
	v_mul_f32_e32 v32, v37, v37
	v_mul_f32_e32 v33, v39, v39
	v_fmac_f32_e32 v32, v36, v36
	v_fmac_f32_e32 v33, v38, v38
	v_add_f32_e32 v32, v32, v33
	v_mul_f32_e32 v33, v45, v45
	v_fmac_f32_e32 v33, v44, v44
	v_add_f32_e32 v32, v33, v32
	v_mul_f32_e32 v33, v47, v47
	v_fmac_f32_e32 v33, v46, v46
	v_add_f32_e32 v32, v33, v32
	v_add_f32_e32 v32, v42, v32
	v_mov_b32_e32 v33, v32
	s_nop 1
	v_permlane16_swap_b32_e32 v32, v33
	s_waitcnt lgkmcnt(1)
	v_lshl_add_u64 v[48:49], s[70:71], 0, v[212:213]
	v_lshl_add_u64 v[48:49], v[200:201], 1, v[48:49]
	v_cvt_pk_bf16_f32 v42, v50, v51
	v_cvt_pk_bf16_f32 v43, v52, v43
	s_waitcnt lgkmcnt(0)
	v_add_f32_e32 v32, v32, v33
	v_mov_b32_e32 v33, v32
	s_nop 1
	v_permlane32_swap_b32_e32 v32, v33
	global_store_dwordx4 v[48:49], v[40:43], off
	v_cvt_pk_bf16_f32 v34, v36, v37
	v_cvt_pk_bf16_f32 v35, v38, v39
	v_cvt_pk_bf16_f32 v36, v44, v45
	v_cvt_pk_bf16_f32 v37, v46, v47
	global_store_dwordx4 v[48:49], v[34:37], off offset:256
	s_and_saveexec_b64 s[44:45], s[0:1]
	s_cbranch_execz .LBB0_585
	s_waitcnt lgkmcnt(0)
	v_add_f32_e32 v34, v32, v33
	v_lshlrev_b64 v[32:33], 6, v[206:207]
	v_lshl_add_u64 v[32:33], s[34:35], 0, v[32:33]
	v_lshl_add_u64 v[32:33], s[42:43], 2, v[32:33]
	s_lshl_b32 s16, s30, 2
	v_lshl_add_u64 v[32:33], v[32:33], 0, s[16:17]
	global_store_dword v[32:33], v34, off
; __device__ __forceinline__ unsigned cvt_pk_bf16(float lo, float hi) { unsigned r; asm volatile("v_cvt_pk_bf16_f32 %0, %1, %2" : "=v"(r) : "v"(lo), "v"(hi)); return r; }
; __device__ __forceinline__ float bf_lo(unsigned w) { return __uint_as_float(w << 16); }
; __device__ __forceinline__ float bf_hi(unsigned w) { return __uint_as_float(w & 0xffff0000u); }
;     __device__ __forceinline__ void operator()(const f32x4 (&acc)[2][2][4][2], const Unit& u, int wr, int wc, int fr, int fq) const {
;     ...
;         for (int ai = 0; ai < 2; ++ai)
; #pragma unroll
;             for (int m = 0; m < 4; ++m) {
;                 const int row = u.pm * BM + ai * HALF + wr * 64 + m * 16 + fr;
;                 float ss = 0.f;
; #pragma unroll
;                 for (int bj = 0; bj < 2; ++bj) {
;                     bf16_t* xp = X + (size_t)row * 1024 + col0 + bj * HALF;
;                     const u32x4 xv = xin[ai][m][bj];
;                     f32x4 y0 = acc[ai][bj][m][0], y1 = acc[ai][bj][m][1];
;                     y0[0] += bf_lo(xv.x); y0[1] += bf_hi(xv.x); y0[2] += bf_lo(xv.y); y0[3] += bf_hi(xv.y);
;                     y1[0] += bf_lo(xv.z); y1[1] += bf_hi(xv.z); y1[2] += bf_lo(xv.w); y1[3] += bf_hi(xv.w);
;                     if (FINAL) {
;                         float* op = out + (size_t)row * 1024 + col0 + bj * HALF;
;                         __builtin_nontemporal_store(y0, (f32x4*)op); __builtin_nontemporal_store(y1, (f32x4*)(op + 4));
;                     } else {
;                         u32x4 w; w.x = cvt_pk_bf16(y0[0], y0[1]); w.y = cvt_pk_bf16(y0[2], y0[3]); w.z = cvt_pk_bf16(y1[0], y1[1]); w.w = cvt_pk_bf16(y1[2], y1[3]);
;                         *(u32x4*)xp = w;
;                         ss += (y0[0] * y0[0] + y0[1] * y0[1]) + (y0[2] * y0[2] + y0[3] * y0[3]) + (y1[0] * y1[0] + y1[1] * y1[1]) + (y1[2] * y1[2] + y1[3] * y1[3]);
;                     }
;                 }
;                 if (!FINAL) {
;                     ss += __shfl_xor(ss, 16); ss += __shfl_xor(ss, 32);
;                     if (fq == 0) ssq[(size_t)row * 16 + u.pn * 4 + wc] = ss;
;                 }
.LBB0_585:
	s_or_b64 exec, exec, s[44:45]
	s_waitcnt vmcnt(14)
	v_lshlrev_b32_e32 v34, 16, v140
	v_add_f32_e32 v28, v28, v34
	v_and_b32_e32 v34, 0xffff0000, v140
	v_add_f32_e32 v29, v29, v34
	v_lshlrev_b32_e32 v34, 16, v141
	v_add_f32_e32 v30, v30, v34
	v_and_b32_e32 v34, 0xffff0000, v141
	v_add_f32_e32 v31, v31, v34
	v_lshlrev_b32_e32 v34, 16, v142
	v_add_f32_e32 v34, v24, v34
	v_and_b32_e32 v24, 0xffff0000, v142
	v_add_f32_e32 v35, v25, v24
	v_lshlrev_b32_e32 v24, 16, v143
	v_add_f32_e32 v36, v26, v24
	v_and_b32_e32 v24, 0xffff0000, v143
	v_mul_f32_e32 v26, v29, v29
	v_add_f32_e32 v27, v27, v24
	v_cvt_pk_bf16_f32 v24, v28, v29
	v_fmac_f32_e32 v26, v28, v28
	v_mul_f32_e32 v28, v31, v31
	v_fmac_f32_e32 v28, v30, v30
	v_add_f32_e32 v26, v26, v28
	v_mul_f32_e32 v28, v35, v35
	v_fmac_f32_e32 v28, v34, v34
	v_add_f32_e32 v26, v28, v26
	v_mul_f32_e32 v28, v27, v27
	v_fmac_f32_e32 v28, v36, v36
	v_add_f32_e32 v26, v28, v26
	v_lshlrev_b32_e32 v28, 16, v136
	v_add_f32_e32 v20, v20, v28
	v_and_b32_e32 v28, 0xffff0000, v136
	v_add_f32_e32 v21, v21, v28
	v_lshlrev_b32_e32 v28, 16, v137
	v_add_f32_e32 v22, v22, v28
	v_and_b32_e32 v28, 0xffff0000, v137
	v_add_f32_e32 v23, v23, v28
	v_lshlrev_b32_e32 v28, 16, v138
	v_add_f32_e32 v28, v16, v28
	v_and_b32_e32 v16, 0xffff0000, v138
	v_add_f32_e32 v29, v17, v16
	v_lshlrev_b32_e32 v16, 16, v139
	v_cvt_pk_bf16_f32 v25, v30, v31
	v_add_f32_e32 v30, v18, v16
	v_and_b32_e32 v16, 0xffff0000, v139
	v_add_f32_e32 v31, v19, v16
	v_mul_f32_e32 v16, v21, v21
	v_mul_f32_e32 v17, v23, v23
	v_fmac_f32_e32 v16, v20, v20
	v_fmac_f32_e32 v17, v22, v22
	v_add_f32_e32 v16, v16, v17
	v_mul_f32_e32 v17, v29, v29
	v_fmac_f32_e32 v17, v28, v28
	v_add_f32_e32 v16, v17, v16
	v_mul_f32_e32 v17, v31, v31
	v_fmac_f32_e32 v17, v30, v30
	v_add_f32_e32 v16, v17, v16
	v_add_f32_e32 v16, v26, v16
	v_mov_b32_e32 v17, v16
	s_nop 1
	v_permlane16_swap_b32_e32 v16, v17
	s_waitcnt lgkmcnt(1)
	v_lshl_add_u64 v[32:33], s[70:71], 0, v[208:209]
	v_lshl_add_u64 v[32:33], v[200:201], 1, v[32:33]
	v_cvt_pk_bf16_f32 v26, v34, v35
	v_cvt_pk_bf16_f32 v27, v36, v27
	s_waitcnt lgkmcnt(0)
	v_add_f32_e32 v16, v16, v17
	v_mov_b32_e32 v17, v16
	s_nop 1
	v_permlane32_swap_b32_e32 v16, v17
	global_store_dwordx4 v[32:33], v[24:27], off
	v_cvt_pk_bf16_f32 v18, v20, v21
	v_cvt_pk_bf16_f32 v19, v22, v23
	v_cvt_pk_bf16_f32 v20, v28, v29
	v_cvt_pk_bf16_f32 v21, v30, v31
	global_store_dwordx4 v[32:33], v[18:21], off offset:256
	s_and_saveexec_b64 s[44:45], s[0:1]
	s_cbranch_execz .LBB0_587
	s_waitcnt lgkmcnt(0)
	v_add_f32_e32 v18, v16, v17
	v_lshlrev_b64 v[16:17], 6, v[202:203]
	v_lshl_add_u64 v[16:17], s[34:35], 0, v[16:17]
	v_lshl_add_u64 v[16:17], s[42:43], 2, v[16:17]
	s_lshl_b32 s16, s30, 2
	v_lshl_add_u64 v[16:17], v[16:17], 0, s[16:17]
	global_store_dword v[16:17], v18, off
.LBB0_587:
	s_or_b64 exec, exec, s[44:45]
	s_waitcnt vmcnt(14)
	v_lshlrev_b32_e32 v18, 16, v132
	v_add_f32_e32 v12, v12, v18
	v_and_b32_e32 v18, 0xffff0000, v132
	v_add_f32_e32 v13, v13, v18
	v_lshlrev_b32_e32 v18, 16, v133
	v_add_f32_e32 v14, v14, v18
	v_and_b32_e32 v18, 0xffff0000, v133
	v_add_f32_e32 v15, v15, v18
	v_lshlrev_b32_e32 v18, 16, v134
	v_add_f32_e32 v18, v8, v18
	v_and_b32_e32 v8, 0xffff0000, v134
	v_add_f32_e32 v19, v9, v8
	v_lshlrev_b32_e32 v8, 16, v135
	v_add_f32_e32 v20, v10, v8
	v_and_b32_e32 v8, 0xffff0000, v135
	v_mul_f32_e32 v10, v13, v13
	v_add_f32_e32 v11, v11, v8
	v_cvt_pk_bf16_f32 v8, v12, v13
	v_fmac_f32_e32 v10, v12, v12
	v_mul_f32_e32 v12, v15, v15
	v_fmac_f32_e32 v12, v14, v14
	v_add_f32_e32 v10, v10, v12
	v_mul_f32_e32 v12, v19, v19
	v_fmac_f32_e32 v12, v18, v18
	v_add_f32_e32 v10, v12, v10
	v_mul_f32_e32 v12, v11, v11
	v_fmac_f32_e32 v12, v20, v20
	v_add_f32_e32 v10, v12, v10
	v_lshlrev_b32_e32 v12, 16, v124
	v_add_f32_e32 v4, v4, v12
	v_and_b32_e32 v12, 0xffff0000, v124
	v_add_f32_e32 v5, v5, v12
	v_lshlrev_b32_e32 v12, 16, v125
	v_add_f32_e32 v6, v6, v12
	v_and_b32_e32 v12, 0xffff0000, v125
	v_add_f32_e32 v7, v7, v12
	v_lshlrev_b32_e32 v12, 16, v126
	v_add_f32_e32 v12, v0, v12
	v_and_b32_e32 v0, 0xffff0000, v126
	v_add_f32_e32 v13, v1, v0
	v_lshlrev_b32_e32 v0, 16, v127
	v_cvt_pk_bf16_f32 v9, v14, v15
	v_add_f32_e32 v14, v2, v0
	v_and_b32_e32 v0, 0xffff0000, v127
	v_add_f32_e32 v15, v3, v0
	v_mul_f32_e32 v0, v5, v5
	v_mul_f32_e32 v1, v7, v7
	v_fmac_f32_e32 v0, v4, v4
	v_fmac_f32_e32 v1, v6, v6
	v_add_f32_e32 v0, v0, v1
	v_mul_f32_e32 v1, v13, v13
	v_fmac_f32_e32 v1, v12, v12
	v_add_f32_e32 v0, v1, v0
	v_mul_f32_e32 v1, v15, v15
	v_fmac_f32_e32 v1, v14, v14
	v_add_f32_e32 v0, v1, v0
	v_add_f32_e32 v0, v10, v0
	v_mov_b32_e32 v1, v0
	s_nop 1
	v_permlane16_swap_b32_e32 v0, v1
	s_waitcnt lgkmcnt(1)
	v_lshl_add_u64 v[16:17], s[70:71], 0, v[204:205]
	v_lshl_add_u64 v[16:17], v[200:201], 1, v[16:17]
	v_cvt_pk_bf16_f32 v10, v18, v19
	v_cvt_pk_bf16_f32 v11, v20, v11
	s_waitcnt lgkmcnt(0)
	v_add_f32_e32 v0, v0, v1
	v_mov_b32_e32 v1, v0
	s_nop 1
	v_permlane32_swap_b32_e32 v0, v1
	global_store_dwordx4 v[16:17], v[8:11], off
	v_cvt_pk_bf16_f32 v2, v4, v5
	v_cvt_pk_bf16_f32 v3, v6, v7
	v_cvt_pk_bf16_f32 v4, v12, v13
	v_cvt_pk_bf16_f32 v5, v14, v15
	global_store_dwordx4 v[16:17], v[2:5], off offset:256
	s_and_saveexec_b64 s[44:45], s[0:1]
	s_cbranch_execz .LBB0_589
	s_waitcnt lgkmcnt(0)
	v_add_f32_e32 v2, v0, v1
	v_lshlrev_b64 v[0:1], 6, v[198:199]
	v_lshl_add_u64 v[0:1], s[34:35], 0, v[0:1]
	v_lshl_add_u64 v[0:1], s[42:43], 2, v[0:1]
	s_lshl_b32 s16, s30, 2
	v_lshl_add_u64 v[0:1], v[0:1], 0, s[16:17]
	global_store_dword v[0:1], v2, off

; __device__ __forceinline__ void rows_rstd(const float* ssq, int row0, int fq, float (&rs)[2][4]) {
;     f32x4 pr[2][4];
; #pragma unroll
;     for (int ai = 0; ai < 2; ++ai)
; #pragma unroll
;         for (int m = 0; m < 4; ++m) pr[ai][m] = *(const f32x4*)(ssq + (size_t)(row0 + ai * HALF + m * 16) * 16 + 4 * fq);
; #pragma unroll
;     for (int ai = 0; ai < 2; ++ai)
; #pragma unroll
;         for (int m = 0; m < 4; ++m) { float t = (pr[ai][m][0] + pr[ai][m][1]) + (pr[ai][m][2] + pr[ai][m][3]); t += __shfl_xor(t, 16); t += __shfl_xor(t, 32); rs[ai][m] = __builtin_amdgcn_rsqf(t * (1.0f / 1024.0f) + 1e-6f); }
; }
;     __device__ __forceinline__ void operator()(const f32x4 (&acc)[2][2][4][2], const Unit& u, int wr, int wc, int fr, int fq) const {
;         float rsv[2][4]; rows_rstd(ssq, u.pm * BM + wr * 64 + fr, fq, rsv);
; #pragma unroll
;         for (int ai = 0; ai < 2; ++ai)
; #pragma unroll
;             for (int m = 0; m < 4; ++m) {
;                 const int row = u.pm * BM + ai * HALF + wr * 64 + m * 16 + fr;
;                 const float rs = rsv[ai][m];
;                 bf16_t* rp = O + (size_t)row * 1536 + wc * 32 + 8 * fq;
.LBB0_663:
	v_mbcnt_lo_u32_b32 v252, -1, 0
	v_mbcnt_hi_u32_b32 v252, -1, v252
	v_and_b32_e32 v252, 48, v252
	v_lshl_add_u32 v252, v161, 6, v252
	v_add_u32_e32 v252, 0x20000, v252
	v_lshl_add_u32 v162, s44, 8, v161
	v_or_b32_e32 v158, 16, v162
	v_ashrrev_i32_e32 v163, 31, v162
	v_ashrrev_i32_e32 v159, 31, v158
	v_lshlrev_b64 v[146:147], 6, v[162:163]
	v_lshlrev_b64 v[148:149], 6, v[158:159]
	v_or_b32_e32 v156, 32, v162
	v_or_b32_e32 v154, 48, v162
	v_lshl_add_u64 v[146:147], v[136:137], 0, v[146:147]
	v_lshl_add_u64 v[148:149], v[136:137], 0, v[148:149]
	v_ashrrev_i32_e32 v157, 31, v156
	v_ashrrev_i32_e32 v155, 31, v154
	ds_read_b128 v[170:173], v252 offset:0
	ds_read_b128 v[174:177], v252 offset:1024
	v_lshlrev_b64 v[146:147], 6, v[156:157]
	v_lshlrev_b64 v[148:149], 6, v[154:155]
	v_add_u32_e32 v152, 0x80, v162
	v_add_u32_e32 v150, 0x90, v162
	v_lshl_add_u64 v[146:147], v[136:137], 0, v[146:147]
	v_lshl_add_u64 v[148:149], v[136:137], 0, v[148:149]
	v_ashrrev_i32_e32 v153, 31, v152
	v_ashrrev_i32_e32 v151, 31, v150
	ds_read_b128 v[178:181], v252 offset:2048
	ds_read_b128 v[182:185], v252 offset:3072
	v_lshlrev_b64 v[146:147], 6, v[152:153]
	v_lshlrev_b64 v[148:149], 6, v[150:151]
	v_lshl_add_u64 v[146:147], v[136:137], 0, v[146:147]
	v_lshl_add_u64 v[148:149], v[136:137], 0, v[148:149]
	ds_read_b128 v[186:189], v252 offset:8192
	ds_read_b128 v[190:193], v252 offset:9216
	v_add_u32_e32 v148, 0xa0, v162
	v_ashrrev_i32_e32 v149, 31, v148
	v_lshlrev_b64 v[146:147], 6, v[148:149]
	v_lshl_add_u64 v[146:147], v[136:137], 0, v[146:147]
	ds_read_b128 v[194:197], v252 offset:10240
	v_add_u32_e32 v146, 0xb0, v162
	v_ashrrev_i32_e32 v147, 31, v146
	v_lshlrev_b64 v[198:199], 6, v[146:147]
	v_lshl_add_u64 v[198:199], v[136:137], 0, v[198:199]
	ds_read_b128 v[198:201], v252 offset:11264
	v_and_b32_e32 v149, 64, v168
	v_xor_b32_e32 v147, 16, v168
	v_add_u32_e32 v149, 64, v149
	v_xor_b32_e32 v151, 32, v168
	v_cmp_lt_i32_e32 vcc, v147, v149
	s_cmp_gt_i32 s4, 1
	s_cselect_b64 s[48:49], -1, 0
	v_cndmask_b32_e32 v147, v168, v147, vcc
	v_cmp_lt_i32_e32 vcc, v151, v149
	v_lshlrev_b32_e32 v147, 2, v147
	s_cmp_gt_u32 s4, 5
	v_cndmask_b32_e32 v149, v168, v151, vcc
	v_lshlrev_b32_e32 v149, 2, v149
	s_cselect_b64 s[0:1], -1, 0
	s_lshl_b32 s5, s4, 7
	s_add_i32 s44, s5, 0xffffff00
	s_ashr_i32 s45, s44, 31
	s_mov_b64 s[50:51], -1
	s_and_b64 vcc, exec, s[48:49]
	s_waitcnt lgkmcnt(0)
	v_add_f32_e32 v151, v170, v171
	v_add_f32_e32 v153, v172, v173
	v_add_f32_e32 v151, v151, v153
	v_add_f32_e32 v153, v174, v175
	v_add_f32_e32 v155, v176, v177
	v_add_f32_e32 v153, v153, v155
	v_add_f32_e32 v157, v178, v179
	v_mov_b32_e32 v178, v151
	s_nop 1
	v_permlane16_swap_b32_e32 v151, v178
	v_add_f32_e32 v159, v180, v181
	v_add_f32_e32 v160, v182, v183
	v_add_f32_e32 v163, v184, v185
	v_add_f32_e32 v170, v186, v187
	v_add_f32_e32 v171, v188, v189
	v_add_f32_e32 v172, v190, v191
	v_add_f32_e32 v173, v192, v193
	v_add_f32_e32 v155, v157, v159
	v_add_f32_e32 v157, v160, v163
	v_add_f32_e32 v174, v194, v195
	v_add_f32_e32 v175, v196, v197
	v_add_f32_e32 v159, v170, v171
	v_add_f32_e32 v160, v172, v173
	v_add_f32_e32 v163, v174, v175
	v_add_f32_e32 v176, v198, v199
	v_add_f32_e32 v177, v200, v201
	v_add_f32_e32 v170, v176, v177
	s_waitcnt lgkmcnt(0)
	v_add_f32_e32 v178, v151, v178
	v_mov_b32_e32 v171, v153
	s_nop 1
	v_permlane16_swap_b32_e32 v153, v171
	v_mov_b32_e32 v172, v155
	s_nop 1
	v_permlane16_swap_b32_e32 v155, v172
	v_mov_b32_e32 v174, v157
	s_nop 1
	v_permlane16_swap_b32_e32 v157, v174
	v_mov_b32_e32 v176, v159
	s_nop 1
	v_permlane16_swap_b32_e32 v159, v176
	v_mov_b32_e32 v177, v160
	s_nop 1
	v_permlane16_swap_b32_e32 v160, v177
	v_mov_b32_e32 v179, v163
	s_nop 1
	v_permlane16_swap_b32_e32 v163, v179
	v_mov_b32_e32 v147, v170
	s_nop 1
	v_permlane16_swap_b32_e32 v170, v147
	v_mov_b32_e32 v180, v178
	s_nop 1
	v_permlane32_swap_b32_e32 v178, v180
	s_waitcnt lgkmcnt(7)
	v_add_f32_e32 v175, v153, v171
	s_waitcnt lgkmcnt(6)
	v_add_f32_e32 v173, v155, v172
	s_waitcnt lgkmcnt(5)
	v_add_f32_e32 v171, v157, v174
	s_waitcnt lgkmcnt(4)
	v_add_f32_e32 v159, v159, v176
	s_waitcnt lgkmcnt(3)
	v_add_f32_e32 v155, v160, v177
	s_waitcnt lgkmcnt(2)
	v_add_f32_e32 v151, v163, v179
	s_waitcnt lgkmcnt(1)
	v_add_f32_e32 v147, v170, v147
	s_waitcnt lgkmcnt(0)
	v_add_f32_e32 v160, v178, v180
	v_mov_b32_e32 v176, v175
	s_nop 1
	v_permlane32_swap_b32_e32 v175, v176
	v_mov_b32_e32 v174, v173
	s_nop 1
	v_permlane32_swap_b32_e32 v173, v174
	v_mov_b32_e32 v172, v171
	s_nop 1
	v_permlane32_swap_b32_e32 v171, v172
	v_mov_b32_e32 v170, v159
	s_nop 1
	v_permlane32_swap_b32_e32 v159, v170
	v_mov_b32_e32 v157, v155
	s_nop 1
	v_permlane32_swap_b32_e32 v155, v157
	v_mov_b32_e32 v153, v151
	s_nop 1
	v_permlane32_swap_b32_e32 v151, v153
	v_fmamk_f32 v160, v160, 0x3a800000, v169
	v_mov_b32_e32 v149, v147
	s_nop 1
	v_permlane32_swap_b32_e32 v147, v149
	v_rsq_f32_e32 v160, v160
	v_mad_i64_i32 v[162:163], s[46:47], v162, s58, v[138:139]
	s_cbranch_vccz .LBB0_665
; __device__ __forceinline__ unsigned cvt_pk_bf16(float lo, float hi) { unsigned r; asm volatile("v_cvt_pk_bf16_f32 %0, %1, %2" : "=v"(r) : "v"(lo), "v"(hi)); return r; }
; __device__ __forceinline__ float fast_sigmoid(float x) { return __builtin_amdgcn_rcpf(1.0f + __expf(-x)); }
;     __device__ __forceinline__ void operator()(const f32x4 (&acc)[2][2][4][2], const Unit& u, int wr, int wc, int fr, int fq) const {
;     ...
;                     float h[8];
;                     const bool glu = u.pn >= 6;
; #pragma unroll
;                     for (int n = 0; n < 2; ++n)
; #pragma unroll
;                         for (int i = 0; i < 4; ++i) { const float a = acc[ai][0][m][n][i] * rs, b = acc[ai][1][m][n][i] * rs; h[4 * n + i] = glu ? a * fast_sigmoid(b) : a * b; }
;                     u32x4 w; w.x = cvt_pk_bf16(h[0], h[1]); w.y = cvt_pk_bf16(h[2], h[3]); w.z = cvt_pk_bf16(h[4], h[5]); w.w = cvt_pk_bf16(h[6], h[7]);
;                     *(u32x4*)(rp + 512 + (u.pn - 2) * HALF) = w;
	v_mul_f32_e32 v177, v116, v160
	v_mul_f32_e32 v179, v117, v160
	v_mul_f32_e32 v178, 0xbfb8aa3b, v177
	v_mul_f32_e32 v180, 0xbfb8aa3b, v179
	v_exp_f32_e32 v178, v178
	v_exp_f32_e32 v180, v180
	v_mul_f32_e32 v181, v124, v160
	v_mul_f32_e32 v183, v126, v160
	v_add_f32_e32 v178, 1.0, v178
	v_add_f32_e32 v180, 1.0, v180
	v_rcp_f32_e32 v178, v178
	v_rcp_f32_e32 v180, v180
	v_mul_f32_e32 v185, v120, v160
	v_mul_f32_e32 v187, v122, v160
	v_cndmask_b32_e64 v177, v177, v178, s[0:1]
	v_mul_f32_e32 v178, v125, v160
	v_cndmask_b32_e64 v179, v179, v180, s[0:1]
	v_mul_f32_e32 v177, v181, v177
	v_mul_f32_e32 v178, v178, v179
	v_mul_f32_e32 v179, v118, v160
	v_mul_f32_e32 v181, v119, v160
	v_mul_f32_e32 v180, 0xbfb8aa3b, v179
	v_mul_f32_e32 v182, 0xbfb8aa3b, v181
	v_exp_f32_e32 v180, v180
	v_exp_f32_e32 v182, v182
	v_cvt_pk_bf16_f32 v178, v177, v178
	s_mov_b64 s[50:51], 0
	v_add_f32_e32 v180, 1.0, v180
	v_add_f32_e32 v182, 1.0, v182
	v_rcp_f32_e32 v180, v180
	v_rcp_f32_e32 v182, v182
	v_cndmask_b32_e64 v179, v179, v180, s[0:1]
	v_mul_f32_e32 v180, v127, v160
	v_cndmask_b32_e64 v181, v181, v182, s[0:1]
	v_mul_f32_e32 v179, v183, v179
	v_mul_f32_e32 v180, v180, v181
	v_mul_f32_e32 v181, v112, v160
	v_mul_f32_e32 v183, v113, v160
	v_mul_f32_e32 v182, 0xbfb8aa3b, v181
	v_mul_f32_e32 v184, 0xbfb8aa3b, v183
	v_exp_f32_e32 v182, v182
	v_exp_f32_e32 v184, v184
	v_cvt_pk_bf16_f32 v179, v179, v180
	v_add_f32_e32 v182, 1.0, v182
	v_add_f32_e32 v184, 1.0, v184
	v_rcp_f32_e32 v182, v182
	v_rcp_f32_e32 v184, v184
	v_cndmask_b32_e64 v181, v181, v182, s[0:1]
	v_mul_f32_e32 v182, v121, v160
	v_cndmask_b32_e64 v183, v183, v184, s[0:1]
	v_mul_f32_e32 v182, v182, v183
	v_mul_f32_e32 v183, v114, v160
	v_mul_f32_e32 v181, v185, v181
	v_mul_f32_e32 v184, 0xbfb8aa3b, v183
	v_mul_f32_e32 v185, v115, v160
	v_exp_f32_e32 v184, v184
	v_mul_f32_e32 v186, 0xbfb8aa3b, v185
	v_exp_f32_e32 v186, v186
	v_cvt_pk_bf16_f32 v180, v181, v182
	v_add_f32_e32 v184, 1.0, v184
	v_rcp_f32_e32 v184, v184
	v_add_f32_e32 v186, 1.0, v186
	v_rcp_f32_e32 v186, v186
	v_cndmask_b32_e64 v183, v183, v184, s[0:1]
	v_mul_f32_e32 v183, v187, v183
	v_mul_f32_e32 v184, v123, v160
	v_cndmask_b32_e64 v185, v185, v186, s[0:1]
	v_mul_f32_e32 v184, v184, v185
	v_cvt_pk_bf16_f32 v181, v183, v184
	v_lshl_add_u64 v[182:183], s[44:45], 1, v[162:163]
	global_store_dwordx4 v[182:183], v[178:181], off offset:1024

; __device__ __forceinline__ unsigned cvt_pk_bf16(float lo, float hi) { unsigned r; asm volatile("v_cvt_pk_bf16_f32 %0, %1, %2" : "=v"(r) : "v"(lo), "v"(hi)); return r; }
;     __device__ __forceinline__ void operator()(const f32x4 (&acc)[2][2][4][2], const Unit& u, int wr, int wc, int fr, int fq) const {
;         const int col0 = u.pn * BM + wc * 32 + 8 * fq;
;         u32x4 xin[2][4][2];
; #pragma unroll
;         for (int ai = 0; ai < 2; ++ai)
; #pragma unroll
;             for (int m = 0; m < 4; ++m)
; #pragma unroll
;                 for (int bj = 0; bj < 2; ++bj) xin[ai][m][bj] = *(const u32x4*)(X + (size_t)(u.pm * BM + ai * HALF + wr * 64 + m * 16 + fr) * 1024 + col0 + bj * HALF);
; #pragma unroll
;         for (int ai = 0; ai < 2; ++ai)
; #pragma unroll
;             for (int m = 0; m < 4; ++m) {
;                 const int row = u.pm * BM + ai * HALF + wr * 64 + m * 16 + fr;
;                 float ss = 0.f;
; #pragma unroll
;                 for (int bj = 0; bj < 2; ++bj) {
;                     bf16_t* xp = X + (size_t)row * 1024 + col0 + bj * HALF;
;                     const u32x4 xv = xin[ai][m][bj];
;                     f32x4 y0 = acc[ai][bj][m][0], y1 = acc[ai][bj][m][1];
;                     y0[0] += bf_lo(xv.x); y0[1] += bf_hi(xv.x); y0[2] += bf_lo(xv.y); y0[3] += bf_hi(xv.y);
;                     y1[0] += bf_lo(xv.z); y1[1] += bf_hi(xv.z); y1[2] += bf_lo(xv.w); y1[3] += bf_hi(xv.w);
;                     if (FINAL) {
;                         float* op = out + (size_t)row * 1024 + col0 + bj * HALF;
;                         __builtin_nontemporal_store(y0, (f32x4*)op); __builtin_nontemporal_store(y1, (f32x4*)(op + 4));
;                     } else {
;                         u32x4 w; w.x = cvt_pk_bf16(y0[0], y0[1]); w.y = cvt_pk_bf16(y0[2], y0[3]); w.z = cvt_pk_bf16(y1[0], y1[1]); w.w = cvt_pk_bf16(y1[2], y1[3]);
;                         *(u32x4*)xp = w;
;                         ss += (y0[0] * y0[0] + y0[1] * y0[1]) + (y0[2] * y0[2] + y0[3] * y0[3]) + (y1[0] * y1[0] + y1[1] * y1[1]) + (y1[2] * y1[2] + y1[3] * y1[3]);
;                     }
;                 }
;                 if (!FINAL) {
;                     ss += __shfl_xor(ss, 16); ss += __shfl_xor(ss, 32);
;                     if (fq == 0) ssq[(size_t)row * 16 + u.pn * 4 + wc] = ss;
;                 }
.LBB0_891:
	v_lshl_or_b32 v200, s8, 8, v233
	v_lshl_add_u32 v226, s30, 8, v231
	v_ashrrev_i32_e32 v201, 31, v200
	v_lshlrev_b64 v[246:247], 1, v[200:201]
	v_ashrrev_i32_e32 v227, 31, v226
	v_lshl_add_u64 v[124:125], s[70:71], 0, v[246:247]
	v_lshlrev_b64 v[126:127], 11, v[226:227]
	v_lshl_add_u64 v[132:133], v[124:125], 0, v[126:127]
	global_load_dwordx4 v[238:241], v[132:133], off
	global_load_dwordx4 v[242:245], v[132:133], off offset:256
	v_or_b32_e32 v222, 16, v226
	v_or_b32_e32 v218, 32, v226
	v_or_b32_e32 v214, 48, v226
	v_add_u32_e32 v210, 0x80, v226
	v_add_u32_e32 v206, 0x90, v226
	v_add_u32_e32 v202, 0xa0, v226
	v_add_u32_e32 v198, 0xb0, v226
	v_ashrrev_i32_e32 v223, 31, v222
	v_ashrrev_i32_e32 v219, 31, v218
	v_ashrrev_i32_e32 v215, 31, v214
	v_ashrrev_i32_e32 v211, 31, v210
	v_ashrrev_i32_e32 v207, 31, v206
	v_ashrrev_i32_e32 v203, 31, v202
	v_ashrrev_i32_e32 v199, 31, v198
	v_lshlrev_b64 v[228:229], 11, v[222:223]
	v_lshlrev_b64 v[224:225], 11, v[218:219]
	v_lshlrev_b64 v[220:221], 11, v[214:215]
	v_lshlrev_b64 v[216:217], 11, v[210:211]
	v_lshlrev_b64 v[212:213], 11, v[206:207]
	v_lshlrev_b64 v[208:209], 11, v[202:203]
	v_lshlrev_b64 v[204:205], 11, v[198:199]
	v_lshl_add_u64 v[248:249], s[70:71], 0, v[126:127]
	v_lshl_add_u64 v[126:127], v[124:125], 0, v[228:229]
	v_lshl_add_u64 v[132:133], v[124:125], 0, v[224:225]
	v_lshl_add_u64 v[134:135], v[124:125], 0, v[220:221]
	v_lshl_add_u64 v[136:137], v[124:125], 0, v[216:217]
	v_lshl_add_u64 v[138:139], v[124:125], 0, v[212:213]
	v_lshl_add_u64 v[250:251], v[124:125], 0, v[208:209]
	v_lshl_add_u64 v[124:125], v[124:125], 0, v[204:205]
	global_load_dwordx4 v[180:183], v[126:127], off
	global_load_dwordx4 v[176:179], v[126:127], off offset:256
	global_load_dwordx4 v[172:175], v[132:133], off
	global_load_dwordx4 v[168:171], v[132:133], off offset:256
	global_load_dwordx4 v[164:167], v[134:135], off
	global_load_dwordx4 v[160:163], v[134:135], off offset:256
	global_load_dwordx4 v[156:159], v[136:137], off
	global_load_dwordx4 v[152:155], v[136:137], off offset:256
	global_load_dwordx4 v[148:151], v[138:139], off
	global_load_dwordx4 v[144:147], v[138:139], off offset:256
	global_load_dwordx4 v[140:143], v[250:251], off
	s_nop 0
	global_load_dwordx4 v[136:139], v[250:251], off offset:256
	global_load_dwordx4 v[132:135], v[124:125], off
	s_nop 0
	global_load_dwordx4 v[124:127], v[124:125], off offset:256
	v_lshl_add_u64 v[246:247], v[248:249], 0, v[246:247]
	s_lshl_b32 s30, s8, 2
	s_ashr_i32 s31, s30, 31
	s_waitcnt vmcnt(14)
	v_lshlrev_b32_e32 v248, 16, v238
	v_and_b32_e32 v238, 0xffff0000, v238
	v_lshlrev_b32_e32 v249, 16, v239
	v_and_b32_e32 v239, 0xffff0000, v239
	v_lshlrev_b32_e32 v250, 16, v240
	v_and_b32_e32 v240, 0xffff0000, v240
	v_lshlrev_b32_e32 v252, 16, v242
	v_lshlrev_b32_e32 v253, 16, v243
	v_add_f32_e32 v129, v129, v238
	v_add_f32_e32 v131, v131, v239
	v_and_b32_e32 v243, 0xffff0000, v243
	v_add_f32_e32 v128, v128, v248
	v_add_f32_e32 v130, v130, v249
	v_add_f32_e32 v121, v121, v240
	v_add_f32_e32 v238, v116, v252
	v_add_f32_e32 v240, v118, v253
	v_cvt_pk_bf16_f32 v116, v128, v129
	v_mul_f32_e32 v118, v129, v129
	v_mul_f32_e32 v129, v131, v131
	v_lshlrev_b32_e32 v251, 16, v241
	v_and_b32_e32 v241, 0xffff0000, v241
	v_and_b32_e32 v242, 0xffff0000, v242
	v_fmac_f32_e32 v118, v128, v128
	v_fmac_f32_e32 v129, v130, v130
	v_add_f32_e32 v128, v119, v243
	v_lshlrev_b32_e32 v119, 16, v244
	v_add_f32_e32 v120, v120, v250
	v_add_f32_e32 v123, v123, v241
	v_add_f32_e32 v239, v117, v242
	v_cvt_pk_bf16_f32 v117, v130, v131
	v_mul_f32_e32 v131, v121, v121
	v_add_f32_e32 v118, v118, v129
	v_add_f32_e32 v129, v112, v119
	v_and_b32_e32 v112, 0xffff0000, v244
	v_add_f32_e32 v122, v122, v251
	v_mul_f32_e32 v241, v123, v123
	v_fmac_f32_e32 v131, v120, v120
	v_add_f32_e32 v130, v113, v112
	v_lshlrev_b32_e32 v112, 16, v245
	v_fmac_f32_e32 v241, v122, v122
	v_add_f32_e32 v118, v131, v118
	v_add_f32_e32 v131, v114, v112
	v_and_b32_e32 v112, 0xffff0000, v245
	v_add_f32_e32 v118, v241, v118
	v_add_f32_e32 v241, v115, v112
	v_mul_f32_e32 v112, v239, v239
	v_mul_f32_e32 v113, v128, v128
	v_fmac_f32_e32 v112, v238, v238
	v_fmac_f32_e32 v113, v240, v240
	v_add_f32_e32 v112, v112, v113
	v_mul_f32_e32 v113, v130, v130
	v_fmac_f32_e32 v113, v129, v129
	v_add_f32_e32 v112, v113, v112
	v_mul_f32_e32 v113, v241, v241
	v_fmac_f32_e32 v113, v131, v131
	v_add_f32_e32 v112, v113, v112
	v_and_b32_e32 v114, 64, v237
	v_add_f32_e32 v113, v118, v112
	v_xor_b32_e32 v112, 16, v237
	v_add_u32_e32 v115, 64, v114
	v_cmp_lt_i32_e32 vcc, v112, v115
	v_cvt_pk_bf16_f32 v118, v120, v121
	v_cvt_pk_bf16_f32 v119, v122, v123
	global_store_dwordx4 v[246:247], v[116:119], off
	s_nop 0
	v_cndmask_b32_e32 v112, v237, v112, vcc
	v_lshlrev_b32_e32 v112, 2, v112
	v_mov_b32_e32 v114, v113
	s_nop 1
	v_permlane16_swap_b32_e32 v113, v114
	v_cvt_pk_bf16_f32 v116, v238, v239
	v_cvt_pk_bf16_f32 v117, v240, v128
	v_cvt_pk_bf16_f32 v118, v129, v130
	v_cvt_pk_bf16_f32 v119, v131, v241
	s_waitcnt lgkmcnt(0)
	v_add_f32_e32 v114, v113, v114
	v_xor_b32_e32 v113, 32, v237
	v_cmp_lt_i32_e32 vcc, v113, v115
	global_store_dwordx4 v[246:247], v[116:119], off offset:256
	s_nop 0
	v_cndmask_b32_e32 v113, v237, v113, vcc
	v_lshlrev_b32_e32 v113, 2, v113
	v_mov_b32_e32 v115, v114
	s_nop 1
	v_permlane32_swap_b32_e32 v114, v115
	s_and_saveexec_b64 s[36:37], s[0:1]
	s_cbranch_execz .LBB0_893
	s_waitcnt lgkmcnt(0)
	v_add_f32_e32 v116, v114, v115
	v_lshlrev_b64 v[114:115], 6, v[226:227]
	v_lshl_add_u64 v[114:115], s[34:35], 0, v[114:115]
	v_lshl_add_u64 v[114:115], s[30:31], 2, v[114:115]
	s_lshl_b32 s8, s49, 2
	v_lshl_add_u64 v[114:115], v[114:115], 0, s[8:9]
	global_store_dword v[114:115], v116, off
; __device__ __forceinline__ unsigned cvt_pk_bf16(float lo, float hi) { unsigned r; asm volatile("v_cvt_pk_bf16_f32 %0, %1, %2" : "=v"(r) : "v"(lo), "v"(hi)); return r; }
; __device__ __forceinline__ float bf_lo(unsigned w) { return __uint_as_float(w << 16); }
; __device__ __forceinline__ float bf_hi(unsigned w) { return __uint_as_float(w & 0xffff0000u); }
;     __device__ __forceinline__ void operator()(const f32x4 (&acc)[2][2][4][2], const Unit& u, int wr, int wc, int fr, int fq) const {
;     ...
;         for (int ai = 0; ai < 2; ++ai)
; #pragma unroll
;             for (int m = 0; m < 4; ++m) {
;                 const int row = u.pm * BM + ai * HALF + wr * 64 + m * 16 + fr;
;                 float ss = 0.f;
; #pragma unroll
;                 for (int bj = 0; bj < 2; ++bj) {
;                     bf16_t* xp = X + (size_t)row * 1024 + col0 + bj * HALF;
;                     const u32x4 xv = xin[ai][m][bj];
;                     f32x4 y0 = acc[ai][bj][m][0], y1 = acc[ai][bj][m][1];
;                     y0[0] += bf_lo(xv.x); y0[1] += bf_hi(xv.x); y0[2] += bf_lo(xv.y); y0[3] += bf_hi(xv.y);
;                     y1[0] += bf_lo(xv.z); y1[1] += bf_hi(xv.z); y1[2] += bf_lo(xv.w); y1[3] += bf_hi(xv.w);
;                     if (FINAL) {
;                         float* op = out + (size_t)row * 1024 + col0 + bj * HALF;
;                         __builtin_nontemporal_store(y0, (f32x4*)op); __builtin_nontemporal_store(y1, (f32x4*)(op + 4));
;                     } else {
;                         u32x4 w; w.x = cvt_pk_bf16(y0[0], y0[1]); w.y = cvt_pk_bf16(y0[2], y0[3]); w.z = cvt_pk_bf16(y1[0], y1[1]); w.w = cvt_pk_bf16(y1[2], y1[3]);
;                         *(u32x4*)xp = w;
;                         ss += (y0[0] * y0[0] + y0[1] * y0[1]) + (y0[2] * y0[2] + y0[3] * y0[3]) + (y1[0] * y1[0] + y1[1] * y1[1]) + (y1[2] * y1[2] + y1[3] * y1[3]);
;                     }
;                 }
;                 if (!FINAL) {
;                     ss += __shfl_xor(ss, 16); ss += __shfl_xor(ss, 32);
;                     if (fq == 0) ssq[(size_t)row * 16 + u.pn * 4 + wc] = ss;
;                 }
.LBB0_893:
	s_or_b64 exec, exec, s[36:37]
	s_waitcnt vmcnt(14)
	v_lshlrev_b32_e32 v116, 16, v180
	v_add_f32_e32 v108, v108, v116
	v_and_b32_e32 v116, 0xffff0000, v180
	v_add_f32_e32 v109, v109, v116
	v_lshlrev_b32_e32 v116, 16, v181
	v_add_f32_e32 v110, v110, v116
	v_and_b32_e32 v116, 0xffff0000, v181
	v_add_f32_e32 v111, v111, v116
	v_lshlrev_b32_e32 v116, 16, v182
	v_add_f32_e32 v116, v104, v116
	v_and_b32_e32 v104, 0xffff0000, v182
	v_add_f32_e32 v117, v105, v104
	v_lshlrev_b32_e32 v104, 16, v183
	v_add_f32_e32 v118, v106, v104
	v_and_b32_e32 v104, 0xffff0000, v183
	v_mul_f32_e32 v106, v109, v109
	v_add_f32_e32 v107, v107, v104
	v_cvt_pk_bf16_f32 v104, v108, v109
	v_fmac_f32_e32 v106, v108, v108
	v_mul_f32_e32 v108, v111, v111
	v_fmac_f32_e32 v108, v110, v110
	v_add_f32_e32 v106, v106, v108
	v_mul_f32_e32 v108, v117, v117
	v_fmac_f32_e32 v108, v116, v116
	v_add_f32_e32 v106, v108, v106
	v_mul_f32_e32 v108, v107, v107
	v_fmac_f32_e32 v108, v118, v118
	v_add_f32_e32 v106, v108, v106
	v_lshlrev_b32_e32 v108, 16, v176
	v_add_f32_e32 v100, v100, v108
	v_and_b32_e32 v108, 0xffff0000, v176
	v_add_f32_e32 v101, v101, v108
	v_lshlrev_b32_e32 v108, 16, v177
	v_add_f32_e32 v102, v102, v108
	v_and_b32_e32 v108, 0xffff0000, v177
	v_add_f32_e32 v103, v103, v108
	v_lshlrev_b32_e32 v108, 16, v178
	v_add_f32_e32 v108, v96, v108
	v_and_b32_e32 v96, 0xffff0000, v178
	v_add_f32_e32 v109, v97, v96
	v_lshlrev_b32_e32 v96, 16, v179
	v_cvt_pk_bf16_f32 v105, v110, v111
	v_add_f32_e32 v110, v98, v96
	v_and_b32_e32 v96, 0xffff0000, v179
	v_add_f32_e32 v111, v99, v96
	v_mul_f32_e32 v96, v101, v101
	v_mul_f32_e32 v97, v103, v103
	v_fmac_f32_e32 v96, v100, v100
	v_fmac_f32_e32 v97, v102, v102
	v_add_f32_e32 v96, v96, v97
	v_mul_f32_e32 v97, v109, v109
	v_fmac_f32_e32 v97, v108, v108
	v_add_f32_e32 v96, v97, v96
	v_mul_f32_e32 v97, v111, v111
	v_fmac_f32_e32 v97, v110, v110
	v_add_f32_e32 v96, v97, v96
	v_add_f32_e32 v96, v106, v96
	v_mov_b32_e32 v97, v96
	s_nop 1
	v_permlane16_swap_b32_e32 v96, v97
	s_waitcnt lgkmcnt(1)
	v_lshl_add_u64 v[114:115], s[70:71], 0, v[228:229]
	v_lshl_add_u64 v[114:115], v[200:201], 1, v[114:115]
	v_cvt_pk_bf16_f32 v106, v116, v117
	v_cvt_pk_bf16_f32 v107, v118, v107
	s_waitcnt lgkmcnt(0)
	v_add_f32_e32 v96, v96, v97
	v_mov_b32_e32 v97, v96
	s_nop 1
	v_permlane32_swap_b32_e32 v96, v97
	global_store_dwordx4 v[114:115], v[104:107], off
	v_cvt_pk_bf16_f32 v98, v100, v101
	v_cvt_pk_bf16_f32 v99, v102, v103
	v_cvt_pk_bf16_f32 v100, v108, v109
	v_cvt_pk_bf16_f32 v101, v110, v111
	global_store_dwordx4 v[114:115], v[98:101], off offset:256
	s_and_saveexec_b64 s[36:37], s[0:1]
	s_cbranch_execz .LBB0_895
	s_waitcnt lgkmcnt(0)
	v_add_f32_e32 v98, v96, v97
	v_lshlrev_b64 v[96:97], 6, v[222:223]
	v_lshl_add_u64 v[96:97], s[34:35], 0, v[96:97]
	v_lshl_add_u64 v[96:97], s[30:31], 2, v[96:97]
	s_lshl_b32 s8, s49, 2
	v_lshl_add_u64 v[96:97], v[96:97], 0, s[8:9]
	global_store_dword v[96:97], v98, off
.LBB0_895:
	s_or_b64 exec, exec, s[36:37]
	s_waitcnt vmcnt(14)
	v_lshlrev_b32_e32 v98, 16, v172
	v_add_f32_e32 v92, v92, v98
	v_and_b32_e32 v98, 0xffff0000, v172
	v_add_f32_e32 v93, v93, v98
	v_lshlrev_b32_e32 v98, 16, v173
	v_add_f32_e32 v94, v94, v98
	v_and_b32_e32 v98, 0xffff0000, v173
	v_add_f32_e32 v95, v95, v98
	v_lshlrev_b32_e32 v98, 16, v174
	v_add_f32_e32 v98, v88, v98
	v_and_b32_e32 v88, 0xffff0000, v174
	v_add_f32_e32 v99, v89, v88
	v_lshlrev_b32_e32 v88, 16, v175
	v_add_f32_e32 v100, v90, v88
	v_and_b32_e32 v88, 0xffff0000, v175
	v_mul_f32_e32 v90, v93, v93
	v_add_f32_e32 v91, v91, v88
	v_cvt_pk_bf16_f32 v88, v92, v93
	v_fmac_f32_e32 v90, v92, v92
	v_mul_f32_e32 v92, v95, v95
	v_fmac_f32_e32 v92, v94, v94
	v_add_f32_e32 v90, v90, v92
	v_mul_f32_e32 v92, v99, v99
	v_fmac_f32_e32 v92, v98, v98
	v_add_f32_e32 v90, v92, v90
	v_mul_f32_e32 v92, v91, v91
	v_fmac_f32_e32 v92, v100, v100
	v_add_f32_e32 v90, v92, v90
	v_lshlrev_b32_e32 v92, 16, v168
	v_add_f32_e32 v84, v84, v92
	v_and_b32_e32 v92, 0xffff0000, v168
	v_add_f32_e32 v85, v85, v92
	v_lshlrev_b32_e32 v92, 16, v169
	v_add_f32_e32 v86, v86, v92
	v_and_b32_e32 v92, 0xffff0000, v169
	v_add_f32_e32 v87, v87, v92
	v_lshlrev_b32_e32 v92, 16, v170
	v_add_f32_e32 v92, v80, v92
	v_and_b32_e32 v80, 0xffff0000, v170
	v_add_f32_e32 v93, v81, v80
	v_lshlrev_b32_e32 v80, 16, v171
	v_cvt_pk_bf16_f32 v89, v94, v95
	v_add_f32_e32 v94, v82, v80
	v_and_b32_e32 v80, 0xffff0000, v171
	v_add_f32_e32 v95, v83, v80
	v_mul_f32_e32 v80, v85, v85
	v_mul_f32_e32 v81, v87, v87
	v_fmac_f32_e32 v80, v84, v84
	v_fmac_f32_e32 v81, v86, v86
	v_add_f32_e32 v80, v80, v81
	v_mul_f32_e32 v81, v93, v93
	v_fmac_f32_e32 v81, v92, v92
	v_add_f32_e32 v80, v81, v80
	v_mul_f32_e32 v81, v95, v95
	v_fmac_f32_e32 v81, v94, v94
	v_add_f32_e32 v80, v81, v80
	v_add_f32_e32 v80, v90, v80
	v_mov_b32_e32 v81, v80
	s_nop 1
	v_permlane16_swap_b32_e32 v80, v81
	s_waitcnt lgkmcnt(1)
	v_lshl_add_u64 v[96:97], s[70:71], 0, v[224:225]
	v_lshl_add_u64 v[96:97], v[200:201], 1, v[96:97]
	v_cvt_pk_bf16_f32 v90, v98, v99
	v_cvt_pk_bf16_f32 v91, v100, v91
	s_waitcnt lgkmcnt(0)
	v_add_f32_e32 v80, v80, v81
	v_mov_b32_e32 v81, v80
	s_nop 1
	v_permlane32_swap_b32_e32 v80, v81
	global_store_dwordx4 v[96:97], v[88:91], off
	v_cvt_pk_bf16_f32 v82, v84, v85
	v_cvt_pk_bf16_f32 v83, v86, v87
	v_cvt_pk_bf16_f32 v84, v92, v93
	v_cvt_pk_bf16_f32 v85, v94, v95
	global_store_dwordx4 v[96:97], v[82:85], off offset:256
	s_and_saveexec_b64 s[36:37], s[0:1]
	s_cbranch_execz .LBB0_897
	s_waitcnt lgkmcnt(0)
	v_add_f32_e32 v82, v80, v81
	v_lshlrev_b64 v[80:81], 6, v[218:219]
	v_lshl_add_u64 v[80:81], s[34:35], 0, v[80:81]
	v_lshl_add_u64 v[80:81], s[30:31], 2, v[80:81]
	s_lshl_b32 s8, s49, 2
	v_lshl_add_u64 v[80:81], v[80:81], 0, s[8:9]
	global_store_dword v[80:81], v82, off
; __device__ __forceinline__ unsigned cvt_pk_bf16(float lo, float hi) { unsigned r; asm volatile("v_cvt_pk_bf16_f32 %0, %1, %2" : "=v"(r) : "v"(lo), "v"(hi)); return r; }
; __device__ __forceinline__ float bf_lo(unsigned w) { return __uint_as_float(w << 16); }
; __device__ __forceinline__ float bf_hi(unsigned w) { return __uint_as_float(w & 0xffff0000u); }
;     __device__ __forceinline__ void operator()(const f32x4 (&acc)[2][2][4][2], const Unit& u, int wr, int wc, int fr, int fq) const {
;     ...
;         for (int ai = 0; ai < 2; ++ai)
; #pragma unroll
;             for (int m = 0; m < 4; ++m) {
;                 const int row = u.pm * BM + ai * HALF + wr * 64 + m * 16 + fr;
;                 float ss = 0.f;
; #pragma unroll
;                 for (int bj = 0; bj < 2; ++bj) {
;                     bf16_t* xp = X + (size_t)row * 1024 + col0 + bj * HALF;
;                     const u32x4 xv = xin[ai][m][bj];
;                     f32x4 y0 = acc[ai][bj][m][0], y1 = acc[ai][bj][m][1];
;                     y0[0] += bf_lo(xv.x); y0[1] += bf_hi(xv.x); y0[2] += bf_lo(xv.y); y0[3] += bf_hi(xv.y);
;                     y1[0] += bf_lo(xv.z); y1[1] += bf_hi(xv.z); y1[2] += bf_lo(xv.w); y1[3] += bf_hi(xv.w);
;                     if (FINAL) {
;                         float* op = out + (size_t)row * 1024 + col0 + bj * HALF;
;                         __builtin_nontemporal_store(y0, (f32x4*)op); __builtin_nontemporal_store(y1, (f32x4*)(op + 4));
;                     } else {
;                         u32x4 w; w.x = cvt_pk_bf16(y0[0], y0[1]); w.y = cvt_pk_bf16(y0[2], y0[3]); w.z = cvt_pk_bf16(y1[0], y1[1]); w.w = cvt_pk_bf16(y1[2], y1[3]);
;                         *(u32x4*)xp = w;
;                         ss += (y0[0] * y0[0] + y0[1] * y0[1]) + (y0[2] * y0[2] + y0[3] * y0[3]) + (y1[0] * y1[0] + y1[1] * y1[1]) + (y1[2] * y1[2] + y1[3] * y1[3]);
;                     }
;                 }
;                 if (!FINAL) {
;                     ss += __shfl_xor(ss, 16); ss += __shfl_xor(ss, 32);
;                     if (fq == 0) ssq[(size_t)row * 16 + u.pn * 4 + wc] = ss;
;                 }
.LBB0_897:
	s_or_b64 exec, exec, s[36:37]
	s_waitcnt vmcnt(14)
	v_lshlrev_b32_e32 v82, 16, v164
	v_add_f32_e32 v76, v76, v82
	v_and_b32_e32 v82, 0xffff0000, v164
	v_add_f32_e32 v77, v77, v82
	v_lshlrev_b32_e32 v82, 16, v165
	v_add_f32_e32 v78, v78, v82
	v_and_b32_e32 v82, 0xffff0000, v165
	v_add_f32_e32 v79, v79, v82
	v_lshlrev_b32_e32 v82, 16, v166
	v_add_f32_e32 v82, v72, v82
	v_and_b32_e32 v72, 0xffff0000, v166
	v_add_f32_e32 v83, v73, v72
	v_lshlrev_b32_e32 v72, 16, v167
	v_add_f32_e32 v84, v74, v72
	v_and_b32_e32 v72, 0xffff0000, v167
	v_mul_f32_e32 v74, v77, v77
	v_add_f32_e32 v75, v75, v72
	v_cvt_pk_bf16_f32 v72, v76, v77
	v_fmac_f32_e32 v74, v76, v76
	v_mul_f32_e32 v76, v79, v79
	v_fmac_f32_e32 v76, v78, v78
	v_add_f32_e32 v74, v74, v76
	v_mul_f32_e32 v76, v83, v83
	v_fmac_f32_e32 v76, v82, v82
	v_add_f32_e32 v74, v76, v74
	v_mul_f32_e32 v76, v75, v75
	v_fmac_f32_e32 v76, v84, v84
	v_add_f32_e32 v74, v76, v74
	v_lshlrev_b32_e32 v76, 16, v160
	v_add_f32_e32 v68, v68, v76
	v_and_b32_e32 v76, 0xffff0000, v160
	v_add_f32_e32 v69, v69, v76
	v_lshlrev_b32_e32 v76, 16, v161
	v_add_f32_e32 v70, v70, v76
	v_and_b32_e32 v76, 0xffff0000, v161
	v_add_f32_e32 v71, v71, v76
	v_lshlrev_b32_e32 v76, 16, v162
	v_add_f32_e32 v76, v64, v76
	v_and_b32_e32 v64, 0xffff0000, v162
	v_add_f32_e32 v77, v65, v64
	v_lshlrev_b32_e32 v64, 16, v163
	v_cvt_pk_bf16_f32 v73, v78, v79
	v_add_f32_e32 v78, v66, v64
	v_and_b32_e32 v64, 0xffff0000, v163
	v_add_f32_e32 v79, v67, v64
	v_mul_f32_e32 v64, v69, v69
	v_mul_f32_e32 v65, v71, v71
	v_fmac_f32_e32 v64, v68, v68
	v_fmac_f32_e32 v65, v70, v70
	v_add_f32_e32 v64, v64, v65
	v_mul_f32_e32 v65, v77, v77
	v_fmac_f32_e32 v65, v76, v76
	v_add_f32_e32 v64, v65, v64
	v_mul_f32_e32 v65, v79, v79
	v_fmac_f32_e32 v65, v78, v78
	v_add_f32_e32 v64, v65, v64
	v_add_f32_e32 v64, v74, v64
	v_mov_b32_e32 v65, v64
	s_nop 1
	v_permlane16_swap_b32_e32 v64, v65
	s_waitcnt lgkmcnt(1)
	v_lshl_add_u64 v[80:81], s[70:71], 0, v[220:221]
	v_lshl_add_u64 v[80:81], v[200:201], 1, v[80:81]
	v_cvt_pk_bf16_f32 v74, v82, v83
	v_cvt_pk_bf16_f32 v75, v84, v75
	s_waitcnt lgkmcnt(0)
	v_add_f32_e32 v64, v64, v65
	v_mov_b32_e32 v65, v64
	s_nop 1
	v_permlane32_swap_b32_e32 v64, v65
	global_store_dwordx4 v[80:81], v[72:75], off
	v_cvt_pk_bf16_f32 v66, v68, v69
	v_cvt_pk_bf16_f32 v67, v70, v71
	v_cvt_pk_bf16_f32 v68, v76, v77
	v_cvt_pk_bf16_f32 v69, v78, v79
	global_store_dwordx4 v[80:81], v[66:69], off offset:256
	s_and_saveexec_b64 s[36:37], s[0:1]
	s_cbranch_execz .LBB0_899
	s_waitcnt lgkmcnt(0)
	v_add_f32_e32 v66, v64, v65
	v_lshlrev_b64 v[64:65], 6, v[214:215]
	v_lshl_add_u64 v[64:65], s[34:35], 0, v[64:65]
	v_lshl_add_u64 v[64:65], s[30:31], 2, v[64:65]
	s_lshl_b32 s8, s49, 2
	v_lshl_add_u64 v[64:65], v[64:65], 0, s[8:9]
	global_store_dword v[64:65], v66, off
.LBB0_899:
	s_or_b64 exec, exec, s[36:37]
	s_waitcnt vmcnt(14)
	v_lshlrev_b32_e32 v66, 16, v156
	v_add_f32_e32 v60, v60, v66
	v_and_b32_e32 v66, 0xffff0000, v156
	v_add_f32_e32 v61, v61, v66
	v_lshlrev_b32_e32 v66, 16, v157
	v_add_f32_e32 v62, v62, v66
	v_and_b32_e32 v66, 0xffff0000, v157
	v_add_f32_e32 v63, v63, v66
	v_lshlrev_b32_e32 v66, 16, v158
	v_add_f32_e32 v66, v56, v66
	v_and_b32_e32 v56, 0xffff0000, v158
	v_add_f32_e32 v67, v57, v56
	v_lshlrev_b32_e32 v56, 16, v159
	v_add_f32_e32 v68, v58, v56
	v_and_b32_e32 v56, 0xffff0000, v159
	v_mul_f32_e32 v58, v61, v61
	v_add_f32_e32 v59, v59, v56
	v_cvt_pk_bf16_f32 v56, v60, v61
	v_fmac_f32_e32 v58, v60, v60
	v_mul_f32_e32 v60, v63, v63
	v_fmac_f32_e32 v60, v62, v62
	v_add_f32_e32 v58, v58, v60
	v_mul_f32_e32 v60, v67, v67
	v_fmac_f32_e32 v60, v66, v66
	v_add_f32_e32 v58, v60, v58
	v_mul_f32_e32 v60, v59, v59
	v_fmac_f32_e32 v60, v68, v68
	v_add_f32_e32 v58, v60, v58
	v_lshlrev_b32_e32 v60, 16, v152
	v_add_f32_e32 v52, v52, v60
	v_and_b32_e32 v60, 0xffff0000, v152
	v_add_f32_e32 v53, v53, v60
	v_lshlrev_b32_e32 v60, 16, v153
	v_add_f32_e32 v54, v54, v60
	v_and_b32_e32 v60, 0xffff0000, v153
	v_add_f32_e32 v55, v55, v60
	v_lshlrev_b32_e32 v60, 16, v154
	v_add_f32_e32 v60, v48, v60
	v_and_b32_e32 v48, 0xffff0000, v154
	v_add_f32_e32 v61, v49, v48
	v_lshlrev_b32_e32 v48, 16, v155
	v_cvt_pk_bf16_f32 v57, v62, v63
	v_add_f32_e32 v62, v50, v48
	v_and_b32_e32 v48, 0xffff0000, v155
	v_add_f32_e32 v63, v51, v48
	v_mul_f32_e32 v48, v53, v53
	v_mul_f32_e32 v49, v55, v55
	v_fmac_f32_e32 v48, v52, v52
	v_fmac_f32_e32 v49, v54, v54
	v_add_f32_e32 v48, v48, v49
	v_mul_f32_e32 v49, v61, v61
	v_fmac_f32_e32 v49, v60, v60
	v_add_f32_e32 v48, v49, v48
	v_mul_f32_e32 v49, v63, v63
	v_fmac_f32_e32 v49, v62, v62
	v_add_f32_e32 v48, v49, v48
	v_add_f32_e32 v48, v58, v48
	v_mov_b32_e32 v49, v48
	s_nop 1
	v_permlane16_swap_b32_e32 v48, v49
	s_waitcnt lgkmcnt(1)
	v_lshl_add_u64 v[64:65], s[70:71], 0, v[216:217]
	v_lshl_add_u64 v[64:65], v[200:201], 1, v[64:65]
	v_cvt_pk_bf16_f32 v58, v66, v67
	v_cvt_pk_bf16_f32 v59, v68, v59
	s_waitcnt lgkmcnt(0)
	v_add_f32_e32 v48, v48, v49
	v_mov_b32_e32 v49, v48
	s_nop 1
	v_permlane32_swap_b32_e32 v48, v49
	global_store_dwordx4 v[64:65], v[56:59], off
	v_cvt_pk_bf16_f32 v50, v52, v53
	v_cvt_pk_bf16_f32 v51, v54, v55
	v_cvt_pk_bf16_f32 v52, v60, v61
	v_cvt_pk_bf16_f32 v53, v62, v63
	global_store_dwordx4 v[64:65], v[50:53], off offset:256
	s_and_saveexec_b64 s[36:37], s[0:1]
	s_cbranch_execz .LBB0_901
	s_waitcnt lgkmcnt(0)
	v_add_f32_e32 v50, v48, v49
	v_lshlrev_b64 v[48:49], 6, v[210:211]
	v_lshl_add_u64 v[48:49], s[34:35], 0, v[48:49]
	v_lshl_add_u64 v[48:49], s[30:31], 2, v[48:49]
	s_lshl_b32 s8, s49, 2
	v_lshl_add_u64 v[48:49], v[48:49], 0, s[8:9]
	global_store_dword v[48:49], v50, off
; __device__ __forceinline__ unsigned cvt_pk_bf16(float lo, float hi) { unsigned r; asm volatile("v_cvt_pk_bf16_f32 %0, %1, %2" : "=v"(r) : "v"(lo), "v"(hi)); return r; }
; __device__ __forceinline__ float bf_lo(unsigned w) { return __uint_as_float(w << 16); }
; __device__ __forceinline__ float bf_hi(unsigned w) { return __uint_as_float(w & 0xffff0000u); }
;     __device__ __forceinline__ void operator()(const f32x4 (&acc)[2][2][4][2], const Unit& u, int wr, int wc, int fr, int fq) const {
;     ...
;         for (int ai = 0; ai < 2; ++ai)
; #pragma unroll
;             for (int m = 0; m < 4; ++m) {
;                 const int row = u.pm * BM + ai * HALF + wr * 64 + m * 16 + fr;
;                 float ss = 0.f;
; #pragma unroll
;                 for (int bj = 0; bj < 2; ++bj) {
;                     bf16_t* xp = X + (size_t)row * 1024 + col0 + bj * HALF;
;                     const u32x4 xv = xin[ai][m][bj];
;                     f32x4 y0 = acc[ai][bj][m][0], y1 = acc[ai][bj][m][1];
;                     y0[0] += bf_lo(xv.x); y0[1] += bf_hi(xv.x); y0[2] += bf_lo(xv.y); y0[3] += bf_hi(xv.y);
;                     y1[0] += bf_lo(xv.z); y1[1] += bf_hi(xv.z); y1[2] += bf_lo(xv.w); y1[3] += bf_hi(xv.w);
;                     if (FINAL) {
;                         float* op = out + (size_t)row * 1024 + col0 + bj * HALF;
;                         __builtin_nontemporal_store(y0, (f32x4*)op); __builtin_nontemporal_store(y1, (f32x4*)(op + 4));
;                     } else {
;                         u32x4 w; w.x = cvt_pk_bf16(y0[0], y0[1]); w.y = cvt_pk_bf16(y0[2], y0[3]); w.z = cvt_pk_bf16(y1[0], y1[1]); w.w = cvt_pk_bf16(y1[2], y1[3]);
;                         *(u32x4*)xp = w;
;                         ss += (y0[0] * y0[0] + y0[1] * y0[1]) + (y0[2] * y0[2] + y0[3] * y0[3]) + (y1[0] * y1[0] + y1[1] * y1[1]) + (y1[2] * y1[2] + y1[3] * y1[3]);
;                     }
;                 }
;                 if (!FINAL) {
;                     ss += __shfl_xor(ss, 16); ss += __shfl_xor(ss, 32);
;                     if (fq == 0) ssq[(size_t)row * 16 + u.pn * 4 + wc] = ss;
;                 }
.LBB0_901:
	s_or_b64 exec, exec, s[36:37]
	s_waitcnt vmcnt(14)
	v_lshlrev_b32_e32 v50, 16, v148
	v_add_f32_e32 v44, v44, v50
	v_and_b32_e32 v50, 0xffff0000, v148
	v_add_f32_e32 v45, v45, v50
	v_lshlrev_b32_e32 v50, 16, v149
	v_add_f32_e32 v46, v46, v50
	v_and_b32_e32 v50, 0xffff0000, v149
	v_add_f32_e32 v47, v47, v50
	v_lshlrev_b32_e32 v50, 16, v150
	v_add_f32_e32 v50, v40, v50
	v_and_b32_e32 v40, 0xffff0000, v150
	v_add_f32_e32 v51, v41, v40
	v_lshlrev_b32_e32 v40, 16, v151
	v_add_f32_e32 v52, v42, v40
	v_and_b32_e32 v40, 0xffff0000, v151
	v_mul_f32_e32 v42, v45, v45
	v_add_f32_e32 v43, v43, v40
	v_cvt_pk_bf16_f32 v40, v44, v45
	v_fmac_f32_e32 v42, v44, v44
	v_mul_f32_e32 v44, v47, v47
	v_fmac_f32_e32 v44, v46, v46
	v_add_f32_e32 v42, v42, v44
	v_mul_f32_e32 v44, v51, v51
	v_fmac_f32_e32 v44, v50, v50
	v_add_f32_e32 v42, v44, v42
	v_mul_f32_e32 v44, v43, v43
	v_fmac_f32_e32 v44, v52, v52
	v_add_f32_e32 v42, v44, v42
	v_lshlrev_b32_e32 v44, 16, v144
	v_add_f32_e32 v36, v36, v44
	v_and_b32_e32 v44, 0xffff0000, v144
	v_add_f32_e32 v37, v37, v44
	v_lshlrev_b32_e32 v44, 16, v145
	v_add_f32_e32 v38, v38, v44
	v_and_b32_e32 v44, 0xffff0000, v145
	v_add_f32_e32 v39, v39, v44
	v_lshlrev_b32_e32 v44, 16, v146
	v_add_f32_e32 v44, v32, v44
	v_and_b32_e32 v32, 0xffff0000, v146
	v_add_f32_e32 v45, v33, v32
	v_lshlrev_b32_e32 v32, 16, v147
	v_cvt_pk_bf16_f32 v41, v46, v47
	v_add_f32_e32 v46, v34, v32
	v_and_b32_e32 v32, 0xffff0000, v147
	v_add_f32_e32 v47, v35, v32
	v_mul_f32_e32 v32, v37, v37
	v_mul_f32_e32 v33, v39, v39
	v_fmac_f32_e32 v32, v36, v36
	v_fmac_f32_e32 v33, v38, v38
	v_add_f32_e32 v32, v32, v33
	v_mul_f32_e32 v33, v45, v45
	v_fmac_f32_e32 v33, v44, v44
	v_add_f32_e32 v32, v33, v32
	v_mul_f32_e32 v33, v47, v47
	v_fmac_f32_e32 v33, v46, v46
	v_add_f32_e32 v32, v33, v32
	v_add_f32_e32 v32, v42, v32
	v_mov_b32_e32 v33, v32
	s_nop 1
	v_permlane16_swap_b32_e32 v32, v33
	s_waitcnt lgkmcnt(1)
	v_lshl_add_u64 v[48:49], s[70:71], 0, v[212:213]
	v_lshl_add_u64 v[48:49], v[200:201], 1, v[48:49]
	v_cvt_pk_bf16_f32 v42, v50, v51
	v_cvt_pk_bf16_f32 v43, v52, v43
	s_waitcnt lgkmcnt(0)
	v_add_f32_e32 v32, v32, v33
	v_mov_b32_e32 v33, v32
	s_nop 1
	v_permlane32_swap_b32_e32 v32, v33
	global_store_dwordx4 v[48:49], v[40:43], off
	v_cvt_pk_bf16_f32 v34, v36, v37
	v_cvt_pk_bf16_f32 v35, v38, v39
	v_cvt_pk_bf16_f32 v36, v44, v45
	v_cvt_pk_bf16_f32 v37, v46, v47
	global_store_dwordx4 v[48:49], v[34:37], off offset:256
	s_and_saveexec_b64 s[36:37], s[0:1]
	s_cbranch_execz .LBB0_903
	s_waitcnt lgkmcnt(0)
	v_add_f32_e32 v34, v32, v33
	v_lshlrev_b64 v[32:33], 6, v[206:207]
	v_lshl_add_u64 v[32:33], s[34:35], 0, v[32:33]
	v_lshl_add_u64 v[32:33], s[30:31], 2, v[32:33]
	s_lshl_b32 s8, s49, 2
	v_lshl_add_u64 v[32:33], v[32:33], 0, s[8:9]
	global_store_dword v[32:33], v34, off
; __device__ __forceinline__ unsigned cvt_pk_bf16(float lo, float hi) { unsigned r; asm volatile("v_cvt_pk_bf16_f32 %0, %1, %2" : "=v"(r) : "v"(lo), "v"(hi)); return r; }
; __device__ __forceinline__ float bf_lo(unsigned w) { return __uint_as_float(w << 16); }
; __device__ __forceinline__ float bf_hi(unsigned w) { return __uint_as_float(w & 0xffff0000u); }
;     __device__ __forceinline__ void operator()(const f32x4 (&acc)[2][2][4][2], const Unit& u, int wr, int wc, int fr, int fq) const {
;     ...
;         for (int ai = 0; ai < 2; ++ai)
; #pragma unroll
;             for (int m = 0; m < 4; ++m) {
;                 const int row = u.pm * BM + ai * HALF + wr * 64 + m * 16 + fr;
;                 float ss = 0.f;
; #pragma unroll
;                 for (int bj = 0; bj < 2; ++bj) {
;                     bf16_t* xp = X + (size_t)row * 1024 + col0 + bj * HALF;
;                     const u32x4 xv = xin[ai][m][bj];
;                     f32x4 y0 = acc[ai][bj][m][0], y1 = acc[ai][bj][m][1];
;                     y0[0] += bf_lo(xv.x); y0[1] += bf_hi(xv.x); y0[2] += bf_lo(xv.y); y0[3] += bf_hi(xv.y);
;                     y1[0] += bf_lo(xv.z); y1[1] += bf_hi(xv.z); y1[2] += bf_lo(xv.w); y1[3] += bf_hi(xv.w);
;                     if (FINAL) {
;                         float* op = out + (size_t)row * 1024 + col0 + bj * HALF;
;                         __builtin_nontemporal_store(y0, (f32x4*)op); __builtin_nontemporal_store(y1, (f32x4*)(op + 4));
;                     } else {
;                         u32x4 w; w.x = cvt_pk_bf16(y0[0], y0[1]); w.y = cvt_pk_bf16(y0[2], y0[3]); w.z = cvt_pk_bf16(y1[0], y1[1]); w.w = cvt_pk_bf16(y1[2], y1[3]);
;                         *(u32x4*)xp = w;
;                         ss += (y0[0] * y0[0] + y0[1] * y0[1]) + (y0[2] * y0[2] + y0[3] * y0[3]) + (y1[0] * y1[0] + y1[1] * y1[1]) + (y1[2] * y1[2] + y1[3] * y1[3]);
;                     }
;                 }
;                 if (!FINAL) {
;                     ss += __shfl_xor(ss, 16); ss += __shfl_xor(ss, 32);
;                     if (fq == 0) ssq[(size_t)row * 16 + u.pn * 4 + wc] = ss;
;                 }
.LBB0_903:
	s_or_b64 exec, exec, s[36:37]
	s_waitcnt vmcnt(14)
	v_lshlrev_b32_e32 v34, 16, v140
	v_add_f32_e32 v28, v28, v34
	v_and_b32_e32 v34, 0xffff0000, v140
	v_add_f32_e32 v29, v29, v34
	v_lshlrev_b32_e32 v34, 16, v141
	v_add_f32_e32 v30, v30, v34
	v_and_b32_e32 v34, 0xffff0000, v141
	v_add_f32_e32 v31, v31, v34
	v_lshlrev_b32_e32 v34, 16, v142
	v_add_f32_e32 v34, v24, v34
	v_and_b32_e32 v24, 0xffff0000, v142
	v_add_f32_e32 v35, v25, v24
	v_lshlrev_b32_e32 v24, 16, v143
	v_add_f32_e32 v36, v26, v24
	v_and_b32_e32 v24, 0xffff0000, v143
	v_mul_f32_e32 v26, v29, v29
	v_add_f32_e32 v27, v27, v24
	v_cvt_pk_bf16_f32 v24, v28, v29
	v_fmac_f32_e32 v26, v28, v28
	v_mul_f32_e32 v28, v31, v31
	v_fmac_f32_e32 v28, v30, v30
	v_add_f32_e32 v26, v26, v28
	v_mul_f32_e32 v28, v35, v35
	v_fmac_f32_e32 v28, v34, v34
	v_add_f32_e32 v26, v28, v26
	v_mul_f32_e32 v28, v27, v27
	v_fmac_f32_e32 v28, v36, v36
	v_add_f32_e32 v26, v28, v26
	v_lshlrev_b32_e32 v28, 16, v136
	v_add_f32_e32 v20, v20, v28
	v_and_b32_e32 v28, 0xffff0000, v136
	v_add_f32_e32 v21, v21, v28
	v_lshlrev_b32_e32 v28, 16, v137
	v_add_f32_e32 v22, v22, v28
	v_and_b32_e32 v28, 0xffff0000, v137
	v_add_f32_e32 v23, v23, v28
	v_lshlrev_b32_e32 v28, 16, v138
	v_add_f32_e32 v28, v16, v28
	v_and_b32_e32 v16, 0xffff0000, v138
	v_add_f32_e32 v29, v17, v16
	v_lshlrev_b32_e32 v16, 16, v139
	v_cvt_pk_bf16_f32 v25, v30, v31
	v_add_f32_e32 v30, v18, v16
	v_and_b32_e32 v16, 0xffff0000, v139
	v_add_f32_e32 v31, v19, v16
	v_mul_f32_e32 v16, v21, v21
	v_mul_f32_e32 v17, v23, v23
	v_fmac_f32_e32 v16, v20, v20
	v_fmac_f32_e32 v17, v22, v22
	v_add_f32_e32 v16, v16, v17
	v_mul_f32_e32 v17, v29, v29
	v_fmac_f32_e32 v17, v28, v28
	v_add_f32_e32 v16, v17, v16
	v_mul_f32_e32 v17, v31, v31
	v_fmac_f32_e32 v17, v30, v30
	v_add_f32_e32 v16, v17, v16
	v_add_f32_e32 v16, v26, v16
	v_mov_b32_e32 v17, v16
	s_nop 1
	v_permlane16_swap_b32_e32 v16, v17
	s_waitcnt lgkmcnt(1)
	v_lshl_add_u64 v[32:33], s[70:71], 0, v[208:209]
	v_lshl_add_u64 v[32:33], v[200:201], 1, v[32:33]
	v_cvt_pk_bf16_f32 v26, v34, v35
	v_cvt_pk_bf16_f32 v27, v36, v27
	s_waitcnt lgkmcnt(0)
	v_add_f32_e32 v16, v16, v17
	v_mov_b32_e32 v17, v16
	s_nop 1
	v_permlane32_swap_b32_e32 v16, v17
	global_store_dwordx4 v[32:33], v[24:27], off
	v_cvt_pk_bf16_f32 v18, v20, v21
	v_cvt_pk_bf16_f32 v19, v22, v23
	v_cvt_pk_bf16_f32 v20, v28, v29
	v_cvt_pk_bf16_f32 v21, v30, v31
	global_store_dwordx4 v[32:33], v[18:21], off offset:256
	s_and_saveexec_b64 s[36:37], s[0:1]
	s_cbranch_execz .LBB0_905
	s_waitcnt lgkmcnt(0)
	v_add_f32_e32 v18, v16, v17
	v_lshlrev_b64 v[16:17], 6, v[202:203]
	v_lshl_add_u64 v[16:17], s[34:35], 0, v[16:17]
	v_lshl_add_u64 v[16:17], s[30:31], 2, v[16:17]
	s_lshl_b32 s8, s49, 2
	v_lshl_add_u64 v[16:17], v[16:17], 0, s[8:9]
	global_store_dword v[16:17], v18, off
.LBB0_905:
	s_or_b64 exec, exec, s[36:37]
	s_waitcnt vmcnt(14)
	v_lshlrev_b32_e32 v18, 16, v132
	v_add_f32_e32 v12, v12, v18
	v_and_b32_e32 v18, 0xffff0000, v132
	v_add_f32_e32 v13, v13, v18
	v_lshlrev_b32_e32 v18, 16, v133
	v_add_f32_e32 v14, v14, v18
	v_and_b32_e32 v18, 0xffff0000, v133
	v_add_f32_e32 v15, v15, v18
	v_lshlrev_b32_e32 v18, 16, v134
	v_add_f32_e32 v18, v8, v18
	v_and_b32_e32 v8, 0xffff0000, v134
	v_add_f32_e32 v19, v9, v8
	v_lshlrev_b32_e32 v8, 16, v135
	v_add_f32_e32 v20, v10, v8
	v_and_b32_e32 v8, 0xffff0000, v135
	v_mul_f32_e32 v10, v13, v13
	v_add_f32_e32 v11, v11, v8
	v_cvt_pk_bf16_f32 v8, v12, v13
	v_fmac_f32_e32 v10, v12, v12
	v_mul_f32_e32 v12, v15, v15
	v_fmac_f32_e32 v12, v14, v14
	v_add_f32_e32 v10, v10, v12
	v_mul_f32_e32 v12, v19, v19
	v_fmac_f32_e32 v12, v18, v18
	v_add_f32_e32 v10, v12, v10
	v_mul_f32_e32 v12, v11, v11
	v_fmac_f32_e32 v12, v20, v20
	v_add_f32_e32 v10, v12, v10
	v_lshlrev_b32_e32 v12, 16, v124
	v_add_f32_e32 v4, v4, v12
	v_and_b32_e32 v12, 0xffff0000, v124
	v_add_f32_e32 v5, v5, v12
	v_lshlrev_b32_e32 v12, 16, v125
	v_add_f32_e32 v6, v6, v12
	v_and_b32_e32 v12, 0xffff0000, v125
	v_add_f32_e32 v7, v7, v12
	v_lshlrev_b32_e32 v12, 16, v126
	v_add_f32_e32 v12, v0, v12
	v_and_b32_e32 v0, 0xffff0000, v126
	v_add_f32_e32 v13, v1, v0
	v_lshlrev_b32_e32 v0, 16, v127
	v_cvt_pk_bf16_f32 v9, v14, v15
	v_add_f32_e32 v14, v2, v0
	v_and_b32_e32 v0, 0xffff0000, v127
	v_add_f32_e32 v15, v3, v0
	v_mul_f32_e32 v0, v5, v5
	v_mul_f32_e32 v1, v7, v7
	v_fmac_f32_e32 v0, v4, v4
	v_fmac_f32_e32 v1, v6, v6
	v_add_f32_e32 v0, v0, v1
	v_mul_f32_e32 v1, v13, v13
	v_fmac_f32_e32 v1, v12, v12
	v_add_f32_e32 v0, v1, v0
	v_mul_f32_e32 v1, v15, v15
	v_fmac_f32_e32 v1, v14, v14
	v_add_f32_e32 v0, v1, v0
	v_add_f32_e32 v0, v10, v0
	v_mov_b32_e32 v1, v0
	s_nop 1
	v_permlane16_swap_b32_e32 v0, v1
	s_waitcnt lgkmcnt(1)
	v_lshl_add_u64 v[16:17], s[70:71], 0, v[204:205]
	v_lshl_add_u64 v[16:17], v[200:201], 1, v[16:17]
	v_cvt_pk_bf16_f32 v10, v18, v19
	v_cvt_pk_bf16_f32 v11, v20, v11
	s_waitcnt lgkmcnt(0)
	v_add_f32_e32 v0, v0, v1
	v_mov_b32_e32 v1, v0
	s_nop 1
	v_permlane32_swap_b32_e32 v0, v1
	global_store_dwordx4 v[16:17], v[8:11], off
	v_cvt_pk_bf16_f32 v2, v4, v5
	v_cvt_pk_bf16_f32 v3, v6, v7
	v_cvt_pk_bf16_f32 v4, v12, v13
	v_cvt_pk_bf16_f32 v5, v14, v15
	global_store_dwordx4 v[16:17], v[2:5], off offset:256
	s_and_saveexec_b64 s[36:37], s[0:1]
	s_cbranch_execz .LBB0_907
	s_waitcnt lgkmcnt(0)
	v_add_f32_e32 v2, v0, v1
	v_lshlrev_b64 v[0:1], 6, v[198:199]
	v_lshl_add_u64 v[0:1], s[34:35], 0, v[0:1]
	v_lshl_add_u64 v[0:1], s[30:31], 2, v[0:1]
	s_lshl_b32 s8, s49, 2
	v_lshl_add_u64 v[0:1], v[0:1], 0, s[8:9]
	global_store_dword v[0:1], v2, off

; __device__ __forceinline__ void rows_rstd(const float* ssq, int row0, int fq, float (&rs)[2][4]) {
;     f32x4 pr[2][4];
; #pragma unroll
;     for (int ai = 0; ai < 2; ++ai)
; #pragma unroll
;         for (int m = 0; m < 4; ++m) pr[ai][m] = *(const f32x4*)(ssq + (size_t)(row0 + ai * HALF + m * 16) * 16 + 4 * fq);
; #pragma unroll
;     for (int ai = 0; ai < 2; ++ai)
; #pragma unroll
;         for (int m = 0; m < 4; ++m) { float t = (pr[ai][m][0] + pr[ai][m][1]) + (pr[ai][m][2] + pr[ai][m][3]); t += __shfl_xor(t, 16); t += __shfl_xor(t, 32); rs[ai][m] = __builtin_amdgcn_rsqf(t * (1.0f / 1024.0f) + 1e-6f); }
; }
;     __device__ __forceinline__ void operator()(const f32x4 (&acc)[2][2][4][2], const Unit& u, int wr, int wc, int fr, int fq) const {
;         const int col0 = u.pn * HALF + wc * 32 + 8 * fq;
;         float rsv[2][4]; rows_rstd(ssq, u.pm * BM + wr * 64 + fr, fq, rsv);
.LBB0_980:
	v_mbcnt_lo_u32_b32 v252, -1, 0
	v_mbcnt_hi_u32_b32 v252, -1, v252
	v_and_b32_e32 v252, 48, v252
	v_lshl_add_u32 v252, v149, 6, v252
	v_add_u32_e32 v252, 0x20000, v252
	v_lshl_add_u32 v170, s30, 8, v149
	v_ashrrev_i32_e32 v171, 31, v170
	v_or_b32_e32 v166, 16, v170
	v_lshlrev_b64 v[144:145], 6, v[170:171]
	v_ashrrev_i32_e32 v167, 31, v166
	v_or_b32_e32 v162, 32, v170
	v_lshl_add_u64 v[144:145], v[136:137], 0, v[144:145]
	v_lshlrev_b64 v[146:147], 6, v[166:167]
	v_ashrrev_i32_e32 v163, 31, v162
	v_or_b32_e32 v158, 48, v170
	v_lshl_add_u64 v[146:147], v[136:137], 0, v[146:147]
	ds_read_b128 v[178:181], v252 offset:0
	ds_read_b128 v[182:185], v252 offset:1024
	v_lshlrev_b64 v[144:145], 6, v[162:163]
	v_ashrrev_i32_e32 v159, 31, v158
	v_add_u32_e32 v154, 0x80, v170
	v_lshl_add_u64 v[144:145], v[136:137], 0, v[144:145]
	v_lshlrev_b64 v[146:147], 6, v[158:159]
	v_ashrrev_i32_e32 v155, 31, v154
	v_lshl_add_u64 v[146:147], v[136:137], 0, v[146:147]
	ds_read_b128 v[186:189], v252 offset:2048
	ds_read_b128 v[190:193], v252 offset:3072
	v_lshlrev_b64 v[144:145], 6, v[154:155]
	v_lshl_add_u64 v[144:145], v[136:137], 0, v[144:145]
	ds_read_b128 v[194:197], v252 offset:8192
	v_add_u32_e32 v150, 0x90, v170
	v_ashrrev_i32_e32 v151, 31, v150
	v_lshlrev_b64 v[144:145], 6, v[150:151]
	v_add_u32_e32 v146, 0xa0, v170
	v_lshl_add_u64 v[144:145], v[136:137], 0, v[144:145]
	v_ashrrev_i32_e32 v147, 31, v146
	ds_read_b128 v[198:201], v252 offset:9216
	v_lshlrev_b64 v[144:145], 6, v[146:147]
	v_lshl_add_u64 v[144:145], v[136:137], 0, v[144:145]
	ds_read_b128 v[202:205], v252 offset:10240
	v_add_u32_e32 v144, 0xb0, v170
	v_ashrrev_i32_e32 v145, 31, v144
	v_lshlrev_b64 v[206:207], 6, v[144:145]
	v_lshl_add_u64 v[206:207], v[136:137], 0, v[206:207]
	ds_read_b128 v[206:209], v252 offset:11264
	v_and_b32_e32 v147, 64, v175
	v_xor_b32_e32 v145, 16, v175
	v_add_u32_e32 v147, 64, v147
	v_xor_b32_e32 v148, 32, v175
	v_cmp_lt_i32_e32 vcc, v145, v147
	v_lshl_or_b32 v172, s28, 7, v157
	v_ashrrev_i32_e32 v173, 31, v172
	v_cndmask_b32_e32 v145, v175, v145, vcc
	v_cmp_lt_i32_e32 vcc, v148, v147
	v_lshlrev_b32_e32 v145, 2, v145
	s_waitcnt lgkmcnt(0)
	v_mov_b32_e32 v210, v179
	v_mov_b32_e32 v211, v180
	v_mov_b32_e32 v179, v181
	v_pk_add_f32 v[178:179], v[210:211], v[178:179]
	v_mov_b32_e32 v180, v183
	v_mov_b32_e32 v181, v184
	v_mov_b32_e32 v183, v185
	v_cndmask_b32_e32 v147, v175, v148, vcc
	v_mov_b32_e32 v184, v187
	v_mov_b32_e32 v185, v188
	v_mov_b32_e32 v187, v189
	v_mov_b32_e32 v188, v191
	v_mov_b32_e32 v189, v192
	v_mov_b32_e32 v191, v193
	v_add_f32_e32 v148, v178, v179
	v_pk_add_f32 v[178:179], v[180:181], v[182:183]
	v_pk_add_f32 v[180:181], v[184:185], v[186:187]
	v_pk_add_f32 v[182:183], v[188:189], v[190:191]
	v_mov_b32_e32 v192, v195
	v_mov_b32_e32 v193, v196
	v_mov_b32_e32 v195, v197
	v_mov_b32_e32 v151, v148
	s_nop 1
	v_permlane16_swap_b32_e32 v148, v151
	v_add_f32_e32 v152, v178, v179
	v_add_f32_e32 v155, v180, v181
	v_add_f32_e32 v156, v182, v183
	v_pk_add_f32 v[184:185], v[192:193], v[194:195]
	v_mov_b32_e32 v160, v152
	s_nop 1
	v_permlane16_swap_b32_e32 v152, v160
	v_mov_b32_e32 v163, v155
	s_nop 1
	v_permlane16_swap_b32_e32 v155, v163
	v_mov_b32_e32 v164, v156
	s_nop 1
	v_permlane16_swap_b32_e32 v156, v164
	v_add_f32_e32 v159, v184, v185
	v_mov_b32_e32 v167, v159
	s_nop 1
	v_permlane16_swap_b32_e32 v159, v167
	v_lshlrev_b32_e32 v147, 2, v147
	s_waitcnt lgkmcnt(4)
	v_add_f32_e32 v148, v148, v151
	v_mov_b32_e32 v151, v148
	s_nop 1
	v_permlane32_swap_b32_e32 v148, v151
	s_waitcnt lgkmcnt(4)
	v_add_f32_e32 v152, v152, v160
	s_waitcnt lgkmcnt(3)
	v_add_f32_e32 v155, v155, v163
	s_waitcnt lgkmcnt(2)
	v_add_f32_e32 v156, v156, v164
	v_mov_b32_e32 v160, v152
	s_nop 1
	v_permlane32_swap_b32_e32 v152, v160
	v_mov_b32_e32 v163, v155
	s_nop 1
	v_permlane32_swap_b32_e32 v155, v163
	v_mov_b32_e32 v164, v156
	s_nop 1
	v_permlane32_swap_b32_e32 v156, v164
	s_waitcnt lgkmcnt(4)
	v_add_f32_e32 v159, v159, v167
	v_mov_b32_e32 v167, v159
	s_nop 1
	v_permlane32_swap_b32_e32 v159, v167
	s_waitcnt lgkmcnt(4)
	v_add_f32_e32 v148, v148, v151
	v_fmamk_f32 v148, v148, 0x3a800000, v176
	s_waitcnt lgkmcnt(3)
	v_add_f32_e32 v151, v152, v160
	s_waitcnt lgkmcnt(2)
	v_add_f32_e32 v152, v155, v163
	s_waitcnt lgkmcnt(1)
	v_add_f32_e32 v155, v156, v164
	v_mov_b32_e32 v180, v199
	v_mov_b32_e32 v181, v200
	v_mov_b32_e32 v199, v201
	v_rsq_f32_e32 v178, v148
	v_fmamk_f32 v148, v151, 0x3a800000, v176
	v_fmamk_f32 v151, v152, 0x3a800000, v176
	v_fmamk_f32 v152, v155, 0x3a800000, v176
	v_pk_add_f32 v[180:181], v[180:181], v[198:199]
	v_rsq_f32_e32 v174, v148
	v_add_f32_e32 v148, v180, v181
	v_rsq_f32_e32 v164, v152
	s_waitcnt lgkmcnt(0)
	v_add_f32_e32 v152, v159, v167
	v_mov_b32_e32 v180, v203
	v_mov_b32_e32 v181, v204
	v_mov_b32_e32 v203, v205
	v_fmamk_f32 v152, v152, 0x3a800000, v176
	v_pk_add_f32 v[180:181], v[180:181], v[202:203]
	v_rsq_f32_e32 v160, v152
	v_add_f32_e32 v152, v180, v181
	v_mov_b32_e32 v180, v207
	v_mov_b32_e32 v181, v208
	v_mov_b32_e32 v207, v209
	v_pk_add_f32 v[180:181], v[180:181], v[206:207]
	v_rsq_f32_e32 v168, v151
	v_add_f32_e32 v156, v180, v181
	v_mul_f32_e32 v180, v124, v178
	v_mul_f32_e32 v181, v120, v178
	v_mov_b32_e32 v151, v148
	s_nop 1
	v_permlane16_swap_b32_e32 v148, v151
	v_mul_f32_e32 v120, 0xbfb8aa3b, v180
	v_exp_f32_e32 v124, v120
	v_mul_f32_e32 v120, v125, v178
	v_mul_f32_e32 v121, v121, v178
	s_waitcnt lgkmcnt(0)
	v_add_f32_e32 v148, v148, v151
	v_mul_f32_e32 v125, 0xbfb8aa3b, v120
	v_exp_f32_e32 v125, v125
	v_mov_b32_e32 v151, v148
	s_nop 1
	v_permlane32_swap_b32_e32 v148, v151
	v_mov_b32_e32 v155, v152
	s_nop 1
	v_permlane16_swap_b32_e32 v152, v155
	v_mov_b32_e32 v145, v156
	s_nop 1
	v_permlane16_swap_b32_e32 v156, v145
	v_add_f32_e32 v125, 1.0, v125
	v_rcp_f32_e32 v125, v125
	v_mul_f32_e32 v120, v120, v121
	s_waitcnt lgkmcnt(2)
; __device__ __forceinline__ unsigned cvt_pk_bf16(float lo, float hi) { unsigned r; asm volatile("v_cvt_pk_bf16_f32 %0, %1, %2" : "=v"(r) : "v"(lo), "v"(hi)); return r; }
; __device__ __forceinline__ float fast_sigmoid(float x) { return __builtin_amdgcn_rcpf(1.0f + __expf(-x)); }
; __device__ __forceinline__ void rows_rstd(const float* ssq, int row0, int fq, float (&rs)[2][4]) {
;     ...
;     for (int ai = 0; ai < 2; ++ai)
; #pragma unroll
;         for (int m = 0; m < 4; ++m) { float t = (pr[ai][m][0] + pr[ai][m][1]) + (pr[ai][m][2] + pr[ai][m][3]); t += __shfl_xor(t, 16); t += __shfl_xor(t, 32); rs[ai][m] = __builtin_amdgcn_rsqf(t * (1.0f / 1024.0f) + 1e-6f); }
;     __device__ __forceinline__ void operator()(const f32x4 (&acc)[2][2][4][2], const Unit& u, int wr, int wc, int fr, int fq) const {
;     ...
;         for (int ai = 0; ai < 2; ++ai)
; #pragma unroll
;             for (int m = 0; m < 4; ++m) {
;                 const int row = u.pm * BM + ai * HALF + wr * 64 + m * 16 + fr;
;                 const float rs = rsv[ai][m];
;                 float h[8];
; #pragma unroll
;                 for (int n = 0; n < 2; ++n)
; #pragma unroll
;                     for (int i = 0; i < 4; ++i) { const float g = acc[ai][0][m][n][i] * rs, up = acc[ai][1][m][n][i] * rs; h[4 * n + i] = g * up * fast_sigmoid(g); }
;                 u32x4 w; w.x = cvt_pk_bf16(h[0], h[1]); w.y = cvt_pk_bf16(h[2], h[3]); w.z = cvt_pk_bf16(h[4], h[5]); w.w = cvt_pk_bf16(h[6], h[7]);
;                 *(u32x4*)(H + (size_t)row * 2816 + col0) = w;
	v_add_f32_e32 v148, v148, v151
	s_waitcnt lgkmcnt(1)
	v_add_f32_e32 v151, v152, v155
	s_waitcnt lgkmcnt(0)
	v_add_f32_e32 v145, v156, v145
	v_mul_f32_e32 v125, v120, v125
	v_mov_b32_e32 v152, v151
	s_nop 1
	v_permlane32_swap_b32_e32 v151, v152
	v_mov_b32_e32 v147, v145
	s_nop 1
	v_permlane32_swap_b32_e32 v145, v147
	v_mul_f32_e32 v120, v126, v178
	v_mul_f32_e32 v121, v122, v178
	v_add_f32_e32 v124, 1.0, v124
	v_mul_f32_e32 v122, 0xbfb8aa3b, v120
	v_exp_f32_e32 v126, v122
	v_mul_f32_e32 v122, v127, v178
	v_mul_f32_e32 v123, v123, v178
	v_fmamk_f32 v148, v148, 0x3a800000, v176
	v_rcp_f32_e32 v124, v124
	v_mul_f32_e32 v127, 0xbfb8aa3b, v122
	v_rsq_f32_e32 v156, v148
	s_waitcnt lgkmcnt(1)
	v_add_f32_e32 v148, v151, v152
	s_waitcnt lgkmcnt(0)
	v_add_f32_e32 v145, v145, v147
	v_exp_f32_e32 v127, v127
	v_fmamk_f32 v148, v148, 0x3a800000, v176
	v_fmamk_f32 v145, v145, 0x3a800000, v176
	v_rsq_f32_e32 v152, v148
	v_rsq_f32_e32 v148, v145
	v_mul_f32_e32 v145, v180, v181
	v_mul_f32_e32 v124, v145, v124
	v_mul_f32_e32 v145, v120, v121
	v_add_f32_e32 v120, 1.0, v126
	v_rcp_f32_e32 v126, v120
	v_add_f32_e32 v120, 1.0, v127
	v_rcp_f32_e32 v127, v120
	v_mul_f32_e32 v120, v116, v178
	v_mul_f32_e32 v121, v112, v178
	v_mul_f32_e32 v116, v122, v123
	v_mul_f32_e32 v112, 0xbfb8aa3b, v120
	v_exp_f32_e32 v112, v112
	v_mul_f32_e32 v122, v116, v127
	v_mul_f32_e32 v120, v120, v121
	v_mul_f32_e32 v126, v145, v126
	v_add_f32_e32 v112, 1.0, v112
	v_rcp_f32_e32 v116, v112
	v_mul_f32_e32 v112, v117, v178
	v_mul_f32_e32 v113, v113, v178
	v_mov_b32_e32 v123, v104
	v_mul_f32_e32 v117, 0xbfb8aa3b, v112
	v_exp_f32_e32 v117, v117
	v_mul_f32_e32 v120, v120, v116
	v_mul_f32_e32 v116, v112, v113
	v_add_f32_e32 v112, 1.0, v117
	v_rcp_f32_e32 v117, v112
	v_mul_f32_e32 v112, v118, v178
	v_mul_f32_e32 v113, v114, v178
	s_andn2_b64 vcc, exec, s[22:23]
	v_mul_f32_e32 v114, 0xbfb8aa3b, v112
	v_exp_f32_e32 v118, v114
	v_mul_f32_e32 v114, v119, v178
	v_mul_f32_e32 v115, v115, v178
	v_mul_f32_e32 v121, v116, v117
	v_mul_f32_e32 v119, 0xbfb8aa3b, v114
	v_exp_f32_e32 v119, v119
	v_add_f32_e32 v116, 1.0, v118
	v_rcp_f32_e32 v116, v116
	v_mul_f32_e32 v112, v112, v113
	v_add_f32_e32 v117, 1.0, v119
	v_rcp_f32_e32 v117, v117
	v_mul_f32_e32 v113, v114, v115
	v_mul_f32_e32 v112, v112, v116
	v_cvt_pk_bf16_f32 v116, v124, v125
	v_mul_f32_e32 v113, v113, v117
	v_cvt_pk_bf16_f32 v117, v126, v122
	v_mul_f32_e32 v122, v108, v174
	v_mul_f32_e32 v123, v123, v174
	v_cvt_pk_bf16_f32 v118, v120, v121
	v_cvt_pk_bf16_f32 v119, v112, v113
	v_mov_b64_e32 v[112:113], s[6:7]
	v_mul_f32_e32 v104, 0xbfb8aa3b, v122
	v_exp_f32_e32 v108, v104
	v_mul_f32_e32 v104, v109, v174
	v_mul_f32_e32 v105, v105, v174
	v_mad_i64_i32 v[120:121], s[34:35], v170, s52, v[112:113]
	v_mul_f32_e32 v109, 0xbfb8aa3b, v104
	v_exp_f32_e32 v109, v109
	v_mul_f32_e32 v104, v104, v105
	v_mov_b32_e32 v105, v106
	v_add_f32_e32 v108, 1.0, v108
	v_add_f32_e32 v109, 1.0, v109
	v_rcp_f32_e32 v109, v109
	v_rcp_f32_e32 v108, v108
	v_lshlrev_b64 v[114:115], 1, v[172:173]
	v_lshl_add_u64 v[120:121], v[120:121], 0, v[114:115]
	v_mul_f32_e32 v109, v104, v109
	v_mul_f32_e32 v104, v110, v174
	v_mul_f32_e32 v105, v105, v174
	global_store_dwordx4 v[120:121], v[116:119], off
	v_mul_f32_e32 v106, 0xbfb8aa3b, v104
	v_exp_f32_e32 v110, v106
	v_mul_f32_e32 v106, v111, v174
	v_mul_f32_e32 v107, v107, v174
	v_mul_f32_e32 v116, v122, v123
	v_mul_f32_e32 v111, 0xbfb8aa3b, v106
	v_exp_f32_e32 v111, v111
	v_mul_f32_e32 v108, v116, v108
	v_mul_f32_e32 v116, v104, v105
	v_add_f32_e32 v104, 1.0, v110
	v_rcp_f32_e32 v110, v104
	v_add_f32_e32 v104, 1.0, v111
	v_rcp_f32_e32 v111, v104
	v_mul_f32_e32 v104, v100, v174
	v_mul_f32_e32 v105, v96, v174
	v_mul_f32_e32 v106, v106, v107
	v_mul_f32_e32 v96, 0xbfb8aa3b, v104
	v_exp_f32_e32 v96, v96
	v_mul_f32_e32 v104, v104, v105
	v_mul_f32_e32 v100, v116, v110
	v_mul_f32_e32 v106, v106, v111
	v_add_f32_e32 v96, 1.0, v96
	v_rcp_f32_e32 v107, v96
	v_mul_f32_e32 v96, v101, v174
	v_mul_f32_e32 v97, v97, v174
	s_mov_b64 s[22:23], -1
	v_mul_f32_e32 v101, 0xbfb8aa3b, v96
	v_exp_f32_e32 v101, v101
	v_mul_f32_e32 v105, v96, v97
	v_mov_b32_e32 v97, v98
	v_mul_f32_e32 v104, v104, v107
	v_add_f32_e32 v96, 1.0, v101
	v_rcp_f32_e32 v101, v96
	v_mul_f32_e32 v96, v102, v174
	v_mul_f32_e32 v97, v97, v174
	v_mul_f32_e32 v101, v105, v101
	v_mul_f32_e32 v98, 0xbfb8aa3b, v96
	v_exp_f32_e32 v102, v98
	v_mul_f32_e32 v98, v103, v174
	v_mul_f32_e32 v99, v99, v174
	v_mul_f32_e32 v96, v96, v97
	v_mul_f32_e32 v103, 0xbfb8aa3b, v98
	v_exp_f32_e32 v103, v103
	v_add_f32_e32 v102, 1.0, v102
	v_rcp_f32_e32 v102, v102
	v_add_f32_e32 v103, 1.0, v103
	v_rcp_f32_e32 v103, v103
	v_mul_f32_e32 v102, v96, v102
	v_mul_f32_e32 v96, v98, v99
	v_mul_f32_e32 v99, v96, v103
	v_cvt_pk_bf16_f32 v96, v108, v109
	v_cvt_pk_bf16_f32 v97, v100, v106
	v_cvt_pk_bf16_f32 v98, v104, v101
	v_cvt_pk_bf16_f32 v99, v102, v99
	v_mul_f32_e32 v102, v92, v168
	v_mul_f32_e32 v103, v88, v168
	v_mad_i64_i32 v[100:101], s[34:35], v166, s52, v[112:113]
	v_mul_f32_e32 v88, 0xbfb8aa3b, v102
	v_exp_f32_e32 v92, v88
	v_mul_f32_e32 v88, v93, v168
	v_mul_f32_e32 v89, v89, v168
	v_lshl_add_u64 v[100:101], v[100:101], 0, v[114:115]
	v_mul_f32_e32 v93, 0xbfb8aa3b, v88
	v_exp_f32_e32 v93, v93
	v_mul_f32_e32 v88, v88, v89
	v_mov_b32_e32 v89, v90
	v_add_f32_e32 v92, 1.0, v92
	v_add_f32_e32 v93, 1.0, v93
	v_rcp_f32_e32 v93, v93
	v_rcp_f32_e32 v92, v92
	global_store_dwordx4 v[100:101], v[96:99], off
	v_mul_f32_e32 v93, v88, v93
	v_mul_f32_e32 v88, v94, v168
	v_mul_f32_e32 v89, v89, v168
	v_mul_f32_e32 v96, v102, v103
	v_mul_f32_e32 v90, 0xbfb8aa3b, v88
	v_exp_f32_e32 v94, v90
	v_mul_f32_e32 v90, v95, v168
; __device__ __forceinline__ unsigned cvt_pk_bf16(float lo, float hi) { unsigned r; asm volatile("v_cvt_pk_bf16_f32 %0, %1, %2" : "=v"(r) : "v"(lo), "v"(hi)); return r; }
; __device__ __forceinline__ float fast_sigmoid(float x) { return __builtin_amdgcn_rcpf(1.0f + __expf(-x)); }
;     __device__ __forceinline__ void operator()(const f32x4 (&acc)[2][2][4][2], const Unit& u, int wr, int wc, int fr, int fq) const {
;     ...
;         for (int ai = 0; ai < 2; ++ai)
; #pragma unroll
;             for (int m = 0; m < 4; ++m) {
;                 const int row = u.pm * BM + ai * HALF + wr * 64 + m * 16 + fr;
;                 const float rs = rsv[ai][m];
;                 float h[8];
; #pragma unroll
;                 for (int n = 0; n < 2; ++n)
; #pragma unroll
;                     for (int i = 0; i < 4; ++i) { const float g = acc[ai][0][m][n][i] * rs, up = acc[ai][1][m][n][i] * rs; h[4 * n + i] = g * up * fast_sigmoid(g); }
;                 u32x4 w; w.x = cvt_pk_bf16(h[0], h[1]); w.y = cvt_pk_bf16(h[2], h[3]); w.z = cvt_pk_bf16(h[4], h[5]); w.w = cvt_pk_bf16(h[6], h[7]);
;                 *(u32x4*)(H + (size_t)row * 2816 + col0) = w;
	v_mul_f32_e32 v91, v91, v168
	v_mul_f32_e32 v92, v96, v92
	v_mul_f32_e32 v95, 0xbfb8aa3b, v90
	v_exp_f32_e32 v95, v95
	v_mul_f32_e32 v96, v88, v89
	v_add_f32_e32 v88, 1.0, v94
	v_rcp_f32_e32 v94, v88
	v_add_f32_e32 v88, 1.0, v95
	v_rcp_f32_e32 v95, v88
	v_mul_f32_e32 v88, v84, v168
	v_mul_f32_e32 v89, v80, v168
	v_mul_f32_e32 v90, v90, v91
	v_mul_f32_e32 v80, 0xbfb8aa3b, v88
	v_exp_f32_e32 v80, v80
	v_mul_f32_e32 v88, v88, v89
	v_mul_f32_e32 v84, v96, v94
	v_mul_f32_e32 v90, v90, v95
	v_add_f32_e32 v80, 1.0, v80
	v_rcp_f32_e32 v91, v80
	v_mul_f32_e32 v80, v85, v168
	v_mul_f32_e32 v81, v81, v168
	v_mul_f32_e32 v88, v88, v91
	v_mul_f32_e32 v85, 0xbfb8aa3b, v80
	v_exp_f32_e32 v85, v85
	v_mul_f32_e32 v89, v80, v81
	v_add_f32_e32 v80, 1.0, v85
	v_rcp_f32_e32 v85, v80
	v_mul_f32_e32 v80, v86, v168
	v_mul_f32_e32 v81, v82, v168
	v_mul_f32_e32 v85, v89, v85
	v_mul_f32_e32 v82, 0xbfb8aa3b, v80
	v_exp_f32_e32 v86, v82
	v_mul_f32_e32 v82, v87, v168
	v_mul_f32_e32 v83, v83, v168
	v_mul_f32_e32 v80, v80, v81
	v_mul_f32_e32 v87, 0xbfb8aa3b, v82
	v_exp_f32_e32 v87, v87
	v_add_f32_e32 v86, 1.0, v86
	v_rcp_f32_e32 v86, v86
	v_add_f32_e32 v87, 1.0, v87
	v_rcp_f32_e32 v87, v87
	v_mul_f32_e32 v86, v80, v86
	v_mul_f32_e32 v80, v82, v83
	v_mul_f32_e32 v83, v80, v87
	v_cvt_pk_bf16_f32 v80, v92, v93
	v_cvt_pk_bf16_f32 v81, v84, v90
	v_cvt_pk_bf16_f32 v82, v88, v85
	v_cvt_pk_bf16_f32 v83, v86, v83
	v_mul_f32_e32 v86, v76, v164
	v_mul_f32_e32 v87, v72, v164
	v_mad_i64_i32 v[84:85], s[34:35], v162, s52, v[112:113]
	v_mul_f32_e32 v72, 0xbfb8aa3b, v86
	v_exp_f32_e32 v76, v72
	v_mul_f32_e32 v72, v77, v164
	v_mul_f32_e32 v73, v73, v164
	v_lshl_add_u64 v[84:85], v[84:85], 0, v[114:115]
	v_mul_f32_e32 v77, 0xbfb8aa3b, v72
	v_exp_f32_e32 v77, v77
	v_mul_f32_e32 v72, v72, v73
	v_mov_b32_e32 v73, v74
	v_add_f32_e32 v76, 1.0, v76
	v_add_f32_e32 v77, 1.0, v77
	v_rcp_f32_e32 v77, v77
	v_rcp_f32_e32 v76, v76
	global_store_dwordx4 v[84:85], v[80:83], off
	v_mul_f32_e32 v77, v72, v77
	v_mul_f32_e32 v72, v78, v164
	v_mul_f32_e32 v73, v73, v164
	v_mul_f32_e32 v80, v86, v87
	v_mul_f32_e32 v74, 0xbfb8aa3b, v72
	v_exp_f32_e32 v78, v74
	v_mul_f32_e32 v74, v79, v164
	v_mul_f32_e32 v75, v75, v164
	v_mul_f32_e32 v76, v80, v76
	v_mul_f32_e32 v79, 0xbfb8aa3b, v74
	v_exp_f32_e32 v79, v79
	v_mul_f32_e32 v80, v72, v73
	v_add_f32_e32 v72, 1.0, v78
	v_rcp_f32_e32 v78, v72
	v_add_f32_e32 v72, 1.0, v79
	v_rcp_f32_e32 v79, v72
	v_mul_f32_e32 v72, v68, v164
	v_mul_f32_e32 v73, v64, v164
	v_mul_f32_e32 v74, v74, v75
	v_mul_f32_e32 v64, 0xbfb8aa3b, v72
	v_exp_f32_e32 v64, v64
	v_mul_f32_e32 v72, v72, v73
	v_mul_f32_e32 v68, v80, v78
	v_mul_f32_e32 v74, v74, v79
	v_add_f32_e32 v64, 1.0, v64
	v_rcp_f32_e32 v75, v64
	v_mul_f32_e32 v64, v69, v164
	v_mul_f32_e32 v65, v65, v164
	v_mul_f32_e32 v72, v72, v75
	v_mul_f32_e32 v69, 0xbfb8aa3b, v64
	v_exp_f32_e32 v69, v69
	v_mul_f32_e32 v73, v64, v65
	v_add_f32_e32 v64, 1.0, v69
	v_rcp_f32_e32 v69, v64
	v_mul_f32_e32 v64, v70, v164
	v_mul_f32_e32 v65, v66, v164
	v_mul_f32_e32 v69, v73, v69
	v_mul_f32_e32 v66, 0xbfb8aa3b, v64
	v_exp_f32_e32 v70, v66
	v_mul_f32_e32 v66, v71, v164
	v_mul_f32_e32 v67, v67, v164
	v_mul_f32_e32 v64, v64, v65
	v_mul_f32_e32 v71, 0xbfb8aa3b, v66
	v_exp_f32_e32 v71, v71
	v_add_f32_e32 v70, 1.0, v70
	v_rcp_f32_e32 v70, v70
	v_add_f32_e32 v71, 1.0, v71
	v_rcp_f32_e32 v71, v71
	v_mul_f32_e32 v70, v64, v70
	v_mul_f32_e32 v64, v66, v67
	v_mul_f32_e32 v67, v64, v71
	v_cvt_pk_bf16_f32 v64, v76, v77
	v_cvt_pk_bf16_f32 v65, v68, v74
	v_cvt_pk_bf16_f32 v66, v72, v69
	v_cvt_pk_bf16_f32 v67, v70, v67
	v_mul_f32_e32 v70, v60, v160
	v_mul_f32_e32 v71, v56, v160
	v_mad_i64_i32 v[68:69], s[34:35], v158, s52, v[112:113]
	v_mul_f32_e32 v56, 0xbfb8aa3b, v70
	v_exp_f32_e32 v60, v56
	v_mul_f32_e32 v56, v61, v160
	v_mul_f32_e32 v57, v57, v160
	v_lshl_add_u64 v[68:69], v[68:69], 0, v[114:115]
	v_mul_f32_e32 v61, 0xbfb8aa3b, v56
	v_exp_f32_e32 v61, v61
	v_mul_f32_e32 v56, v56, v57
	v_mov_b32_e32 v57, v58
	v_add_f32_e32 v60, 1.0, v60
	v_add_f32_e32 v61, 1.0, v61
	v_rcp_f32_e32 v61, v61
	v_rcp_f32_e32 v60, v60
	global_store_dwordx4 v[68:69], v[64:67], off
	v_mul_f32_e32 v61, v56, v61
	v_mul_f32_e32 v56, v62, v160
	v_mul_f32_e32 v57, v57, v160
	v_mul_f32_e32 v64, v70, v71
	v_mul_f32_e32 v58, 0xbfb8aa3b, v56
	v_exp_f32_e32 v62, v58
	v_mul_f32_e32 v58, v63, v160
	v_mul_f32_e32 v59, v59, v160
	v_mul_f32_e32 v60, v64, v60
	v_mul_f32_e32 v63, 0xbfb8aa3b, v58
	v_exp_f32_e32 v63, v63
	v_mul_f32_e32 v64, v56, v57
	v_add_f32_e32 v56, 1.0, v62
	v_rcp_f32_e32 v62, v56
	v_add_f32_e32 v56, 1.0, v63
	v_rcp_f32_e32 v63, v56
	v_mul_f32_e32 v56, v52, v160
	v_mul_f32_e32 v57, v48, v160
	v_mul_f32_e32 v58, v58, v59
	v_mul_f32_e32 v48, 0xbfb8aa3b, v56
	v_exp_f32_e32 v48, v48
	v_mul_f32_e32 v56, v56, v57
	v_mul_f32_e32 v52, v64, v62
	v_mul_f32_e32 v58, v58, v63
	v_add_f32_e32 v48, 1.0, v48
	v_rcp_f32_e32 v59, v48
	v_mul_f32_e32 v48, v53, v160
	v_mul_f32_e32 v49, v49, v160
	v_mul_f32_e32 v56, v56, v59
	v_mul_f32_e32 v53, 0xbfb8aa3b, v48
	v_exp_f32_e32 v53, v53
	v_mul_f32_e32 v57, v48, v49
	v_add_f32_e32 v48, 1.0, v53
	v_rcp_f32_e32 v53, v48
	v_mul_f32_e32 v48, v54, v160
	v_mul_f32_e32 v49, v50, v160
	v_mul_f32_e32 v53, v57, v53
	v_mul_f32_e32 v50, 0xbfb8aa3b, v48
	v_exp_f32_e32 v54, v50
	v_mul_f32_e32 v50, v55, v160
	v_mul_f32_e32 v51, v51, v160
	v_mul_f32_e32 v48, v48, v49
	v_mul_f32_e32 v55, 0xbfb8aa3b, v50
	v_exp_f32_e32 v55, v55
	v_add_f32_e32 v54, 1.0, v54
	v_rcp_f32_e32 v54, v54
	v_add_f32_e32 v55, 1.0, v55
	v_rcp_f32_e32 v55, v55
	v_mul_f32_e32 v54, v48, v54
	v_mul_f32_e32 v48, v50, v51
	v_mul_f32_e32 v51, v48, v55
	v_cvt_pk_bf16_f32 v48, v60, v61
	v_cvt_pk_bf16_f32 v49, v52, v58
; __device__ __forceinline__ unsigned cvt_pk_bf16(float lo, float hi) { unsigned r; asm volatile("v_cvt_pk_bf16_f32 %0, %1, %2" : "=v"(r) : "v"(lo), "v"(hi)); return r; }
; __device__ __forceinline__ float fast_sigmoid(float x) { return __builtin_amdgcn_rcpf(1.0f + __expf(-x)); }
; #define PG8_BAR __builtin_amdgcn_s_barrier()
;     __device__ __forceinline__ void operator()(const f32x4 (&acc)[2][2][4][2], const Unit& u, int wr, int wc, int fr, int fq) const {
;     ...
;         for (int ai = 0; ai < 2; ++ai)
; #pragma unroll
;             for (int m = 0; m < 4; ++m) {
;                 const int row = u.pm * BM + ai * HALF + wr * 64 + m * 16 + fr;
;                 const float rs = rsv[ai][m];
;                 float h[8];
; #pragma unroll
;                 for (int n = 0; n < 2; ++n)
; #pragma unroll
;                     for (int i = 0; i < 4; ++i) { const float g = acc[ai][0][m][n][i] * rs, up = acc[ai][1][m][n][i] * rs; h[4 * n + i] = g * up * fast_sigmoid(g); }
;                 u32x4 w; w.x = cvt_pk_bf16(h[0], h[1]); w.y = cvt_pk_bf16(h[2], h[3]); w.z = cvt_pk_bf16(h[4], h[5]); w.w = cvt_pk_bf16(h[6], h[7]);
;                 *(u32x4*)(H + (size_t)row * 2816 + col0) = w;
; template <class Epi, class Sched, bool ALIGN_EPI = false, bool SP2 = false>
; __device__ __forceinline__ void gemm_phase(PG8_LAS unsigned char* lds, const Gemm g, const Sched& S, const Epi& E) {
;     ...
;         if (!has_next) break;
; #pragma unroll
;         for (int a = 0; a < 2; ++a)
; #pragma unroll
;             for (int b = 0; b < 2; ++b)
; #pragma unroll
;                 for (int m = 0; m < 4; ++m)
; #pragma unroll
;                     for (int n = 0; n < 2; ++n) acc[a][b][m][n] = (f32x4){0.f, 0.f, 0.f, 0.f};
;         cur = nxt; cA = nA; cB = nB; ++ui;
;         if constexpr (ALIGN_EPI) { if (wr == 1) PG8_BAR; }
	v_cvt_pk_bf16_f32 v50, v56, v53
	v_cvt_pk_bf16_f32 v51, v54, v51
	v_mul_f32_e32 v54, v44, v156
	v_mul_f32_e32 v55, v40, v156
	v_mad_i64_i32 v[52:53], s[34:35], v154, s52, v[112:113]
	v_mul_f32_e32 v40, 0xbfb8aa3b, v54
	v_exp_f32_e32 v44, v40
	v_mul_f32_e32 v40, v45, v156
	v_mul_f32_e32 v41, v41, v156
	v_lshl_add_u64 v[52:53], v[52:53], 0, v[114:115]
	v_mul_f32_e32 v45, 0xbfb8aa3b, v40
	v_exp_f32_e32 v45, v45
	v_mul_f32_e32 v40, v40, v41
	v_mov_b32_e32 v41, v42
	v_add_f32_e32 v44, 1.0, v44
	v_add_f32_e32 v45, 1.0, v45
	v_rcp_f32_e32 v45, v45
	v_rcp_f32_e32 v44, v44
	global_store_dwordx4 v[52:53], v[48:51], off
	v_mul_f32_e32 v45, v40, v45
	v_mul_f32_e32 v40, v46, v156
	v_mul_f32_e32 v41, v41, v156
	v_mul_f32_e32 v48, v54, v55
	v_mul_f32_e32 v42, 0xbfb8aa3b, v40
	v_exp_f32_e32 v46, v42
	v_mul_f32_e32 v42, v47, v156
	v_mul_f32_e32 v43, v43, v156
	v_mul_f32_e32 v44, v48, v44
	v_mul_f32_e32 v47, 0xbfb8aa3b, v42
	v_exp_f32_e32 v47, v47
	v_mul_f32_e32 v48, v40, v41
	v_add_f32_e32 v40, 1.0, v46
	v_rcp_f32_e32 v46, v40
	v_add_f32_e32 v40, 1.0, v47
	v_rcp_f32_e32 v47, v40
	v_mul_f32_e32 v40, v36, v156
	v_mul_f32_e32 v41, v32, v156
	v_mul_f32_e32 v42, v42, v43
	v_mul_f32_e32 v32, 0xbfb8aa3b, v40
	v_exp_f32_e32 v32, v32
	v_mul_f32_e32 v40, v40, v41
	v_mul_f32_e32 v36, v48, v46
	v_mul_f32_e32 v42, v42, v47
	v_add_f32_e32 v32, 1.0, v32
	v_rcp_f32_e32 v43, v32
	v_mul_f32_e32 v32, v37, v156
	v_mul_f32_e32 v33, v33, v156
	v_mul_f32_e32 v40, v40, v43
	v_mul_f32_e32 v37, 0xbfb8aa3b, v32
	v_exp_f32_e32 v37, v37
	v_mul_f32_e32 v41, v32, v33
	v_add_f32_e32 v32, 1.0, v37
	v_rcp_f32_e32 v37, v32
	v_mul_f32_e32 v32, v38, v156
	v_mul_f32_e32 v33, v34, v156
	v_mul_f32_e32 v37, v41, v37
	v_mul_f32_e32 v34, 0xbfb8aa3b, v32
	v_exp_f32_e32 v38, v34
	v_mul_f32_e32 v34, v39, v156
	v_mul_f32_e32 v35, v35, v156
	v_mul_f32_e32 v32, v32, v33
	v_mul_f32_e32 v39, 0xbfb8aa3b, v34
	v_exp_f32_e32 v39, v39
	v_add_f32_e32 v38, 1.0, v38
	v_rcp_f32_e32 v38, v38
	v_add_f32_e32 v39, 1.0, v39
	v_rcp_f32_e32 v39, v39
	v_mul_f32_e32 v38, v32, v38
	v_mul_f32_e32 v32, v34, v35
	v_mul_f32_e32 v35, v32, v39
	v_cvt_pk_bf16_f32 v32, v44, v45
	v_cvt_pk_bf16_f32 v33, v36, v42
	v_cvt_pk_bf16_f32 v34, v40, v37
	v_cvt_pk_bf16_f32 v35, v38, v35
	v_mul_f32_e32 v38, v28, v152
	v_mul_f32_e32 v39, v24, v152
	v_mad_i64_i32 v[36:37], s[34:35], v150, s52, v[112:113]
	v_mul_f32_e32 v24, 0xbfb8aa3b, v38
	v_exp_f32_e32 v28, v24
	v_mul_f32_e32 v24, v29, v152
	v_mul_f32_e32 v25, v25, v152
	v_lshl_add_u64 v[36:37], v[36:37], 0, v[114:115]
	v_mul_f32_e32 v29, 0xbfb8aa3b, v24
	v_exp_f32_e32 v29, v29
	v_mul_f32_e32 v24, v24, v25
	v_mov_b32_e32 v25, v26
	v_add_f32_e32 v28, 1.0, v28
	v_add_f32_e32 v29, 1.0, v29
	v_rcp_f32_e32 v29, v29
	v_rcp_f32_e32 v28, v28
	global_store_dwordx4 v[36:37], v[32:35], off
	v_mul_f32_e32 v29, v24, v29
	v_mul_f32_e32 v24, v30, v152
	v_mul_f32_e32 v25, v25, v152
	v_mul_f32_e32 v32, v38, v39
	v_mul_f32_e32 v26, 0xbfb8aa3b, v24
	v_exp_f32_e32 v30, v26
	v_mul_f32_e32 v26, v31, v152
	v_mul_f32_e32 v27, v27, v152
	v_mul_f32_e32 v28, v32, v28
	v_mul_f32_e32 v31, 0xbfb8aa3b, v26
	v_exp_f32_e32 v31, v31
	v_mul_f32_e32 v32, v24, v25
	v_add_f32_e32 v24, 1.0, v30
	v_rcp_f32_e32 v30, v24
	v_add_f32_e32 v24, 1.0, v31
	v_rcp_f32_e32 v31, v24
	v_mul_f32_e32 v24, v20, v152
	v_mul_f32_e32 v25, v16, v152
	v_mul_f32_e32 v26, v26, v27
	v_mul_f32_e32 v16, 0xbfb8aa3b, v24
	v_exp_f32_e32 v16, v16
	v_mul_f32_e32 v24, v24, v25
	v_mul_f32_e32 v20, v32, v30
	v_mul_f32_e32 v26, v26, v31
	v_add_f32_e32 v16, 1.0, v16
	v_rcp_f32_e32 v27, v16
	v_mul_f32_e32 v16, v21, v152
	v_mul_f32_e32 v17, v17, v152
	v_mul_f32_e32 v24, v24, v27
	v_mul_f32_e32 v21, 0xbfb8aa3b, v16
	v_exp_f32_e32 v21, v21
	v_mul_f32_e32 v25, v16, v17
	v_add_f32_e32 v16, 1.0, v21
	v_rcp_f32_e32 v21, v16
	v_mul_f32_e32 v16, v22, v152
	v_mul_f32_e32 v17, v18, v152
	v_mul_f32_e32 v21, v25, v21
	v_mul_f32_e32 v18, 0xbfb8aa3b, v16
	v_exp_f32_e32 v22, v18
	v_mul_f32_e32 v18, v23, v152
	v_mul_f32_e32 v19, v19, v152
	v_mul_f32_e32 v16, v16, v17
	v_mul_f32_e32 v23, 0xbfb8aa3b, v18
	v_exp_f32_e32 v23, v23
	v_add_f32_e32 v22, 1.0, v22
	v_rcp_f32_e32 v22, v22
	v_add_f32_e32 v23, 1.0, v23
	v_rcp_f32_e32 v23, v23
	v_mul_f32_e32 v22, v16, v22
	v_mul_f32_e32 v16, v18, v19
	v_mul_f32_e32 v19, v16, v23
	v_cvt_pk_bf16_f32 v16, v28, v29
	v_cvt_pk_bf16_f32 v17, v20, v26
	v_cvt_pk_bf16_f32 v18, v24, v21
	v_cvt_pk_bf16_f32 v19, v22, v19
	v_mul_f32_e32 v22, v12, v148
	v_mul_f32_e32 v23, v8, v148
	v_mad_i64_i32 v[20:21], s[34:35], v146, s52, v[112:113]
	v_mul_f32_e32 v8, 0xbfb8aa3b, v22
	v_exp_f32_e32 v12, v8
	v_mul_f32_e32 v8, v13, v148
	v_mul_f32_e32 v9, v9, v148
	v_lshl_add_u64 v[20:21], v[20:21], 0, v[114:115]
	v_mul_f32_e32 v13, 0xbfb8aa3b, v8
	v_exp_f32_e32 v13, v13
	v_mul_f32_e32 v8, v8, v9
	v_mov_b32_e32 v9, v10
	v_add_f32_e32 v12, 1.0, v12
	v_add_f32_e32 v13, 1.0, v13
	v_rcp_f32_e32 v13, v13
	v_rcp_f32_e32 v12, v12
	global_store_dwordx4 v[20:21], v[16:19], off
	v_mul_f32_e32 v13, v8, v13
	v_mul_f32_e32 v8, v14, v148
	v_mul_f32_e32 v9, v9, v148
	v_mul_f32_e32 v16, v22, v23
	v_mul_f32_e32 v10, 0xbfb8aa3b, v8
	v_exp_f32_e32 v14, v10
	v_mul_f32_e32 v10, v15, v148
	v_mul_f32_e32 v11, v11, v148
	v_mul_f32_e32 v12, v16, v12
	v_mul_f32_e32 v15, 0xbfb8aa3b, v10
	v_exp_f32_e32 v15, v15
	v_mul_f32_e32 v16, v8, v9
	v_add_f32_e32 v8, 1.0, v14
	v_rcp_f32_e32 v14, v8
	v_add_f32_e32 v8, 1.0, v15
	v_rcp_f32_e32 v15, v8
	v_mul_f32_e32 v8, v4, v148
	v_mul_f32_e32 v9, v0, v148
	v_mul_f32_e32 v10, v10, v11
	v_mul_f32_e32 v0, 0xbfb8aa3b, v8
	v_exp_f32_e32 v0, v0
	v_mul_f32_e32 v8, v8, v9
	v_mul_f32_e32 v4, v16, v14
	v_mul_f32_e32 v10, v10, v15
	v_add_f32_e32 v0, 1.0, v0
	v_rcp_f32_e32 v11, v0
	v_mul_f32_e32 v0, v5, v148
	v_mul_f32_e32 v1, v1, v148
	v_mul_f32_e32 v8, v8, v11
	v_mul_f32_e32 v5, 0xbfb8aa3b, v0
	v_exp_f32_e32 v5, v5
	v_mul_f32_e32 v9, v0, v1
	v_add_f32_e32 v0, 1.0, v5
	v_rcp_f32_e32 v5, v0
	v_mul_f32_e32 v0, v6, v148
	v_mul_f32_e32 v1, v2, v148
	v_mul_f32_e32 v5, v9, v5
	v_mul_f32_e32 v2, 0xbfb8aa3b, v0
	v_exp_f32_e32 v6, v2
	v_mul_f32_e32 v2, v7, v148
	v_mul_f32_e32 v3, v3, v148
	v_mul_f32_e32 v0, v0, v1
	v_mul_f32_e32 v7, 0xbfb8aa3b, v2
	v_exp_f32_e32 v7, v7
	v_add_f32_e32 v6, 1.0, v6
	v_rcp_f32_e32 v6, v6
	v_add_f32_e32 v7, 1.0, v7
	v_rcp_f32_e32 v7, v7
	v_mul_f32_e32 v6, v0, v6
	v_mul_f32_e32 v0, v2, v3
	v_mul_f32_e32 v3, v0, v7
	v_cvt_pk_bf16_f32 v0, v12, v13
	v_cvt_pk_bf16_f32 v1, v4, v10
	v_cvt_pk_bf16_f32 v2, v8, v5
	v_mad_i64_i32 v[4:5], s[34:35], v144, s52, v[112:113]
	v_lshl_add_u64 v[4:5], v[4:5], 0, v[114:115]
	v_cvt_pk_bf16_f32 v3, v6, v3
	global_store_dwordx4 v[4:5], v[0:3], off
	s_cbranch_vccnz .LBB0_972
	s_andn2_b64 vcc, exec, s[8:9]
	s_cbranch_vccnz .LBB0_971
	s_barrier
	s_branch .LBB0_971
